# batched serialized loads: scan_sum, conv SS sum, scan_fix prefix, epilogue sample rstd, samp_fin rstd, final norm, S-stream preamble
# speedup vs baseline: 1.0302x; 1.0302x over previous
; __device__ __forceinline__ void rows_rstd(const float* SS, const Unit& u, int wr, int fr, int fq, float (&rs)[2][4]) {
;     if (u.pm < 32) { const float* RSTD = (const float*)((const char*)SS + SS_TO_RSTD);
; #pragma unroll
;         for (int ai = 0; ai < 2; ++ai)
; #pragma unroll
;             for (int m = 0; m < 4; ++m) rs[ai][m] = RSTD[u.pm * BM + ai * HALF + wr * 64 + m * 16 + fr];
;     } else {
; #pragma unroll
;         for (int ai = 0; ai < 2; ++ai)
; #pragma unroll
;             for (int m = 0; m < 4; ++m) {
;                 const int row = u.pm * BM + ai * HALF + wr * 64 + m * 16 + fr; float s = 0.f;
; #pragma unroll
;                 for (int j = 0; j < 8; ++j) s += SS[(size_t)(fq * 8 + j) * MPAD + row];
;                 s += __shfl_xor(s, 16); s += __shfl_xor(s, 32);
;                 rs[ai][m] = 1.0f / sqrtf(s * (1.0f / 2048.0f) + RMS_EPS);
;             }
;     }
; }
.LBB0_234:
	s_lshl_b32 s6, s76, 8
	v_mov_b32_e32 v140, v159
	v_mov_b32_e32 v141, v161
	s_add_i32 s6, s6, s70
	s_cmp_lt_i32 s76, 32
	v_add_u32_e32 v156, s6, v141
	v_lshlrev_b32_e32 v154, 3, v140
	v_add_u32_e32 v152, 16, v156
	v_add_u32_e32 v150, 32, v156
	v_add_u32_e32 v148, 48, v156
	v_add_u32_e32 v146, 0x80, v156
	v_add_u32_e32 v144, 0x90, v156
	v_add_u32_e32 v142, 0xa0, v156
	s_mov_b64 s[6:7], -1
	v_ashrrev_i32_e32 v157, 31, v156
	v_ashrrev_i32_e32 v155, 31, v154
	v_ashrrev_i32_e32 v153, 31, v152
	v_ashrrev_i32_e32 v151, 31, v150
	v_ashrrev_i32_e32 v149, 31, v148
	v_ashrrev_i32_e32 v147, 31, v146
	v_ashrrev_i32_e32 v145, 31, v144
	v_ashrrev_i32_e32 v143, 31, v142
	v_add_u32_e32 v140, 0xb0, v156
	s_cbranch_scc1 .LBB0_236
	v_and_b32_e32 v158, 64, v219
	v_xor_b32_e32 v141, 16, v219
	v_add_u32_e32 v158, 64, v158
	v_cmp_lt_i32_e32 vcc, v141, v158
	v_lshl_add_u64 v[194:195], v[156:157], 2, s[14:15]
	v_mad_i64_i32 v[170:171], s[6:7], v154, s46, v[194:195]
	v_cndmask_b32_e32 v141, v219, v141, vcc
	v_lshlrev_b32_e32 v169, 2, v141
	v_xor_b32_e32 v141, 32, v219
	v_cmp_lt_i32_e32 vcc, v141, v158
	s_nop 1
	v_cndmask_b32_e32 v141, v219, v141, vcc
	v_lshlrev_b32_e32 v167, 2, v141
	global_load_dword v208, v[170:171], off
	v_or_b32_e32 v171, 1, v154
	v_mad_i64_i32 v[172:173], s[6:7], v171, s46, v[194:195]
	global_load_dword v209, v[172:173], off
	v_or_b32_e32 v172, 2, v154
	v_mad_i64_i32 v[174:175], s[6:7], v172, s46, v[194:195]
	v_or_b32_e32 v173, 3, v154
	global_load_dword v210, v[174:175], off
	v_mad_i64_i32 v[174:175], s[6:7], v173, s46, v[194:195]
	global_load_dword v211, v[174:175], off
	v_or_b32_e32 v174, 4, v154
	v_mad_i64_i32 v[176:177], s[6:7], v174, s46, v[194:195]
	v_or_b32_e32 v175, 5, v154
	global_load_dword v212, v[176:177], off
	v_mad_i64_i32 v[176:177], s[6:7], v175, s46, v[194:195]
	global_load_dword v213, v[176:177], off
	v_or_b32_e32 v176, 6, v154
	v_mad_i64_i32 v[196:197], s[6:7], v176, s46, v[194:195]
	v_or_b32_e32 v177, 7, v154
	v_mad_i64_i32 v[194:195], s[6:7], v177, s46, v[194:195]
	global_load_dword v214, v[196:197], off
	global_load_dword v215, v[194:195], off
	v_lshl_add_u64 v[194:195], v[152:153], 2, s[14:15]
	s_waitcnt vmcnt(0)
	v_add_f32_e32 v141, 0, v208
	v_add_f32_e32 v141, v141, v209
	v_add_f32_e32 v141, v141, v210
	v_add_f32_e32 v141, v141, v211
	v_add_f32_e32 v141, v141, v212
	v_add_f32_e32 v141, v141, v213
	v_add_f32_e32 v141, v141, v214
	v_add_f32_e32 v141, v141, v215
	ds_bpermute_b32 v158, v169, v141
	s_waitcnt lgkmcnt(0)
	v_add_f32_e32 v141, v141, v158
	ds_bpermute_b32 v158, v167, v141
	s_waitcnt lgkmcnt(0)
	v_add_f32_e32 v141, v141, v158
	v_fmamk_f32 v141, v141, 0x3a000000, v220
	v_cmp_gt_f32_e32 vcc, s43, v141
	v_mul_f32_e32 v158, 0x4f800000, v141
	s_nop 0
	v_cndmask_b32_e32 v141, v141, v158, vcc
	v_sqrt_f32_e32 v158, v141
	s_nop 0
	v_add_u32_e32 v160, -1, v158
	v_fma_f32 v162, -v160, v158, v141
	v_cmp_ge_f32_e64 s[6:7], 0, v162
	v_add_u32_e32 v162, 1, v158
	s_nop 0
	v_cndmask_b32_e64 v160, v158, v160, s[6:7]
	v_fma_f32 v158, -v162, v158, v141
	v_cmp_lt_f32_e64 s[6:7], 0, v158
	s_nop 1
	v_cndmask_b32_e64 v158, v160, v162, s[6:7]
	v_mul_f32_e32 v160, 0x37800000, v158
	v_cndmask_b32_e32 v158, v158, v160, vcc
	v_cmp_class_f32_e32 vcc, v141, v221
	v_mad_i64_i32 v[196:197], s[6:7], v154, s46, v[194:195]
	s_nop 0
	v_cndmask_b32_e32 v141, v158, v141, vcc
	v_div_scale_f32 v158, s[6:7], v141, v141, 1.0
	v_rcp_f32_e32 v160, v158
	s_nop 0
	v_fma_f32 v162, -v158, v160, 1.0
	v_fmac_f32_e32 v160, v162, v160
	v_div_scale_f32 v162, vcc, 1.0, v141, 1.0
	v_mul_f32_e32 v164, v162, v160
	v_fma_f32 v166, -v158, v164, v162
	v_fmac_f32_e32 v164, v166, v160
	v_fma_f32 v158, -v158, v164, v162
	v_div_fmas_f32 v158, v158, v160, v164
	v_div_fixup_f32 v158, v158, v141, 1.0
	global_load_dword v208, v[196:197], off
	v_mad_i64_i32 v[196:197], s[6:7], v171, s46, v[194:195]
	global_load_dword v209, v[196:197], off
	v_mad_i64_i32 v[196:197], s[6:7], v172, s46, v[194:195]
	global_load_dword v210, v[196:197], off
	v_mad_i64_i32 v[196:197], s[6:7], v173, s46, v[194:195]
	global_load_dword v211, v[196:197], off
	v_mad_i64_i32 v[196:197], s[6:7], v174, s46, v[194:195]
	global_load_dword v212, v[196:197], off
	v_mad_i64_i32 v[196:197], s[6:7], v175, s46, v[194:195]
	global_load_dword v213, v[196:197], off
	v_mad_i64_i32 v[196:197], s[6:7], v176, s46, v[194:195]
	v_mad_i64_i32 v[194:195], s[6:7], v177, s46, v[194:195]
	global_load_dword v214, v[196:197], off
	global_load_dword v215, v[194:195], off
	v_lshl_add_u64 v[194:195], v[150:151], 2, s[14:15]
	s_waitcnt vmcnt(0)
	v_add_f32_e32 v141, 0, v208
	v_add_f32_e32 v141, v141, v209
	v_add_f32_e32 v141, v141, v210
	v_add_f32_e32 v141, v141, v211
	v_add_f32_e32 v141, v141, v212
	v_add_f32_e32 v141, v141, v213
	v_add_f32_e32 v141, v141, v214
	v_add_f32_e32 v141, v141, v215
	ds_bpermute_b32 v160, v169, v141
	s_waitcnt lgkmcnt(0)
	v_add_f32_e32 v141, v141, v160
	ds_bpermute_b32 v160, v167, v141
	s_waitcnt lgkmcnt(0)
; __device__ __forceinline__ void rows_rstd(const float* SS, const Unit& u, int wr, int fr, int fq, float (&rs)[2][4]) {
;     ...
;             for (int m = 0; m < 4; ++m) rs[ai][m] = RSTD[u.pm * BM + ai * HALF + wr * 64 + m * 16 + fr];
;     } else {
; #pragma unroll
;         for (int ai = 0; ai < 2; ++ai)
; #pragma unroll
;             for (int m = 0; m < 4; ++m) {
;                 const int row = u.pm * BM + ai * HALF + wr * 64 + m * 16 + fr; float s = 0.f;
; #pragma unroll
;                 for (int j = 0; j < 8; ++j) s += SS[(size_t)(fq * 8 + j) * MPAD + row];
;                 s += __shfl_xor(s, 16); s += __shfl_xor(s, 32);
;                 rs[ai][m] = 1.0f / sqrtf(s * (1.0f / 2048.0f) + RMS_EPS);
	v_add_f32_e32 v141, v141, v160
	v_fmamk_f32 v141, v141, 0x3a000000, v220
	v_cmp_gt_f32_e32 vcc, s43, v141
	v_mul_f32_e32 v160, 0x4f800000, v141
	s_nop 0
	v_cndmask_b32_e32 v141, v141, v160, vcc
	v_sqrt_f32_e32 v160, v141
	s_nop 0
	v_add_u32_e32 v162, -1, v160
	v_fma_f32 v164, -v162, v160, v141
	v_cmp_ge_f32_e64 s[6:7], 0, v164
	v_add_u32_e32 v164, 1, v160
	s_nop 0
	v_cndmask_b32_e64 v162, v160, v162, s[6:7]
	v_fma_f32 v160, -v164, v160, v141
	v_cmp_lt_f32_e64 s[6:7], 0, v160
	s_nop 1
	v_cndmask_b32_e64 v160, v162, v164, s[6:7]
	v_mul_f32_e32 v162, 0x37800000, v160
	v_cndmask_b32_e32 v160, v160, v162, vcc
	v_cmp_class_f32_e32 vcc, v141, v221
	v_mad_i64_i32 v[196:197], s[6:7], v154, s46, v[194:195]
	s_nop 0
	v_cndmask_b32_e32 v141, v160, v141, vcc
	v_div_scale_f32 v160, s[6:7], v141, v141, 1.0
	v_rcp_f32_e32 v162, v160
	s_nop 0
	v_fma_f32 v164, -v160, v162, 1.0
	v_fmac_f32_e32 v162, v164, v162
	v_div_scale_f32 v164, vcc, 1.0, v141, 1.0
	v_mul_f32_e32 v166, v164, v162
	v_fma_f32 v168, -v160, v166, v164
	v_fmac_f32_e32 v166, v168, v162
	v_fma_f32 v160, -v160, v166, v164
	v_div_fmas_f32 v160, v160, v162, v166
	v_div_fixup_f32 v160, v160, v141, 1.0
	global_load_dword v208, v[196:197], off
	v_mad_i64_i32 v[196:197], s[6:7], v171, s46, v[194:195]
	global_load_dword v209, v[196:197], off
	v_mad_i64_i32 v[196:197], s[6:7], v172, s46, v[194:195]
	global_load_dword v210, v[196:197], off
	v_mad_i64_i32 v[196:197], s[6:7], v173, s46, v[194:195]
	global_load_dword v211, v[196:197], off
	v_mad_i64_i32 v[196:197], s[6:7], v174, s46, v[194:195]
	global_load_dword v212, v[196:197], off
	v_mad_i64_i32 v[196:197], s[6:7], v175, s46, v[194:195]
	global_load_dword v213, v[196:197], off
	v_mad_i64_i32 v[196:197], s[6:7], v176, s46, v[194:195]
	v_mad_i64_i32 v[194:195], s[6:7], v177, s46, v[194:195]
	global_load_dword v214, v[196:197], off
	global_load_dword v215, v[194:195], off
	v_lshl_add_u64 v[194:195], v[148:149], 2, s[14:15]
	s_waitcnt vmcnt(0)
	v_add_f32_e32 v141, 0, v208
	v_add_f32_e32 v141, v141, v209
	v_add_f32_e32 v141, v141, v210
	v_add_f32_e32 v141, v141, v211
	v_add_f32_e32 v141, v141, v212
	v_add_f32_e32 v141, v141, v213
	v_add_f32_e32 v141, v141, v214
	v_add_f32_e32 v141, v141, v215
	ds_bpermute_b32 v162, v169, v141
	s_waitcnt lgkmcnt(0)
	v_add_f32_e32 v141, v141, v162
	ds_bpermute_b32 v162, v167, v141
	s_waitcnt lgkmcnt(0)
	v_add_f32_e32 v141, v141, v162
	v_fmamk_f32 v141, v141, 0x3a000000, v220
	v_cmp_gt_f32_e32 vcc, s43, v141
	v_mul_f32_e32 v162, 0x4f800000, v141
	s_nop 0
	v_cndmask_b32_e32 v141, v141, v162, vcc
	v_sqrt_f32_e32 v162, v141
	s_nop 0
	v_add_u32_e32 v164, -1, v162
	v_fma_f32 v166, -v164, v162, v141
	v_cmp_ge_f32_e64 s[6:7], 0, v166
	v_add_u32_e32 v166, 1, v162
	s_nop 0
	v_cndmask_b32_e64 v164, v162, v164, s[6:7]
	v_fma_f32 v162, -v166, v162, v141
	v_cmp_lt_f32_e64 s[6:7], 0, v162
	s_nop 1
	v_cndmask_b32_e64 v162, v164, v166, s[6:7]
	v_mul_f32_e32 v164, 0x37800000, v162
	v_cndmask_b32_e32 v162, v162, v164, vcc
	v_cmp_class_f32_e32 vcc, v141, v221
	v_mad_i64_i32 v[196:197], s[6:7], v154, s46, v[194:195]
	s_nop 0
	v_cndmask_b32_e32 v141, v162, v141, vcc
	v_div_scale_f32 v162, s[6:7], v141, v141, 1.0
	v_rcp_f32_e32 v164, v162
	s_nop 0
	v_fma_f32 v166, -v162, v164, 1.0
	v_fmac_f32_e32 v164, v166, v164
	v_div_scale_f32 v166, vcc, 1.0, v141, 1.0
	v_mul_f32_e32 v168, v166, v164
	v_fma_f32 v170, -v162, v168, v166
	v_fmac_f32_e32 v168, v170, v164
	v_fma_f32 v162, -v162, v168, v166
	v_div_fmas_f32 v162, v162, v164, v168
	v_div_fixup_f32 v162, v162, v141, 1.0
	global_load_dword v208, v[196:197], off
	v_mad_i64_i32 v[196:197], s[6:7], v171, s46, v[194:195]
	global_load_dword v209, v[196:197], off
	v_mad_i64_i32 v[196:197], s[6:7], v172, s46, v[194:195]
	global_load_dword v210, v[196:197], off
	v_mad_i64_i32 v[196:197], s[6:7], v173, s46, v[194:195]
	global_load_dword v211, v[196:197], off
	v_mad_i64_i32 v[196:197], s[6:7], v174, s46, v[194:195]
	global_load_dword v212, v[196:197], off
	v_mad_i64_i32 v[196:197], s[6:7], v175, s46, v[194:195]
	global_load_dword v213, v[196:197], off
	v_mad_i64_i32 v[196:197], s[6:7], v176, s46, v[194:195]
	v_mad_i64_i32 v[194:195], s[6:7], v177, s46, v[194:195]
	global_load_dword v214, v[196:197], off
	global_load_dword v215, v[194:195], off
	v_lshl_add_u64 v[194:195], v[146:147], 2, s[14:15]
	s_waitcnt vmcnt(0)
	v_add_f32_e32 v141, 0, v208
	v_add_f32_e32 v141, v141, v209
	v_add_f32_e32 v141, v141, v210
	v_add_f32_e32 v141, v141, v211
	v_add_f32_e32 v141, v141, v212
	v_add_f32_e32 v141, v141, v213
	v_add_f32_e32 v141, v141, v214
	v_add_f32_e32 v141, v141, v215
	ds_bpermute_b32 v164, v169, v141
	s_waitcnt lgkmcnt(0)
	v_add_f32_e32 v141, v141, v164
	ds_bpermute_b32 v164, v167, v141
	s_waitcnt lgkmcnt(0)
; __device__ __forceinline__ void rows_rstd(const float* SS, const Unit& u, int wr, int fr, int fq, float (&rs)[2][4]) {
;     ...
;             for (int m = 0; m < 4; ++m) rs[ai][m] = RSTD[u.pm * BM + ai * HALF + wr * 64 + m * 16 + fr];
;     } else {
; #pragma unroll
;         for (int ai = 0; ai < 2; ++ai)
; #pragma unroll
;             for (int m = 0; m < 4; ++m) {
;                 const int row = u.pm * BM + ai * HALF + wr * 64 + m * 16 + fr; float s = 0.f;
; #pragma unroll
;                 for (int j = 0; j < 8; ++j) s += SS[(size_t)(fq * 8 + j) * MPAD + row];
;                 s += __shfl_xor(s, 16); s += __shfl_xor(s, 32);
;                 rs[ai][m] = 1.0f / sqrtf(s * (1.0f / 2048.0f) + RMS_EPS);
	v_add_f32_e32 v141, v141, v164
	v_fmamk_f32 v141, v141, 0x3a000000, v220
	v_cmp_gt_f32_e32 vcc, s43, v141
	v_mul_f32_e32 v164, 0x4f800000, v141
	s_nop 0
	v_cndmask_b32_e32 v141, v141, v164, vcc
	v_sqrt_f32_e32 v164, v141
	s_nop 0
	v_add_u32_e32 v166, -1, v164
	v_fma_f32 v168, -v166, v164, v141
	v_cmp_ge_f32_e64 s[6:7], 0, v168
	v_add_u32_e32 v168, 1, v164
	s_nop 0
	v_cndmask_b32_e64 v166, v164, v166, s[6:7]
	v_fma_f32 v164, -v168, v164, v141
	v_cmp_lt_f32_e64 s[6:7], 0, v164
	s_nop 1
	v_cndmask_b32_e64 v164, v166, v168, s[6:7]
	v_mul_f32_e32 v166, 0x37800000, v164
	v_cndmask_b32_e32 v164, v164, v166, vcc
	v_cmp_class_f32_e32 vcc, v141, v221
	v_mad_i64_i32 v[196:197], s[6:7], v154, s46, v[194:195]
	s_nop 0
	v_cndmask_b32_e32 v141, v164, v141, vcc
	v_div_scale_f32 v164, s[6:7], v141, v141, 1.0
	v_rcp_f32_e32 v166, v164
	s_nop 0
	v_fma_f32 v168, -v164, v166, 1.0
	v_fmac_f32_e32 v166, v168, v166
	v_div_scale_f32 v168, vcc, 1.0, v141, 1.0
	v_mul_f32_e32 v170, v168, v166
	v_fma_f32 v189, -v164, v170, v168
	v_fmac_f32_e32 v170, v189, v166
	v_fma_f32 v164, -v164, v170, v168
	v_div_fmas_f32 v164, v164, v166, v170
	v_div_fixup_f32 v164, v164, v141, 1.0
	global_load_dword v208, v[196:197], off
	v_mad_i64_i32 v[196:197], s[6:7], v171, s46, v[194:195]
	global_load_dword v209, v[196:197], off
	v_mad_i64_i32 v[196:197], s[6:7], v172, s46, v[194:195]
	global_load_dword v210, v[196:197], off
	v_mad_i64_i32 v[196:197], s[6:7], v173, s46, v[194:195]
	global_load_dword v211, v[196:197], off
	v_mad_i64_i32 v[196:197], s[6:7], v174, s46, v[194:195]
	global_load_dword v212, v[196:197], off
	v_mad_i64_i32 v[196:197], s[6:7], v175, s46, v[194:195]
	global_load_dword v213, v[196:197], off
	v_mad_i64_i32 v[196:197], s[6:7], v176, s46, v[194:195]
	v_mad_i64_i32 v[194:195], s[6:7], v177, s46, v[194:195]
	global_load_dword v214, v[196:197], off
	global_load_dword v215, v[194:195], off
	s_waitcnt vmcnt(0)
	v_add_f32_e32 v141, 0, v208
	v_add_f32_e32 v141, v141, v209
	v_add_f32_e32 v141, v141, v210
	v_add_f32_e32 v141, v141, v211
	v_add_f32_e32 v141, v141, v212
	v_add_f32_e32 v141, v141, v213
	v_add_f32_e32 v141, v141, v214
	v_add_f32_e32 v141, v141, v215
	ds_bpermute_b32 v166, v169, v141
	s_waitcnt lgkmcnt(0)
	v_add_f32_e32 v141, v141, v166
	ds_bpermute_b32 v166, v167, v141
	s_waitcnt lgkmcnt(0)
	v_add_f32_e32 v141, v141, v166
	v_fmamk_f32 v141, v141, 0x3a000000, v220
	v_cmp_gt_f32_e32 vcc, s43, v141
	v_mul_f32_e32 v166, 0x4f800000, v141
	s_nop 0
	v_cndmask_b32_e32 v141, v141, v166, vcc
	v_sqrt_f32_e32 v166, v141
	s_nop 0
	v_add_u32_e32 v168, -1, v166
	v_fma_f32 v170, -v168, v166, v141
	v_cmp_ge_f32_e64 s[6:7], 0, v170
	v_add_u32_e32 v170, 1, v166
	s_nop 0
	v_cndmask_b32_e64 v168, v166, v168, s[6:7]
	v_fma_f32 v166, -v170, v166, v141
	v_cmp_lt_f32_e64 s[6:7], 0, v166
	s_nop 1
	v_cndmask_b32_e64 v166, v168, v170, s[6:7]
	v_mul_f32_e32 v168, 0x37800000, v166
	v_cndmask_b32_e32 v166, v166, v168, vcc
	v_cmp_class_f32_e32 vcc, v141, v221
	s_nop 1
	v_cndmask_b32_e32 v141, v166, v141, vcc
	v_div_scale_f32 v166, s[6:7], v141, v141, 1.0
	v_rcp_f32_e32 v168, v166
	s_nop 0
	v_fma_f32 v170, -v166, v168, 1.0
	v_fmac_f32_e32 v168, v170, v168
	v_div_scale_f32 v170, vcc, 1.0, v141, 1.0
	v_mul_f32_e32 v189, v170, v168
	v_fma_f32 v194, -v166, v189, v170
	v_fmac_f32_e32 v189, v194, v168
	v_fma_f32 v166, -v166, v189, v170
	v_lshl_add_u64 v[194:195], v[144:145], 2, s[14:15]
	v_div_fmas_f32 v166, v166, v168, v189
	v_mad_i64_i32 v[196:197], s[6:7], v154, s46, v[194:195]
	v_div_fixup_f32 v166, v166, v141, 1.0
	global_load_dword v208, v[196:197], off
	v_mad_i64_i32 v[196:197], s[6:7], v171, s46, v[194:195]
	global_load_dword v209, v[196:197], off
	v_mad_i64_i32 v[196:197], s[6:7], v172, s46, v[194:195]
	global_load_dword v210, v[196:197], off
	v_mad_i64_i32 v[196:197], s[6:7], v173, s46, v[194:195]
	global_load_dword v211, v[196:197], off
	v_mad_i64_i32 v[196:197], s[6:7], v174, s46, v[194:195]
	global_load_dword v212, v[196:197], off
	v_mad_i64_i32 v[196:197], s[6:7], v175, s46, v[194:195]
	global_load_dword v213, v[196:197], off
	v_mad_i64_i32 v[196:197], s[6:7], v176, s46, v[194:195]
	v_mad_i64_i32 v[194:195], s[6:7], v177, s46, v[194:195]
	global_load_dword v214, v[196:197], off
	global_load_dword v215, v[194:195], off
	s_waitcnt vmcnt(0)
	v_add_f32_e32 v141, 0, v208
	v_add_f32_e32 v141, v141, v209
	v_add_f32_e32 v141, v141, v210
	v_add_f32_e32 v141, v141, v211
	v_add_f32_e32 v141, v141, v212
	v_add_f32_e32 v141, v141, v213
	v_add_f32_e32 v141, v141, v214
	v_add_f32_e32 v141, v141, v215
	ds_bpermute_b32 v168, v169, v141
	s_waitcnt lgkmcnt(0)
	v_add_f32_e32 v141, v141, v168
	ds_bpermute_b32 v168, v167, v141
	s_waitcnt lgkmcnt(0)
; __device__ __forceinline__ void rows_rstd(const float* SS, const Unit& u, int wr, int fr, int fq, float (&rs)[2][4]) {
;     ...
;             for (int m = 0; m < 4; ++m) rs[ai][m] = RSTD[u.pm * BM + ai * HALF + wr * 64 + m * 16 + fr];
;     } else {
; #pragma unroll
;         for (int ai = 0; ai < 2; ++ai)
; #pragma unroll
;             for (int m = 0; m < 4; ++m) {
;                 const int row = u.pm * BM + ai * HALF + wr * 64 + m * 16 + fr; float s = 0.f;
; #pragma unroll
;                 for (int j = 0; j < 8; ++j) s += SS[(size_t)(fq * 8 + j) * MPAD + row];
;                 s += __shfl_xor(s, 16); s += __shfl_xor(s, 32);
;                 rs[ai][m] = 1.0f / sqrtf(s * (1.0f / 2048.0f) + RMS_EPS);
	v_add_f32_e32 v141, v141, v168
	v_fmamk_f32 v141, v141, 0x3a000000, v220
	v_cmp_gt_f32_e32 vcc, s43, v141
	v_mul_f32_e32 v168, 0x4f800000, v141
	s_nop 0
	v_cndmask_b32_e32 v141, v141, v168, vcc
	v_sqrt_f32_e32 v168, v141
	s_nop 0
	v_add_u32_e32 v170, -1, v168
	v_fma_f32 v189, -v170, v168, v141
	v_cmp_ge_f32_e64 s[6:7], 0, v189
	v_add_u32_e32 v189, 1, v168
	s_nop 0
	v_cndmask_b32_e64 v170, v168, v170, s[6:7]
	v_fma_f32 v168, -v189, v168, v141
	v_cmp_lt_f32_e64 s[6:7], 0, v168
	s_nop 1
	v_cndmask_b32_e64 v168, v170, v189, s[6:7]
	v_mul_f32_e32 v170, 0x37800000, v168
	v_cndmask_b32_e32 v168, v168, v170, vcc
	v_cmp_class_f32_e32 vcc, v141, v221
	s_nop 1
	v_cndmask_b32_e32 v141, v168, v141, vcc
	v_div_scale_f32 v168, s[6:7], v141, v141, 1.0
	v_rcp_f32_e32 v170, v168
	s_nop 0
	v_fma_f32 v189, -v168, v170, 1.0
	v_fmac_f32_e32 v170, v189, v170
	v_div_scale_f32 v189, vcc, 1.0, v141, 1.0
	v_mul_f32_e32 v194, v189, v170
	v_fma_f32 v195, -v168, v194, v189
	v_fmac_f32_e32 v194, v195, v170
	v_fma_f32 v168, -v168, v194, v189
	v_div_fmas_f32 v168, v168, v170, v194
	v_lshl_add_u64 v[194:195], v[142:143], 2, s[14:15]
	v_mad_i64_i32 v[196:197], s[6:7], v154, s46, v[194:195]
	v_div_fixup_f32 v168, v168, v141, 1.0
	global_load_dword v208, v[196:197], off
	v_mad_i64_i32 v[196:197], s[6:7], v171, s46, v[194:195]
	global_load_dword v209, v[196:197], off
	v_mad_i64_i32 v[196:197], s[6:7], v172, s46, v[194:195]
	global_load_dword v210, v[196:197], off
	v_mad_i64_i32 v[196:197], s[6:7], v173, s46, v[194:195]
	global_load_dword v211, v[196:197], off
	v_mad_i64_i32 v[196:197], s[6:7], v174, s46, v[194:195]
	global_load_dword v212, v[196:197], off
	v_mad_i64_i32 v[196:197], s[6:7], v175, s46, v[194:195]
	global_load_dword v213, v[196:197], off
	v_mad_i64_i32 v[196:197], s[6:7], v176, s46, v[194:195]
	v_mad_i64_i32 v[194:195], s[6:7], v177, s46, v[194:195]
	global_load_dword v214, v[196:197], off
	global_load_dword v215, v[194:195], off
	s_waitcnt vmcnt(0)
	v_add_f32_e32 v141, 0, v208
	v_add_f32_e32 v141, v141, v209
	v_add_f32_e32 v141, v141, v210
	v_add_f32_e32 v141, v141, v211
	v_add_f32_e32 v141, v141, v212
	v_add_f32_e32 v141, v141, v213
	v_add_f32_e32 v141, v141, v214
	v_add_f32_e32 v141, v141, v215
	ds_bpermute_b32 v170, v169, v141
	s_waitcnt lgkmcnt(0)
	v_add_f32_e32 v141, v141, v170
	ds_bpermute_b32 v170, v167, v141
	s_waitcnt lgkmcnt(0)
	v_add_f32_e32 v141, v141, v170
	v_fmamk_f32 v141, v141, 0x3a000000, v220
	v_cmp_gt_f32_e32 vcc, s43, v141
	v_mul_f32_e32 v170, 0x4f800000, v141
	s_nop 0
	v_cndmask_b32_e32 v141, v141, v170, vcc
	v_sqrt_f32_e32 v170, v141
	s_nop 0
	v_add_u32_e32 v189, -1, v170
	v_fma_f32 v194, -v189, v170, v141
	v_cmp_ge_f32_e64 s[6:7], 0, v194
	v_add_u32_e32 v194, 1, v170
	s_nop 0
	v_cndmask_b32_e64 v189, v170, v189, s[6:7]
	v_fma_f32 v170, -v194, v170, v141
	v_cmp_lt_f32_e64 s[6:7], 0, v170
	s_nop 1
	v_cndmask_b32_e64 v170, v189, v194, s[6:7]
	v_mul_f32_e32 v189, 0x37800000, v170
	v_cndmask_b32_e32 v170, v170, v189, vcc
	v_cmp_class_f32_e32 vcc, v141, v221
	s_nop 1
	v_cndmask_b32_e32 v141, v170, v141, vcc
	v_div_scale_f32 v170, s[6:7], v141, v141, 1.0
	v_rcp_f32_e32 v189, v170
	s_nop 0
	v_fma_f32 v194, -v170, v189, 1.0
	v_fmac_f32_e32 v189, v194, v189
	v_div_scale_f32 v194, vcc, 1.0, v141, 1.0
	v_mul_f32_e32 v195, v194, v189
	v_fma_f32 v196, -v170, v195, v194
	v_fmac_f32_e32 v195, v196, v189
	v_fma_f32 v170, -v170, v195, v194
	v_div_fmas_f32 v170, v170, v189, v195
	v_div_fixup_f32 v170, v170, v141, 1.0
	v_ashrrev_i32_e32 v141, 31, v140
	v_lshl_add_u64 v[194:195], v[140:141], 2, s[14:15]
	v_mad_i64_i32 v[196:197], s[6:7], v154, s46, v[194:195]
	global_load_dword v208, v[196:197], off
	v_mad_i64_i32 v[196:197], s[6:7], v171, s46, v[194:195]
	global_load_dword v209, v[196:197], off
	v_mad_i64_i32 v[196:197], s[6:7], v172, s46, v[194:195]
	global_load_dword v210, v[196:197], off
	v_mad_i64_i32 v[172:173], s[6:7], v173, s46, v[194:195]
	global_load_dword v211, v[172:173], off
	v_mad_i64_i32 v[172:173], s[6:7], v174, s46, v[194:195]
	global_load_dword v212, v[172:173], off
	v_mad_i64_i32 v[172:173], s[6:7], v175, s46, v[194:195]
	global_load_dword v213, v[172:173], off
	v_mad_i64_i32 v[172:173], s[6:7], v176, s46, v[194:195]
	global_load_dword v214, v[172:173], off
	v_mad_i64_i32 v[172:173], s[6:7], v177, s46, v[194:195]
	global_load_dword v215, v[172:173], off
	s_waitcnt vmcnt(0)
	v_add_f32_e32 v189, 0, v208
	v_add_f32_e32 v171, v189, v209
	v_add_f32_e32 v171, v171, v210
	v_add_f32_e32 v171, v171, v211
	v_add_f32_e32 v171, v171, v212
	v_add_f32_e32 v171, v171, v213
	v_add_f32_e32 v171, v171, v214
	v_add_f32_e32 v171, v171, v215
	ds_bpermute_b32 v169, v169, v171
	s_waitcnt lgkmcnt(0)
	v_add_f32_e32 v169, v171, v169
	ds_bpermute_b32 v167, v167, v169
	s_waitcnt lgkmcnt(0)
	v_add_f32_e32 v167, v169, v167
	v_fmamk_f32 v167, v167, 0x3a000000, v220
	v_cmp_gt_f32_e32 vcc, s43, v167
	v_mul_f32_e32 v169, 0x4f800000, v167
	s_nop 0
	v_cndmask_b32_e32 v167, v167, v169, vcc
	v_sqrt_f32_e32 v169, v167
	s_nop 0
	v_add_u32_e32 v171, -1, v169
	v_fma_f32 v172, -v171, v169, v167
	v_cmp_ge_f32_e64 s[6:7], 0, v172
	v_add_u32_e32 v172, 1, v169
	s_nop 0
	v_cndmask_b32_e64 v171, v169, v171, s[6:7]
	v_fma_f32 v169, -v172, v169, v167
	v_cmp_lt_f32_e64 s[6:7], 0, v169
	s_nop 1
	v_cndmask_b32_e64 v169, v171, v172, s[6:7]
	v_mul_f32_e32 v171, 0x37800000, v169
	v_cndmask_b32_e32 v169, v169, v171, vcc
	v_cmp_class_f32_e32 vcc, v167, v221
	s_nop 1
	v_cndmask_b32_e32 v167, v169, v167, vcc
	v_div_scale_f32 v169, s[6:7], v167, v167, 1.0
	v_rcp_f32_e32 v171, v169
	s_mov_b64 s[6:7], 0
	v_fma_f32 v172, -v169, v171, 1.0
	v_fmac_f32_e32 v171, v172, v171
	v_div_scale_f32 v172, vcc, 1.0, v167, 1.0
	v_mul_f32_e32 v173, v172, v171
	v_fma_f32 v174, -v169, v173, v172
	v_fmac_f32_e32 v173, v174, v171
	v_fma_f32 v169, -v169, v173, v172
	v_div_fmas_f32 v169, v169, v171, v173
	v_div_fixup_f32 v172, v169, v167, 1.0

; template <int NSL>
; __device__ __forceinline__ void phase_samp_fin(KArgs a, float scale, int gw, int NGW, int lane) {
;     ...
;     {
;         float* RSTD = (float*)(a->ws + WS_RSTD);
;         for (int r = gw * 64 + lane; r < MPROMPT; r += NGW * 64) { float s = 0.f;
; #pragma unroll
;             for (int j = 0; j < 32; ++j) s += SS[(size_t)j * MPAD + r];
;             RSTD[r] = 1.0f / sqrtf(s * (1.0f / 2048.0f) + RMS_EPS); }
;     }
.LBB0_439:
	v_add_co_u32_e32 v8, vcc, 0x8000, v4
	global_load_dword v132, v[4:5], off
	s_nop 0
	v_addc_co_u32_e32 v9, vcc, 0, v5, vcc
	global_load_dword v133, v[8:9], off offset:1024
	v_add_co_u32_e32 v8, vcc, 0x10000, v4
	v_add_u32_e32 v2, s36, v2
	s_nop 0
	v_addc_co_u32_e32 v9, vcc, 0, v5, vcc
	global_load_dword v134, v[8:9], off offset:2048
	v_add_co_u32_e32 v8, vcc, 0x18000, v4
	s_nop 1
	v_addc_co_u32_e32 v9, vcc, 0, v5, vcc
	global_load_dword v135, v[8:9], off offset:3072
	v_add_co_u32_e32 v8, vcc, 0x21000, v4
	s_nop 1
	v_addc_co_u32_e32 v9, vcc, 0, v5, vcc
	global_load_dword v136, v[8:9], off
	v_add_co_u32_e32 v8, vcc, 0x29000, v4
	s_nop 1
	v_addc_co_u32_e32 v9, vcc, 0, v5, vcc
	global_load_dword v137, v[8:9], off offset:1024
	v_add_co_u32_e32 v8, vcc, 0x31000, v4
	s_nop 1
	v_addc_co_u32_e32 v9, vcc, 0, v5, vcc
	global_load_dword v138, v[8:9], off offset:2048
	v_add_co_u32_e32 v8, vcc, 0x39000, v4
	s_nop 1
	v_addc_co_u32_e32 v9, vcc, 0, v5, vcc
	global_load_dword v139, v[8:9], off offset:3072
	v_add_co_u32_e32 v8, vcc, 0x42000, v4
	s_nop 1
	v_addc_co_u32_e32 v9, vcc, 0, v5, vcc
	global_load_dword v140, v[8:9], off
	v_add_co_u32_e32 v8, vcc, 0x4a000, v4
	s_nop 1
	v_addc_co_u32_e32 v9, vcc, 0, v5, vcc
	global_load_dword v141, v[8:9], off offset:1024
	v_add_co_u32_e32 v8, vcc, 0x52000, v4
	s_nop 1
	v_addc_co_u32_e32 v9, vcc, 0, v5, vcc
	global_load_dword v142, v[8:9], off offset:2048
	v_add_co_u32_e32 v8, vcc, 0x5a000, v4
	s_nop 1
	v_addc_co_u32_e32 v9, vcc, 0, v5, vcc
	global_load_dword v143, v[8:9], off offset:3072
	v_add_co_u32_e32 v8, vcc, 0x63000, v4
	s_nop 1
	v_addc_co_u32_e32 v9, vcc, 0, v5, vcc
	global_load_dword v144, v[8:9], off
	v_add_co_u32_e32 v8, vcc, 0x6b000, v4
	s_nop 1
	v_addc_co_u32_e32 v9, vcc, 0, v5, vcc
	global_load_dword v145, v[8:9], off offset:1024
	v_add_co_u32_e32 v8, vcc, 0x73000, v4
	s_nop 1
	v_addc_co_u32_e32 v9, vcc, 0, v5, vcc
	global_load_dword v146, v[8:9], off offset:2048
	v_add_co_u32_e32 v8, vcc, 0x7b000, v4
	s_nop 1
	v_addc_co_u32_e32 v9, vcc, 0, v5, vcc
	global_load_dword v147, v[8:9], off offset:3072
	v_add_co_u32_e32 v8, vcc, 0x84000, v4
	s_nop 1
	v_addc_co_u32_e32 v9, vcc, 0, v5, vcc
	global_load_dword v148, v[8:9], off
	v_add_co_u32_e32 v8, vcc, 0x8c000, v4
	s_nop 1
	v_addc_co_u32_e32 v9, vcc, 0, v5, vcc
	global_load_dword v149, v[8:9], off offset:1024
	v_add_co_u32_e32 v8, vcc, 0x94000, v4
	s_nop 1
	v_addc_co_u32_e32 v9, vcc, 0, v5, vcc
	global_load_dword v150, v[8:9], off offset:2048
	v_add_co_u32_e32 v8, vcc, 0x9c000, v4
	s_nop 1
	v_addc_co_u32_e32 v9, vcc, 0, v5, vcc
	global_load_dword v151, v[8:9], off offset:3072
	v_add_co_u32_e32 v8, vcc, 0xa5000, v4
	s_nop 1
	v_addc_co_u32_e32 v9, vcc, 0, v5, vcc
	global_load_dword v152, v[8:9], off
	v_add_co_u32_e32 v8, vcc, 0xad000, v4
	s_nop 1
	v_addc_co_u32_e32 v9, vcc, 0, v5, vcc
	global_load_dword v153, v[8:9], off offset:1024
	v_add_co_u32_e32 v8, vcc, 0xb5000, v4
	s_nop 1
	v_addc_co_u32_e32 v9, vcc, 0, v5, vcc
	global_load_dword v154, v[8:9], off offset:2048
	v_add_co_u32_e32 v8, vcc, 0xbd000, v4
	s_nop 1
	v_addc_co_u32_e32 v9, vcc, 0, v5, vcc
	global_load_dword v155, v[8:9], off offset:3072
	v_add_co_u32_e32 v8, vcc, 0xc6000, v4
	s_nop 1
	v_addc_co_u32_e32 v9, vcc, 0, v5, vcc
	global_load_dword v156, v[8:9], off
	v_add_co_u32_e32 v8, vcc, 0xce000, v4
	s_nop 1
	v_addc_co_u32_e32 v9, vcc, 0, v5, vcc
	global_load_dword v157, v[8:9], off offset:1024
	v_add_co_u32_e32 v8, vcc, 0xd6000, v4
	s_nop 1
	v_addc_co_u32_e32 v9, vcc, 0, v5, vcc
	global_load_dword v158, v[8:9], off offset:2048
	v_add_co_u32_e32 v8, vcc, 0xde000, v4
	s_nop 1
	v_addc_co_u32_e32 v9, vcc, 0, v5, vcc
	global_load_dword v159, v[8:9], off offset:3072
	v_add_co_u32_e32 v8, vcc, 0xe7000, v4
	s_nop 1
	v_addc_co_u32_e32 v9, vcc, 0, v5, vcc
	global_load_dword v160, v[8:9], off
	v_add_co_u32_e32 v8, vcc, 0xef000, v4
	s_nop 1
	v_addc_co_u32_e32 v9, vcc, 0, v5, vcc
	global_load_dword v161, v[8:9], off offset:1024
	v_add_co_u32_e32 v8, vcc, 0xf7000, v4
	s_nop 1
	v_addc_co_u32_e32 v9, vcc, 0, v5, vcc
	global_load_dword v162, v[8:9], off offset:2048
	v_add_co_u32_e32 v8, vcc, 0xff000, v4
	s_nop 1
	v_addc_co_u32_e32 v9, vcc, 0, v5, vcc
	global_load_dword v163, v[8:9], off offset:3072
	s_waitcnt vmcnt(0)
	v_add_f32_e32 v3, 0, v132
	v_add_f32_e32 v3, v3, v133
	v_add_f32_e32 v3, v3, v134
	v_add_f32_e32 v3, v3, v135
	v_add_f32_e32 v3, v3, v136
	v_add_f32_e32 v3, v3, v137
	v_add_f32_e32 v3, v3, v138
	v_add_f32_e32 v3, v3, v139
	v_add_f32_e32 v3, v3, v140
	v_add_f32_e32 v3, v3, v141
	v_add_f32_e32 v3, v3, v142
	v_add_f32_e32 v3, v3, v143
	v_add_f32_e32 v3, v3, v144
	v_add_f32_e32 v3, v3, v145
	v_add_f32_e32 v3, v3, v146
	v_add_f32_e32 v3, v3, v147
	v_add_f32_e32 v3, v3, v148
	v_add_f32_e32 v3, v3, v149
	v_add_f32_e32 v3, v3, v150
	v_add_f32_e32 v3, v3, v151
	v_add_f32_e32 v3, v3, v152
	v_add_f32_e32 v3, v3, v153
	v_add_f32_e32 v3, v3, v154
	v_add_f32_e32 v3, v3, v155
	v_add_f32_e32 v3, v3, v156
	v_add_f32_e32 v3, v3, v157
	v_add_f32_e32 v3, v3, v158
	v_add_f32_e32 v3, v3, v159
	v_add_f32_e32 v3, v3, v160
	v_add_f32_e32 v3, v3, v161
	v_add_f32_e32 v3, v3, v162
	v_add_f32_e32 v3, v3, v163
	v_fmamk_f32 v3, v3, 0x3a000000, v220
	v_cmp_gt_f32_e32 vcc, s43, v3
	v_mul_f32_e32 v7, 0x4f800000, v3
	s_nop 0
	v_cndmask_b32_e32 v3, v3, v7, vcc
	v_sqrt_f32_e32 v7, v3
	s_nop 0
	v_add_u32_e32 v8, -1, v7
	v_fma_f32 v9, -v8, v7, v3
	v_cmp_ge_f32_e64 s[4:5], 0, v9
	v_add_u32_e32 v9, 1, v7
	s_nop 0
	v_cndmask_b32_e64 v8, v7, v8, s[4:5]
	v_fma_f32 v7, -v9, v7, v3
	v_cmp_lt_f32_e64 s[4:5], 0, v7
	s_nop 1
	v_cndmask_b32_e64 v7, v8, v9, s[4:5]
	v_mul_f32_e32 v8, 0x37800000, v7
	v_cndmask_b32_e32 v7, v7, v8, vcc
	v_cmp_class_f32_e32 vcc, v3, v221
	s_nop 1
	v_cndmask_b32_e32 v3, v7, v3, vcc
	v_div_scale_f32 v7, s[4:5], v3, v3, 1.0
	v_rcp_f32_e32 v8, v7
	s_nop 0
	v_fma_f32 v9, -v7, v8, 1.0
	v_fmac_f32_e32 v8, v9, v8
	v_div_scale_f32 v9, vcc, 1.0, v3, 1.0
	v_mul_f32_e32 v10, v9, v8
	v_fma_f32 v11, -v7, v10, v9
	v_fmac_f32_e32 v10, v11, v8
	v_fma_f32 v7, -v7, v10, v9
	v_div_fmas_f32 v7, v7, v8, v10
	v_add_co_u32_e32 v8, vcc, 0x108000, v4
	v_div_fixup_f32 v3, v7, v3, 1.0
	s_nop 0
	v_addc_co_u32_e32 v9, vcc, 0, v5, vcc
	v_cmp_lt_i32_e32 vcc, s40, v2
	v_lshl_add_u64 v[4:5], v[4:5], 0, s[50:51]
	s_or_b64 s[12:13], vcc, s[12:13]
	global_store_dword v[8:9], v3, off offset:256
	s_andn2_b64 exec, exec, s[12:13]
	s_cbranch_execnz .LBB0_439

; __device__ __forceinline__ void rows_rstd(const float* SS, const Unit& u, int wr, int fr, int fq, float (&rs)[2][4]) {
;     if (u.pm < 32) { const float* RSTD = (const float*)((const char*)SS + SS_TO_RSTD);
; #pragma unroll
;         for (int ai = 0; ai < 2; ++ai)
; #pragma unroll
;             for (int m = 0; m < 4; ++m) rs[ai][m] = RSTD[u.pm * BM + ai * HALF + wr * 64 + m * 16 + fr];
;     } else {
; #pragma unroll
;         for (int ai = 0; ai < 2; ++ai)
; #pragma unroll
;             for (int m = 0; m < 4; ++m) {
;                 const int row = u.pm * BM + ai * HALF + wr * 64 + m * 16 + fr; float s = 0.f;
; #pragma unroll
;                 for (int j = 0; j < 8; ++j) s += SS[(size_t)(fq * 8 + j) * MPAD + row];
;                 s += __shfl_xor(s, 16); s += __shfl_xor(s, 32);
;                 rs[ai][m] = 1.0f / sqrtf(s * (1.0f / 2048.0f) + RMS_EPS);
;             }
;     }
; }
.LBB0_525:
	s_lshl_b32 s6, s48, 8
	v_mov_b32_e32 v141, v189
	v_mov_b32_e32 v140, v194
	s_add_i32 s6, s6, s56
	s_cmp_lt_i32 s48, 32
	v_add_u32_e32 v170, s6, v140
	v_add_u32_e32 v152, 16, v170
	v_add_u32_e32 v150, 32, v170
	v_add_u32_e32 v148, 48, v170
	v_add_u32_e32 v146, 0x80, v170
	v_add_u32_e32 v144, 0x90, v170
	v_add_u32_e32 v142, 0xa0, v170
	s_mov_b64 s[6:7], -1
	v_ashrrev_i32_e32 v171, 31, v170
	v_lshlrev_b32_e32 v155, 3, v141
	v_ashrrev_i32_e32 v153, 31, v152
	v_ashrrev_i32_e32 v151, 31, v150
	v_ashrrev_i32_e32 v149, 31, v148
	v_ashrrev_i32_e32 v147, 31, v146
	v_ashrrev_i32_e32 v145, 31, v144
	v_ashrrev_i32_e32 v143, 31, v142
	v_add_u32_e32 v140, 0xb0, v170
	s_cbranch_scc1 .LBB0_527
	v_and_b32_e32 v154, 64, v219
	v_lshlrev_b32_e32 v157, 3, v141
	v_xor_b32_e32 v141, 16, v219
	v_add_u32_e32 v154, 64, v154
	v_cmp_lt_i32_e32 vcc, v141, v154
	v_lshl_add_u64 v[174:175], v[170:171], 2, s[18:19]
	v_mad_i64_i32 v[162:163], s[6:7], v157, s46, v[174:175]
	v_cndmask_b32_e32 v141, v219, v141, vcc
	v_lshlrev_b32_e32 v160, 2, v141
	v_xor_b32_e32 v141, 32, v219
	v_cmp_lt_i32_e32 vcc, v141, v154
	v_or_b32_e32 v161, 1, v157
	s_nop 0
	v_cndmask_b32_e32 v141, v219, v141, vcc
	v_lshlrev_b32_e32 v159, 2, v141
	global_load_dword v208, v[162:163], off
	v_mad_i64_i32 v[162:163], s[6:7], v161, s46, v[174:175]
	global_load_dword v209, v[162:163], off
	v_or_b32_e32 v163, 2, v157
	v_mad_i64_i32 v[164:165], s[6:7], v163, s46, v[174:175]
	global_load_dword v210, v[164:165], off
	v_or_b32_e32 v165, 3, v157
	v_mad_i64_i32 v[166:167], s[6:7], v165, s46, v[174:175]
	global_load_dword v211, v[166:167], off
	v_or_b32_e32 v166, 4, v157
	v_mad_i64_i32 v[168:169], s[6:7], v166, s46, v[174:175]
	v_or_b32_e32 v167, 5, v157
	global_load_dword v212, v[168:169], off
	v_mad_i64_i32 v[168:169], s[6:7], v167, s46, v[174:175]
	global_load_dword v213, v[168:169], off
	v_or_b32_e32 v169, 6, v157
	v_mad_i64_i32 v[172:173], s[6:7], v169, s46, v[174:175]
	global_load_dword v214, v[172:173], off
	v_or_b32_e32 v173, 7, v157
	v_mad_i64_i32 v[174:175], s[6:7], v173, s46, v[174:175]
	global_load_dword v215, v[174:175], off
	v_lshl_add_u64 v[174:175], v[152:153], 2, s[18:19]
	s_waitcnt vmcnt(0)
	v_add_f32_e32 v141, 0, v208
	v_add_f32_e32 v141, v141, v209
	v_add_f32_e32 v141, v141, v210
	v_add_f32_e32 v141, v141, v211
	v_add_f32_e32 v141, v141, v212
	v_add_f32_e32 v141, v141, v213
	v_add_f32_e32 v141, v141, v214
	v_add_f32_e32 v141, v141, v215
	ds_bpermute_b32 v154, v160, v141
	s_waitcnt lgkmcnt(0)
	v_add_f32_e32 v141, v141, v154
	ds_bpermute_b32 v154, v159, v141
	s_waitcnt lgkmcnt(0)
	v_add_f32_e32 v141, v141, v154
	v_fmamk_f32 v141, v141, 0x3a000000, v220
	v_cmp_gt_f32_e32 vcc, s43, v141
	v_mul_f32_e32 v154, 0x4f800000, v141
	s_nop 0
	v_cndmask_b32_e32 v141, v141, v154, vcc
	v_sqrt_f32_e32 v154, v141
	s_nop 0
	v_add_u32_e32 v156, -1, v154
	v_fma_f32 v158, -v156, v154, v141
	v_cmp_ge_f32_e64 s[6:7], 0, v158
	v_add_u32_e32 v158, 1, v154
	s_nop 0
	v_cndmask_b32_e64 v156, v154, v156, s[6:7]
	v_fma_f32 v154, -v158, v154, v141
	v_cmp_lt_f32_e64 s[6:7], 0, v154
	s_nop 1
	v_cndmask_b32_e64 v154, v156, v158, s[6:7]
	v_mul_f32_e32 v156, 0x37800000, v154
	v_cndmask_b32_e32 v154, v154, v156, vcc
	v_cmp_class_f32_e32 vcc, v141, v221
	v_mad_i64_i32 v[176:177], s[6:7], v157, s46, v[174:175]
	s_nop 0
	v_cndmask_b32_e32 v141, v154, v141, vcc
	v_div_scale_f32 v154, s[6:7], v141, v141, 1.0
	v_rcp_f32_e32 v156, v154
	s_nop 0
	v_fma_f32 v158, -v154, v156, 1.0
	v_fmac_f32_e32 v156, v158, v156
	v_div_scale_f32 v158, vcc, 1.0, v141, 1.0
	v_mul_f32_e32 v162, v158, v156
	v_fma_f32 v164, -v154, v162, v158
	v_fmac_f32_e32 v162, v164, v156
	v_fma_f32 v154, -v154, v162, v158
	v_div_fmas_f32 v154, v154, v156, v162
	v_div_fixup_f32 v172, v154, v141, 1.0
	global_load_dword v208, v[176:177], off
	v_mad_i64_i32 v[176:177], s[6:7], v161, s46, v[174:175]
	global_load_dword v209, v[176:177], off
	v_mad_i64_i32 v[176:177], s[6:7], v163, s46, v[174:175]
	global_load_dword v210, v[176:177], off
	v_mad_i64_i32 v[176:177], s[6:7], v165, s46, v[174:175]
	global_load_dword v211, v[176:177], off
	v_mad_i64_i32 v[176:177], s[6:7], v166, s46, v[174:175]
	global_load_dword v212, v[176:177], off
	v_mad_i64_i32 v[176:177], s[6:7], v167, s46, v[174:175]
	global_load_dword v213, v[176:177], off
	v_mad_i64_i32 v[176:177], s[6:7], v169, s46, v[174:175]
	v_mad_i64_i32 v[174:175], s[6:7], v173, s46, v[174:175]
	global_load_dword v214, v[176:177], off
	global_load_dword v215, v[174:175], off
	v_lshl_add_u64 v[174:175], v[150:151], 2, s[18:19]
	s_waitcnt vmcnt(0)
	v_add_f32_e32 v141, 0, v208
	v_add_f32_e32 v141, v141, v209
	v_add_f32_e32 v141, v141, v210
	v_add_f32_e32 v141, v141, v211
	v_add_f32_e32 v141, v141, v212
	v_add_f32_e32 v141, v141, v213
	v_add_f32_e32 v141, v141, v214
	v_add_f32_e32 v141, v141, v215
	ds_bpermute_b32 v154, v160, v141
	s_waitcnt lgkmcnt(0)
	v_add_f32_e32 v141, v141, v154
	ds_bpermute_b32 v154, v159, v141
	s_waitcnt lgkmcnt(0)
; __device__ __forceinline__ void rows_rstd(const float* SS, const Unit& u, int wr, int fr, int fq, float (&rs)[2][4]) {
;     ...
;             for (int m = 0; m < 4; ++m) rs[ai][m] = RSTD[u.pm * BM + ai * HALF + wr * 64 + m * 16 + fr];
;     } else {
; #pragma unroll
;         for (int ai = 0; ai < 2; ++ai)
; #pragma unroll
;             for (int m = 0; m < 4; ++m) {
;                 const int row = u.pm * BM + ai * HALF + wr * 64 + m * 16 + fr; float s = 0.f;
; #pragma unroll
;                 for (int j = 0; j < 8; ++j) s += SS[(size_t)(fq * 8 + j) * MPAD + row];
;                 s += __shfl_xor(s, 16); s += __shfl_xor(s, 32);
;                 rs[ai][m] = 1.0f / sqrtf(s * (1.0f / 2048.0f) + RMS_EPS);
	v_add_f32_e32 v141, v141, v154
	v_fmamk_f32 v141, v141, 0x3a000000, v220
	v_cmp_gt_f32_e32 vcc, s43, v141
	v_mul_f32_e32 v154, 0x4f800000, v141
	s_nop 0
	v_cndmask_b32_e32 v141, v141, v154, vcc
	v_sqrt_f32_e32 v154, v141
	s_nop 0
	v_add_u32_e32 v156, -1, v154
	v_fma_f32 v158, -v156, v154, v141
	v_cmp_ge_f32_e64 s[6:7], 0, v158
	v_add_u32_e32 v158, 1, v154
	s_nop 0
	v_cndmask_b32_e64 v156, v154, v156, s[6:7]
	v_fma_f32 v154, -v158, v154, v141
	v_cmp_lt_f32_e64 s[6:7], 0, v154
	s_nop 1
	v_cndmask_b32_e64 v154, v156, v158, s[6:7]
	v_mul_f32_e32 v156, 0x37800000, v154
	v_cndmask_b32_e32 v154, v154, v156, vcc
	v_cmp_class_f32_e32 vcc, v141, v221
	v_mad_i64_i32 v[176:177], s[6:7], v157, s46, v[174:175]
	s_nop 0
	v_cndmask_b32_e32 v141, v154, v141, vcc
	v_div_scale_f32 v154, s[6:7], v141, v141, 1.0
	v_rcp_f32_e32 v156, v154
	s_nop 0
	v_fma_f32 v158, -v154, v156, 1.0
	v_fmac_f32_e32 v156, v158, v156
	v_div_scale_f32 v158, vcc, 1.0, v141, 1.0
	v_mul_f32_e32 v162, v158, v156
	v_fma_f32 v164, -v154, v162, v158
	v_fmac_f32_e32 v162, v164, v156
	v_fma_f32 v154, -v154, v162, v158
	v_div_fmas_f32 v154, v154, v156, v162
	v_div_fixup_f32 v168, v154, v141, 1.0
	global_load_dword v208, v[176:177], off
	v_mad_i64_i32 v[176:177], s[6:7], v161, s46, v[174:175]
	global_load_dword v209, v[176:177], off
	v_mad_i64_i32 v[176:177], s[6:7], v163, s46, v[174:175]
	global_load_dword v210, v[176:177], off
	v_mad_i64_i32 v[176:177], s[6:7], v165, s46, v[174:175]
	global_load_dword v211, v[176:177], off
	v_mad_i64_i32 v[176:177], s[6:7], v166, s46, v[174:175]
	global_load_dword v212, v[176:177], off
	v_mad_i64_i32 v[176:177], s[6:7], v167, s46, v[174:175]
	global_load_dword v213, v[176:177], off
	v_mad_i64_i32 v[176:177], s[6:7], v169, s46, v[174:175]
	v_mad_i64_i32 v[174:175], s[6:7], v173, s46, v[174:175]
	global_load_dword v214, v[176:177], off
	global_load_dword v215, v[174:175], off
	v_lshl_add_u64 v[174:175], v[148:149], 2, s[18:19]
	s_waitcnt vmcnt(0)
	v_add_f32_e32 v141, 0, v208
	v_add_f32_e32 v141, v141, v209
	v_add_f32_e32 v141, v141, v210
	v_add_f32_e32 v141, v141, v211
	v_add_f32_e32 v141, v141, v212
	v_add_f32_e32 v141, v141, v213
	v_add_f32_e32 v141, v141, v214
	v_add_f32_e32 v141, v141, v215
	ds_bpermute_b32 v154, v160, v141
	s_waitcnt lgkmcnt(0)
	v_add_f32_e32 v141, v141, v154
	ds_bpermute_b32 v154, v159, v141
	s_waitcnt lgkmcnt(0)
	v_add_f32_e32 v141, v141, v154
	v_fmamk_f32 v141, v141, 0x3a000000, v220
	v_cmp_gt_f32_e32 vcc, s43, v141
	v_mul_f32_e32 v154, 0x4f800000, v141
	s_nop 0
	v_cndmask_b32_e32 v141, v141, v154, vcc
	v_sqrt_f32_e32 v154, v141
	s_nop 0
	v_add_u32_e32 v156, -1, v154
	v_fma_f32 v158, -v156, v154, v141
	v_cmp_ge_f32_e64 s[6:7], 0, v158
	v_add_u32_e32 v158, 1, v154
	s_nop 0
	v_cndmask_b32_e64 v156, v154, v156, s[6:7]
	v_fma_f32 v154, -v158, v154, v141
	v_cmp_lt_f32_e64 s[6:7], 0, v154
	s_nop 1
	v_cndmask_b32_e64 v154, v156, v158, s[6:7]
	v_mul_f32_e32 v156, 0x37800000, v154
	v_cndmask_b32_e32 v154, v154, v156, vcc
	v_cmp_class_f32_e32 vcc, v141, v221
	v_mad_i64_i32 v[176:177], s[6:7], v157, s46, v[174:175]
	s_nop 0
	v_cndmask_b32_e32 v141, v154, v141, vcc
	v_div_scale_f32 v154, s[6:7], v141, v141, 1.0
	v_rcp_f32_e32 v156, v154
	s_nop 0
	v_fma_f32 v158, -v154, v156, 1.0
	v_fmac_f32_e32 v156, v158, v156
	v_div_scale_f32 v158, vcc, 1.0, v141, 1.0
	v_mul_f32_e32 v162, v158, v156
	v_fma_f32 v164, -v154, v162, v158
	v_fmac_f32_e32 v162, v164, v156
	v_fma_f32 v154, -v154, v162, v158
	v_div_fmas_f32 v154, v154, v156, v162
	v_div_fixup_f32 v164, v154, v141, 1.0
	global_load_dword v208, v[176:177], off
	v_mad_i64_i32 v[176:177], s[6:7], v161, s46, v[174:175]
	global_load_dword v209, v[176:177], off
	v_mad_i64_i32 v[176:177], s[6:7], v163, s46, v[174:175]
	global_load_dword v210, v[176:177], off
	v_mad_i64_i32 v[176:177], s[6:7], v165, s46, v[174:175]
	global_load_dword v211, v[176:177], off
	v_mad_i64_i32 v[176:177], s[6:7], v166, s46, v[174:175]
	global_load_dword v212, v[176:177], off
	v_mad_i64_i32 v[176:177], s[6:7], v167, s46, v[174:175]
	global_load_dword v213, v[176:177], off
	v_mad_i64_i32 v[176:177], s[6:7], v169, s46, v[174:175]
	v_mad_i64_i32 v[174:175], s[6:7], v173, s46, v[174:175]
	global_load_dword v214, v[176:177], off
	global_load_dword v215, v[174:175], off
	s_waitcnt vmcnt(0)
	v_add_f32_e32 v141, 0, v208
	v_add_f32_e32 v141, v141, v209
	v_add_f32_e32 v141, v141, v210
	v_add_f32_e32 v141, v141, v211
	v_add_f32_e32 v141, v141, v212
	v_add_f32_e32 v141, v141, v213
	v_add_f32_e32 v141, v141, v214
	v_add_f32_e32 v141, v141, v215
	ds_bpermute_b32 v154, v160, v141
	s_waitcnt lgkmcnt(0)
	v_add_f32_e32 v141, v141, v154
	ds_bpermute_b32 v154, v159, v141
	s_waitcnt lgkmcnt(0)
; __device__ __forceinline__ void rows_rstd(const float* SS, const Unit& u, int wr, int fr, int fq, float (&rs)[2][4]) {
;     ...
;             for (int m = 0; m < 4; ++m) rs[ai][m] = RSTD[u.pm * BM + ai * HALF + wr * 64 + m * 16 + fr];
;     } else {
; #pragma unroll
;         for (int ai = 0; ai < 2; ++ai)
; #pragma unroll
;             for (int m = 0; m < 4; ++m) {
;                 const int row = u.pm * BM + ai * HALF + wr * 64 + m * 16 + fr; float s = 0.f;
; #pragma unroll
;                 for (int j = 0; j < 8; ++j) s += SS[(size_t)(fq * 8 + j) * MPAD + row];
;                 s += __shfl_xor(s, 16); s += __shfl_xor(s, 32);
;                 rs[ai][m] = 1.0f / sqrtf(s * (1.0f / 2048.0f) + RMS_EPS);
	v_add_f32_e32 v141, v141, v154
	v_fmamk_f32 v141, v141, 0x3a000000, v220
	v_cmp_gt_f32_e32 vcc, s43, v141
	v_mul_f32_e32 v154, 0x4f800000, v141
	s_nop 0
	v_cndmask_b32_e32 v141, v141, v154, vcc
	v_sqrt_f32_e32 v154, v141
	s_nop 0
	v_add_u32_e32 v156, -1, v154
	v_fma_f32 v158, -v156, v154, v141
	v_cmp_ge_f32_e64 s[6:7], 0, v158
	v_add_u32_e32 v158, 1, v154
	s_nop 0
	v_cndmask_b32_e64 v156, v154, v156, s[6:7]
	v_fma_f32 v154, -v158, v154, v141
	v_cmp_lt_f32_e64 s[6:7], 0, v154
	s_nop 1
	v_cndmask_b32_e64 v154, v156, v158, s[6:7]
	v_mul_f32_e32 v156, 0x37800000, v154
	v_cndmask_b32_e32 v154, v154, v156, vcc
	v_cmp_class_f32_e32 vcc, v141, v221
	s_nop 1
	v_cndmask_b32_e32 v141, v154, v141, vcc
	v_div_scale_f32 v154, s[6:7], v141, v141, 1.0
	v_rcp_f32_e32 v156, v154
	s_nop 0
	v_fma_f32 v158, -v154, v156, 1.0
	v_fmac_f32_e32 v156, v158, v156
	v_div_scale_f32 v158, vcc, 1.0, v141, 1.0
	v_mul_f32_e32 v162, v158, v156
	v_fma_f32 v174, -v154, v162, v158
	v_fmac_f32_e32 v162, v174, v156
	v_fma_f32 v154, -v154, v162, v158
	v_lshl_add_u64 v[174:175], v[146:147], 2, s[18:19]
	v_div_fmas_f32 v154, v154, v156, v162
	v_mad_i64_i32 v[176:177], s[6:7], v157, s46, v[174:175]
	v_div_fixup_f32 v162, v154, v141, 1.0
	global_load_dword v208, v[176:177], off
	v_mad_i64_i32 v[176:177], s[6:7], v161, s46, v[174:175]
	global_load_dword v209, v[176:177], off
	v_mad_i64_i32 v[176:177], s[6:7], v163, s46, v[174:175]
	global_load_dword v210, v[176:177], off
	v_mad_i64_i32 v[176:177], s[6:7], v165, s46, v[174:175]
	global_load_dword v211, v[176:177], off
	v_mad_i64_i32 v[176:177], s[6:7], v166, s46, v[174:175]
	global_load_dword v212, v[176:177], off
	v_mad_i64_i32 v[176:177], s[6:7], v167, s46, v[174:175]
	global_load_dword v213, v[176:177], off
	v_mad_i64_i32 v[176:177], s[6:7], v169, s46, v[174:175]
	v_mad_i64_i32 v[174:175], s[6:7], v173, s46, v[174:175]
	global_load_dword v214, v[176:177], off
	global_load_dword v215, v[174:175], off
	s_waitcnt vmcnt(0)
	v_add_f32_e32 v141, 0, v208
	v_add_f32_e32 v141, v141, v209
	v_add_f32_e32 v141, v141, v210
	v_add_f32_e32 v141, v141, v211
	v_add_f32_e32 v141, v141, v212
	v_add_f32_e32 v141, v141, v213
	v_add_f32_e32 v141, v141, v214
	v_add_f32_e32 v141, v141, v215
	ds_bpermute_b32 v154, v160, v141
	s_waitcnt lgkmcnt(0)
	v_add_f32_e32 v141, v141, v154
	ds_bpermute_b32 v154, v159, v141
	s_waitcnt lgkmcnt(0)
	v_add_f32_e32 v141, v141, v154
	v_fmamk_f32 v141, v141, 0x3a000000, v220
	v_cmp_gt_f32_e32 vcc, s43, v141
	v_mul_f32_e32 v154, 0x4f800000, v141
	s_nop 0
	v_cndmask_b32_e32 v141, v141, v154, vcc
	v_sqrt_f32_e32 v154, v141
	s_nop 0
	v_add_u32_e32 v156, -1, v154
	v_fma_f32 v158, -v156, v154, v141
	v_cmp_ge_f32_e64 s[6:7], 0, v158
	v_add_u32_e32 v158, 1, v154
	s_nop 0
	v_cndmask_b32_e64 v156, v154, v156, s[6:7]
	v_fma_f32 v154, -v158, v154, v141
	v_cmp_lt_f32_e64 s[6:7], 0, v154
	s_nop 1
	v_cndmask_b32_e64 v154, v156, v158, s[6:7]
	v_mul_f32_e32 v156, 0x37800000, v154
	v_cndmask_b32_e32 v154, v154, v156, vcc
	v_cmp_class_f32_e32 vcc, v141, v221
	s_nop 1
	v_cndmask_b32_e32 v141, v154, v141, vcc
	v_div_scale_f32 v154, s[6:7], v141, v141, 1.0
	v_rcp_f32_e32 v156, v154
	s_nop 0
	v_fma_f32 v158, -v154, v156, 1.0
	v_fmac_f32_e32 v156, v158, v156
	v_div_scale_f32 v158, vcc, 1.0, v141, 1.0
	v_mul_f32_e32 v174, v158, v156
	v_fma_f32 v175, -v154, v174, v158
	v_fmac_f32_e32 v174, v175, v156
	v_fma_f32 v154, -v154, v174, v158
	v_div_fmas_f32 v154, v154, v156, v174
	v_lshl_add_u64 v[174:175], v[144:145], 2, s[18:19]
	v_mad_i64_i32 v[176:177], s[6:7], v157, s46, v[174:175]
	v_div_fixup_f32 v158, v154, v141, 1.0
	global_load_dword v208, v[176:177], off
	v_mad_i64_i32 v[176:177], s[6:7], v161, s46, v[174:175]
	global_load_dword v209, v[176:177], off
	v_mad_i64_i32 v[176:177], s[6:7], v163, s46, v[174:175]
	global_load_dword v210, v[176:177], off
	v_mad_i64_i32 v[176:177], s[6:7], v165, s46, v[174:175]
	global_load_dword v211, v[176:177], off
	v_mad_i64_i32 v[176:177], s[6:7], v166, s46, v[174:175]
	global_load_dword v212, v[176:177], off
	v_mad_i64_i32 v[176:177], s[6:7], v167, s46, v[174:175]
	global_load_dword v213, v[176:177], off
	v_mad_i64_i32 v[176:177], s[6:7], v169, s46, v[174:175]
	v_mad_i64_i32 v[174:175], s[6:7], v173, s46, v[174:175]
	global_load_dword v214, v[176:177], off
	global_load_dword v215, v[174:175], off
	s_waitcnt vmcnt(0)
	v_add_f32_e32 v141, 0, v208
	v_add_f32_e32 v141, v141, v209
	v_add_f32_e32 v141, v141, v210
	v_add_f32_e32 v141, v141, v211
	v_add_f32_e32 v141, v141, v212
	v_add_f32_e32 v141, v141, v213
	v_add_f32_e32 v141, v141, v214
	v_add_f32_e32 v141, v141, v215
	ds_bpermute_b32 v154, v160, v141
	s_waitcnt lgkmcnt(0)
	v_add_f32_e32 v141, v141, v154
	ds_bpermute_b32 v154, v159, v141
	s_waitcnt lgkmcnt(0)
; __device__ __forceinline__ void rows_rstd(const float* SS, const Unit& u, int wr, int fr, int fq, float (&rs)[2][4]) {
;     ...
;             for (int m = 0; m < 4; ++m) rs[ai][m] = RSTD[u.pm * BM + ai * HALF + wr * 64 + m * 16 + fr];
;     } else {
; #pragma unroll
;         for (int ai = 0; ai < 2; ++ai)
; #pragma unroll
;             for (int m = 0; m < 4; ++m) {
;                 const int row = u.pm * BM + ai * HALF + wr * 64 + m * 16 + fr; float s = 0.f;
; #pragma unroll
;                 for (int j = 0; j < 8; ++j) s += SS[(size_t)(fq * 8 + j) * MPAD + row];
;                 s += __shfl_xor(s, 16); s += __shfl_xor(s, 32);
;                 rs[ai][m] = 1.0f / sqrtf(s * (1.0f / 2048.0f) + RMS_EPS);
	v_add_f32_e32 v141, v141, v154
	v_fmamk_f32 v141, v141, 0x3a000000, v220
	v_cmp_gt_f32_e32 vcc, s43, v141
	v_mul_f32_e32 v154, 0x4f800000, v141
	s_nop 0
	v_cndmask_b32_e32 v141, v141, v154, vcc
	v_sqrt_f32_e32 v154, v141
	s_nop 0
	v_add_u32_e32 v156, -1, v154
	v_fma_f32 v174, -v156, v154, v141
	v_cmp_ge_f32_e64 s[6:7], 0, v174
	v_add_u32_e32 v174, 1, v154
	s_nop 0
	v_cndmask_b32_e64 v156, v154, v156, s[6:7]
	v_fma_f32 v154, -v174, v154, v141
	v_cmp_lt_f32_e64 s[6:7], 0, v154
	s_nop 1
	v_cndmask_b32_e64 v154, v156, v174, s[6:7]
	v_mul_f32_e32 v156, 0x37800000, v154
	v_cndmask_b32_e32 v154, v154, v156, vcc
	v_cmp_class_f32_e32 vcc, v141, v221
	s_nop 1
	v_cndmask_b32_e32 v141, v154, v141, vcc
	v_div_scale_f32 v154, s[6:7], v141, v141, 1.0
	v_rcp_f32_e32 v156, v154
	s_nop 0
	v_fma_f32 v174, -v154, v156, 1.0
	v_fmac_f32_e32 v156, v174, v156
	v_div_scale_f32 v174, vcc, 1.0, v141, 1.0
	v_mul_f32_e32 v175, v174, v156
	v_fma_f32 v176, -v154, v175, v174
	v_fmac_f32_e32 v175, v176, v156
	v_fma_f32 v154, -v154, v175, v174
	v_div_fmas_f32 v154, v154, v156, v175
	v_lshl_add_u64 v[174:175], v[142:143], 2, s[18:19]
	v_mad_i64_i32 v[176:177], s[6:7], v157, s46, v[174:175]
	v_div_fixup_f32 v156, v154, v141, 1.0
	global_load_dword v208, v[176:177], off
	v_mad_i64_i32 v[176:177], s[6:7], v161, s46, v[174:175]
	global_load_dword v209, v[176:177], off
	v_mad_i64_i32 v[176:177], s[6:7], v163, s46, v[174:175]
	global_load_dword v210, v[176:177], off
	v_mad_i64_i32 v[176:177], s[6:7], v165, s46, v[174:175]
	global_load_dword v211, v[176:177], off
	v_mad_i64_i32 v[176:177], s[6:7], v166, s46, v[174:175]
	global_load_dword v212, v[176:177], off
	v_mad_i64_i32 v[176:177], s[6:7], v167, s46, v[174:175]
	global_load_dword v213, v[176:177], off
	v_mad_i64_i32 v[176:177], s[6:7], v169, s46, v[174:175]
	v_mad_i64_i32 v[174:175], s[6:7], v173, s46, v[174:175]
	global_load_dword v214, v[176:177], off
	global_load_dword v215, v[174:175], off
	s_waitcnt vmcnt(0)
	v_add_f32_e32 v141, 0, v208
	v_add_f32_e32 v141, v141, v209
	v_add_f32_e32 v141, v141, v210
	v_add_f32_e32 v141, v141, v211
	v_add_f32_e32 v141, v141, v212
	v_add_f32_e32 v141, v141, v213
	v_add_f32_e32 v141, v141, v214
	v_add_f32_e32 v141, v141, v215
	ds_bpermute_b32 v154, v160, v141
	s_waitcnt lgkmcnt(0)
	v_add_f32_e32 v141, v141, v154
	ds_bpermute_b32 v154, v159, v141
	s_waitcnt lgkmcnt(0)
	v_add_f32_e32 v141, v141, v154
	v_fmamk_f32 v141, v141, 0x3a000000, v220
	v_cmp_gt_f32_e32 vcc, s43, v141
	v_mul_f32_e32 v154, 0x4f800000, v141
	s_nop 0
	v_cndmask_b32_e32 v141, v141, v154, vcc
	v_sqrt_f32_e32 v154, v141
	s_nop 0
	v_add_u32_e32 v174, -1, v154
	v_fma_f32 v175, -v174, v154, v141
	v_cmp_ge_f32_e64 s[6:7], 0, v175
	v_add_u32_e32 v175, 1, v154
	s_nop 0
	v_cndmask_b32_e64 v174, v154, v174, s[6:7]
	v_fma_f32 v154, -v175, v154, v141
	v_cmp_lt_f32_e64 s[6:7], 0, v154
	s_nop 1
	v_cndmask_b32_e64 v154, v174, v175, s[6:7]
	v_mul_f32_e32 v174, 0x37800000, v154
	v_cndmask_b32_e32 v154, v154, v174, vcc
	v_cmp_class_f32_e32 vcc, v141, v221
	s_nop 1
	v_cndmask_b32_e32 v141, v154, v141, vcc
	v_div_scale_f32 v154, s[6:7], v141, v141, 1.0
	v_rcp_f32_e32 v174, v154
	s_nop 0
	v_fma_f32 v175, -v154, v174, 1.0
	v_fmac_f32_e32 v174, v175, v174
	v_div_scale_f32 v175, vcc, 1.0, v141, 1.0
	v_mul_f32_e32 v176, v175, v174
	v_fma_f32 v177, -v154, v176, v175
	v_fmac_f32_e32 v176, v177, v174
	v_fma_f32 v154, -v154, v176, v175
	v_div_fmas_f32 v154, v154, v174, v176
	v_div_fixup_f32 v154, v154, v141, 1.0
	v_ashrrev_i32_e32 v141, 31, v140
	v_lshl_add_u64 v[174:175], v[140:141], 2, s[18:19]
	v_mad_i64_i32 v[176:177], s[6:7], v157, s46, v[174:175]
	global_load_dword v208, v[176:177], off
	v_mad_i64_i32 v[176:177], s[6:7], v161, s46, v[174:175]
	global_load_dword v209, v[176:177], off
	v_mad_i64_i32 v[176:177], s[6:7], v163, s46, v[174:175]
	global_load_dword v210, v[176:177], off
	v_mad_i64_i32 v[176:177], s[6:7], v165, s46, v[174:175]
	global_load_dword v211, v[176:177], off
	v_mad_i64_i32 v[176:177], s[6:7], v166, s46, v[174:175]
	v_mad_i64_i32 v[166:167], s[6:7], v167, s46, v[174:175]
	global_load_dword v212, v[176:177], off
	global_load_dword v213, v[166:167], off
	v_mad_i64_i32 v[166:167], s[6:7], v169, s46, v[174:175]
	global_load_dword v214, v[166:167], off
	v_mad_i64_i32 v[166:167], s[6:7], v173, s46, v[174:175]
	global_load_dword v215, v[166:167], off
	s_waitcnt vmcnt(0)
	v_add_f32_e32 v141, 0, v208
	v_add_f32_e32 v141, v141, v209
	v_add_f32_e32 v141, v141, v210
	v_add_f32_e32 v141, v141, v211
	v_add_f32_e32 v141, v141, v212
	v_add_f32_e32 v141, v141, v213
	v_add_f32_e32 v141, v141, v214
	v_add_f32_e32 v141, v141, v215
	ds_bpermute_b32 v160, v160, v141
	s_waitcnt lgkmcnt(0)
	v_add_f32_e32 v141, v141, v160
	ds_bpermute_b32 v159, v159, v141
	s_waitcnt lgkmcnt(0)
	v_add_f32_e32 v141, v141, v159
	v_fmamk_f32 v141, v141, 0x3a000000, v220
	v_cmp_gt_f32_e32 vcc, s43, v141
	v_mul_f32_e32 v159, 0x4f800000, v141
	s_nop 0
	v_cndmask_b32_e32 v141, v141, v159, vcc
	v_sqrt_f32_e32 v159, v141
	s_nop 0
	v_add_u32_e32 v160, -1, v159
	v_fma_f32 v161, -v160, v159, v141
	v_cmp_ge_f32_e64 s[6:7], 0, v161
	v_add_u32_e32 v161, 1, v159
	s_nop 0
	v_cndmask_b32_e64 v160, v159, v160, s[6:7]
	v_fma_f32 v159, -v161, v159, v141
	v_cmp_lt_f32_e64 s[6:7], 0, v159
	s_nop 1
	v_cndmask_b32_e64 v159, v160, v161, s[6:7]
	v_mul_f32_e32 v160, 0x37800000, v159
	v_cndmask_b32_e32 v159, v159, v160, vcc
	v_cmp_class_f32_e32 vcc, v141, v221
	s_nop 1
	v_cndmask_b32_e32 v141, v159, v141, vcc
	v_div_scale_f32 v159, s[6:7], v141, v141, 1.0
	v_rcp_f32_e32 v160, v159
	s_mov_b64 s[6:7], 0
	v_fma_f32 v161, -v159, v160, 1.0
	v_fmac_f32_e32 v160, v161, v160
	v_div_scale_f32 v161, vcc, 1.0, v141, 1.0
	v_mul_f32_e32 v163, v161, v160
	v_fma_f32 v165, -v159, v163, v161
	v_fmac_f32_e32 v163, v165, v160
	v_fma_f32 v159, -v159, v163, v161
	v_div_fmas_f32 v159, v159, v160, v163
	v_div_fixup_f32 v166, v159, v141, 1.0

; __device__ __forceinline__ void phase_gla_seq(KArgs a, LAS unsigned char* lds, int tid, int wave, int lane) {
;     ...
;             const int k8 = it & 7, sh = it >> 3, h = sh & 3, s = sh >> 2; const size_t row = MPROMPT + s; const int kk = k8 * 32 + (lane & 31);
;             float z = bg[h * 256 + kk];
; #pragma unroll
;             for (int r = 0; r < 16; ++r) z += G1[row * 16 + r] * wg2[(size_t)r * 1024 + h * 256 + kk];
.LBB0_898:
	s_ashr_i32 s29, s2, 5
	s_ashr_i32 s4, s2, 3
	s_add_i32 s16, s29, 0x2000
	s_and_b32 s5, s4, 3
	s_ashr_i32 s17, s16, 31
	s_lshl_b32 s30, s5, 8
	s_lshl_b64 s[18:19], s[16:17], 6
	v_or_b32_e32 v2, s30, v68
	s_add_u32 s18, s22, s18
	v_lshlrev_b32_e32 v2, 2, v2
	s_addc_u32 s19, s23, s19
	s_lshl_b32 s48, s5, 10
	global_load_dword v104, v2, s[6:7]
	v_lshl_add_u64 v[18:19], v[70:71], 0, s[48:49]
	global_load_dwordx4 v[108:111], v1, s[18:19] offset:16
	global_load_dwordx4 v[112:115], v1, s[18:19]
	global_load_dwordx4 v[116:119], v1, s[18:19] offset:48
	global_load_dwordx4 v[120:123], v1, s[18:19] offset:32
	global_load_dword v105, v[18:19], off
	s_mov_b32 s18, 0x8000
	v_mov_b32_e32 v83, v67
	v_add_co_u32_e32 v20, vcc, s38, v18
	s_nop 1
	v_addc_co_u32_e32 v21, vcc, 0, v19, vcc
	global_load_dword v106, v[20:21], off offset:-4096
	global_load_dword v107, v[20:21], off
	v_add_co_u32_e32 v10, vcc, s41, v18
	s_nop 1
	v_addc_co_u32_e32 v11, vcc, 0, v19, vcc
	global_load_dword v124, v[10:11], off offset:-4096
	global_load_dword v125, v[10:11], off
	v_add_co_u32_e32 v10, vcc, s42, v18
	s_nop 1
	v_addc_co_u32_e32 v11, vcc, 0, v19, vcc
	global_load_dword v126, v[10:11], off offset:-4096
	global_load_dword v127, v[10:11], off
	v_add_co_u32_e32 v10, vcc, s18, v18
	s_mov_b32 s18, 0xa000
	s_nop 0
	v_addc_co_u32_e32 v11, vcc, 0, v19, vcc
	global_load_dword v128, v[10:11], off offset:-4096
	v_add_co_u32_e32 v8, vcc, s18, v18
	s_nop 0
	s_nop 1
	v_addc_co_u32_e32 v9, vcc, 0, v19, vcc
	global_load_dword v135, v[10:11], off
	global_load_dword v136, v[8:9], off offset:-4096
	s_mov_b32 s18, 0xc000
	s_nop 0
	global_load_dword v145, v[8:9], off
	v_add_co_u32_e32 v8, vcc, s18, v18
	s_mov_b32 s18, 0xe000
	s_nop 0
	v_addc_co_u32_e32 v9, vcc, 0, v19, vcc
	global_load_dword v146, v[8:9], off offset:-4096
	s_nop 0
	global_load_dword v153, v[8:9], off
	v_add_co_u32_e32 v8, vcc, s18, v18
	s_mov_b32 s18, 0xf000
	s_nop 0
	v_addc_co_u32_e32 v9, vcc, 0, v19, vcc
	global_load_dword v154, v[8:9], off offset:-4096
	v_add_co_u32_e32 v6, vcc, s18, v18
	s_nop 0
	s_nop 1
	v_addc_co_u32_e32 v7, vcc, 0, v19, vcc
	global_load_dword v161, v[8:9], off
	global_load_dword v162, v[6:7], off
	s_lshl_b64 s[18:19], s[16:17], 10
	s_or_b32 s18, s18, s30
	s_lshl_b64 s[16:17], s[16:17], 12
	s_add_u32 s16, s20, s16
	s_addc_u32 s17, s21, s17
	s_nop 0
	s_waitcnt vmcnt(0)
; __device__ __forceinline__ void phase_gla_seq(KArgs a, LAS unsigned char* lds, int tid, int wave, int lane) {
;     ...
;             float z = bg[h * 256 + kk];
; #pragma unroll
;             for (int r = 0; r < 16; ++r) z += G1[row * 16 + r] * wg2[(size_t)r * 1024 + h * 256 + kk];
;             const float eg = __expf((fminf(z, 0.f) - log1pf(__expf(-fabsf(z)))) * 0.0625f);
;             const float qe = bf2f(Q[row * 1024 + h * 256 + kk]) * eg, kv = bf2f(Kf[row * 1024 + h * 256 + kk]);
;             const u32x2 va = *(const u32x2*)(V + row * DM + h * 512 + lane * 4), vb = *(const u32x2*)(V + row * DM + h * 512 + 256 + lane * 4);
;             const f32x4 v0 = (f32x4){bflo(va.x), bfhi(va.x), bflo(va.y), bfhi(va.y)}, v1 = (f32x4){bflo(vb.x), bfhi(vb.x), bflo(vb.y), bfhi(vb.y)};
	v_fmac_f32_e32 v104, v112, v105
	v_fmac_f32_e32 v104, v113, v106
	v_fmac_f32_e32 v104, v114, v107
	v_fmac_f32_e32 v104, v115, v124
	v_fmac_f32_e32 v104, v108, v125
	v_fmac_f32_e32 v104, v109, v126
	v_mov_b32_e32 v130, v127
	v_mov_b32_e32 v131, v128
	v_pk_mul_f32 v[132:133], v[110:111], v[130:131]
	v_add_f32_e32 v129, v104, v132
	v_add_f32_e32 v134, v129, v133
	v_mov_b32_e32 v140, v135
	v_mov_b32_e32 v141, v136
	v_pk_mul_f32 v[142:143], v[120:121], v[140:141]
	v_add_f32_e32 v137, v134, v142
	v_add_f32_e32 v144, v137, v143
	v_mov_b32_e32 v148, v145
	v_mov_b32_e32 v149, v146
	v_pk_mul_f32 v[150:151], v[122:123], v[148:149]
	v_add_f32_e32 v147, v144, v150
	v_add_f32_e32 v152, v147, v151
	v_mov_b32_e32 v156, v153
	v_mov_b32_e32 v157, v154
	v_pk_mul_f32 v[158:159], v[116:117], v[156:157]
	v_add_f32_e32 v155, v152, v158
	v_add_f32_e32 v160, v155, v159
	v_mov_b32_e32 v166, v161
	v_mov_b32_e32 v167, v162
	v_pk_mul_f32 v[168:169], v[118:119], v[166:167]
	v_add_f32_e32 v170, v160, v168
	v_add_f32_e32 v171, v170, v169
	v_mov_b32_e32 v2, v170
	v_mov_b32_e32 v3, v171
	v_mov_b32_e32 v4, v118
	v_mov_b32_e32 v5, v119
	v_mov_b32_e32 v10, v160
	v_mov_b32_e32 v12, v134
	v_mov_b32_e32 v13, v115
	v_mov_b32_e32 v14, v120
	v_mov_b32_e32 v15, v121
	v_mov_b32_e32 v16, v122
	v_mov_b32_e32 v17, v123
	v_mov_b32_e32 v22, v104
	v_min_f32_e32 v6, 0, v3
	v_mul_f32_e64 v3, |v3|, s60
	v_exp_f32_e32 v3, v3
	v_mov_b32_e32 v2, 0
	v_add_f32_e32 v7, 1.0, v3
	v_add_f32_e32 v4, -1.0, v7
	v_sub_f32_e32 v5, v4, v7
	v_add_f32_e32 v5, 1.0, v5
	v_sub_f32_e32 v4, v3, v4
	v_add_f32_e32 v8, v4, v5
	v_frexp_mant_f32_e32 v4, v7
	v_cmp_gt_f32_e32 vcc, s3, v4
	v_cvt_f64_f32_e32 v[4:5], v7
	v_frexp_exp_i32_f64_e32 v4, v[4:5]
	v_subbrev_co_u32_e32 v4, vcc, 0, v4, vcc
	v_sub_u32_e32 v5, 0, v4
	v_ldexp_f32 v7, v7, v5
	v_ldexp_f32 v5, v8, v5
	v_add_f32_e32 v8, -1.0, v7
	v_add_f32_e32 v9, 1.0, v8
	v_sub_f32_e32 v9, v7, v9
	v_add_f32_e32 v9, v5, v9
	v_add_f32_e32 v10, v8, v9
	v_sub_f32_e32 v8, v10, v8
	v_sub_f32_e32 v8, v9, v8
	v_add_f32_e32 v9, 1.0, v7
	v_add_f32_e32 v11, -1.0, v9
	v_sub_f32_e32 v7, v7, v11
	v_add_f32_e32 v5, v5, v7
	v_add_f32_e32 v7, v9, v5
	v_sub_f32_e32 v9, v7, v9
	v_sub_f32_e32 v5, v5, v9
	v_rcp_f32_e32 v9, v7
	v_cvt_f32_i32_e32 v4, v4
	v_cmp_neq_f32_e32 vcc, s34, v3
	v_mul_f32_e32 v11, v10, v9
	v_mul_f32_e32 v12, v7, v11
	v_fma_f32 v13, v11, v7, -v12
	v_fmac_f32_e32 v13, v11, v5
	v_add_f32_e32 v14, v12, v13
	v_sub_f32_e32 v15, v10, v14
	v_sub_f32_e32 v10, v10, v15
	v_sub_f32_e32 v12, v14, v12
	v_sub_f32_e32 v10, v10, v14
	v_add_f32_e32 v8, v8, v10
	v_sub_f32_e32 v10, v12, v13
	v_add_f32_e32 v8, v10, v8
	v_add_f32_e32 v10, v15, v8
	v_mul_f32_e32 v12, v9, v10
	v_mul_f32_e32 v13, v7, v12
	v_fma_f32 v7, v12, v7, -v13
	v_fmac_f32_e32 v7, v12, v5
	v_sub_f32_e32 v5, v15, v10
	v_add_f32_e32 v5, v8, v5
	v_add_f32_e32 v8, v13, v7
	v_sub_f32_e32 v14, v10, v8
	v_sub_f32_e32 v10, v10, v14
	v_sub_f32_e32 v13, v8, v13
	v_sub_f32_e32 v8, v10, v8
	v_add_f32_e32 v5, v5, v8
	v_sub_f32_e32 v7, v13, v7
	v_add_f32_e32 v5, v7, v5
	v_add_f32_e32 v7, v11, v12
	v_add_f32_e32 v5, v14, v5
	v_sub_f32_e32 v8, v7, v11
	v_mul_f32_e32 v5, v9, v5
	v_sub_f32_e32 v8, v12, v8
	v_add_f32_e32 v5, v8, v5
	v_mul_f32_e32 v11, 0x3f317218, v4
	v_add_f32_e32 v8, v7, v5
	v_fma_f32 v12, v4, s80, -v11
	v_mul_f32_e32 v9, v8, v8
	v_fmac_f32_e32 v12, 0xb102e308, v4
	v_sub_f32_e32 v4, v8, v7
	v_fmamk_f32 v10, v9, 0x3e9b6dac, v226
	v_sub_f32_e32 v4, v5, v4
	v_add_f32_e32 v5, v11, v12
	v_fmaak_f32 v10, v9, v10, 0x3f2aaada
	v_sub_f32_e32 v7, v5, v11
	v_ldexp_f32 v11, v8, 1
	v_mul_f32_e32 v8, v8, v9
	v_mul_f32_e32 v8, v8, v10
	v_add_f32_e32 v9, v11, v8
	v_sub_f32_e32 v10, v9, v11
	v_ldexp_f32 v4, v4, 1
	v_sub_f32_e32 v8, v8, v10
	v_add_f32_e32 v4, v4, v8
	v_add_f32_e32 v8, v9, v4
	v_sub_f32_e32 v9, v8, v9
	v_sub_f32_e32 v4, v4, v9
	v_add_f32_e32 v9, v5, v8
	v_sub_f32_e32 v10, v9, v5
	v_sub_f32_e32 v11, v9, v10
	v_sub_f32_e32 v7, v12, v7
	v_sub_f32_e32 v5, v5, v11
	v_sub_f32_e32 v8, v8, v10
	v_add_f32_e32 v5, v8, v5
	v_add_f32_e32 v8, v7, v4
	v_sub_f32_e32 v10, v8, v7
	v_sub_f32_e32 v11, v8, v10
	v_sub_f32_e32 v7, v7, v11
	v_sub_f32_e32 v4, v4, v10
	v_add_f32_e32 v5, v8, v5
	v_add_f32_e32 v4, v4, v7
	v_add_f32_e32 v7, v9, v5
	v_sub_f32_e32 v8, v7, v9
	v_sub_f32_e32 v5, v5, v8
	v_add_f32_e32 v4, v4, v5
	v_add_f32_e32 v4, v7, v4
	v_cndmask_b32_e32 v4, v228, v4, vcc
	v_cmp_ngt_f32_e32 vcc, -1.0, v3
	v_mov_b32_e32 v5, s19
	s_mov_b32 s19, -8
	v_cndmask_b32_e32 v4, v229, v4, vcc
	v_cmp_neq_f32_e32 vcc, -1.0, v3
	v_mov_b32_e32 v8, v2
	v_mov_b32_e32 v9, v2
	v_cndmask_b32_e32 v4, v230, v4, vcc
	v_cmp_lt_f32_e64 vcc, |v3|, s44
	s_nop 1
	v_cndmask_b32_e32 v3, v4, v3, vcc
	v_sub_f32_e32 v3, v6, v3
	v_or_b32_e32 v4, s18, v68
	v_mul_f32_e32 v3, 0x3d800000, v3
	v_lshlrev_b64 v[4:5], 1, v[4:5]
	v_mul_f32_e32 v3, 0x3fb8aa3b, v3
	v_lshl_add_u64 v[6:7], s[10:11], 0, v[4:5]
	v_exp_f32_e32 v80, v3
	global_load_ushort v3, v[6:7], off
	s_lshl_b32 s18, s5, 9
	s_add_u32 s16, s16, s48
	v_lshl_add_u64 v[4:5], s[12:13], 0, v[4:5]
	s_addc_u32 s17, s17, 0
	s_ashr_i32 s5, s4, 31
	global_load_ushort v165, v[4:5], off
	s_nop 0
	global_load_dwordx2 v[4:5], v69, s[16:17]
	global_load_dwordx2 v[6:7], v69, s[16:17] offset:512
	s_waitcnt vmcnt(3)
	v_lshlrev_b32_e32 v3, 16, v3
	v_mul_f32_e32 v81, v80, v3
	s_lshl_b64 s[16:17], s[4:5], 19
	s_add_u32 s4, s8, s16
	s_addc_u32 s5, s9, s17
	s_add_u32 s16, s14, s16
	s_addc_u32 s17, s15, s17
	s_waitcnt vmcnt(2)
	v_lshlrev_b32_e32 v82, 16, v165
	s_waitcnt vmcnt(1)
	v_lshlrev_b32_e32 v72, 16, v4
	v_and_b32_e32 v73, 0xffff0000, v4
	v_lshlrev_b32_e32 v74, 16, v5
	v_and_b32_e32 v75, 0xffff0000, v5
	s_waitcnt vmcnt(0)
	v_lshlrev_b32_e32 v76, 16, v6
	v_and_b32_e32 v77, 0xffff0000, v6
	v_lshlrev_b32_e32 v78, 16, v7
	v_and_b32_e32 v79, 0xffff0000, v7
	v_mov_b32_e32 v3, v2
	v_mov_b32_e32 v4, v2
	v_mov_b32_e32 v5, v2
	v_mov_b32_e32 v6, v2
	v_mov_b32_e32 v7, v2

; __device__ __forceinline__ void rows_rstd(const float* SS, const Unit& u, int wr, int fr, int fq, float (&rs)[2][4]) {
;     if (u.pm < 32) { const float* RSTD = (const float*)((const char*)SS + SS_TO_RSTD);
; #pragma unroll
;         for (int ai = 0; ai < 2; ++ai)
; #pragma unroll
;             for (int m = 0; m < 4; ++m) rs[ai][m] = RSTD[u.pm * BM + ai * HALF + wr * 64 + m * 16 + fr];
;     } else {
; #pragma unroll
;         for (int ai = 0; ai < 2; ++ai)
; #pragma unroll
;             for (int m = 0; m < 4; ++m) {
;                 const int row = u.pm * BM + ai * HALF + wr * 64 + m * 16 + fr; float s = 0.f;
; #pragma unroll
;                 for (int j = 0; j < 8; ++j) s += SS[(size_t)(fq * 8 + j) * MPAD + row];
;                 s += __shfl_xor(s, 16); s += __shfl_xor(s, 32);
;                 rs[ai][m] = 1.0f / sqrtf(s * (1.0f / 2048.0f) + RMS_EPS);
;             }
;     }
; }
.LBB0_1235:
	s_lshl_b32 s6, s27, 8
	v_mov_b32_e32 v140, v189
	v_mov_b32_e32 v141, v194
	s_add_i32 s6, s6, s84
	s_cmp_lt_i32 s27, 32
	v_add_u32_e32 v168, s6, v141
	v_lshlrev_b32_e32 v170, 3, v140
	v_add_u32_e32 v154, 16, v168
	v_add_u32_e32 v150, 32, v168
	v_add_u32_e32 v148, 48, v168
	v_add_u32_e32 v146, 0x80, v168
	v_add_u32_e32 v144, 0x90, v168
	v_add_u32_e32 v142, 0xa0, v168
	s_mov_b64 s[6:7], -1
	v_ashrrev_i32_e32 v169, 31, v168
	v_ashrrev_i32_e32 v171, 31, v170
	v_ashrrev_i32_e32 v155, 31, v154
	v_ashrrev_i32_e32 v151, 31, v150
	v_ashrrev_i32_e32 v149, 31, v148
	v_ashrrev_i32_e32 v147, 31, v146
	v_ashrrev_i32_e32 v145, 31, v144
	v_ashrrev_i32_e32 v143, 31, v142
	v_add_u32_e32 v140, 0xb0, v168
	s_cbranch_scc1 .LBB0_1237
	v_and_b32_e32 v152, 64, v219
	v_xor_b32_e32 v141, 16, v219
	v_add_u32_e32 v152, 64, v152
	v_cmp_lt_i32_e32 vcc, v141, v152
	v_lshl_add_u64 v[174:175], v[168:169], 2, s[14:15]
	v_mad_i64_i32 v[158:159], s[6:7], v170, s46, v[174:175]
	v_cndmask_b32_e32 v141, v219, v141, vcc
	v_lshlrev_b32_e32 v157, 2, v141
	v_xor_b32_e32 v141, 32, v219
	v_cmp_lt_i32_e32 vcc, v141, v152
	s_nop 1
	v_cndmask_b32_e32 v141, v219, v141, vcc
	v_lshlrev_b32_e32 v153, 2, v141
	global_load_dword v208, v[158:159], off
	v_or_b32_e32 v158, 1, v170
	v_mad_i64_i32 v[160:161], s[6:7], v158, s46, v[174:175]
	global_load_dword v209, v[160:161], off
	v_or_b32_e32 v159, 2, v170
	v_mad_i64_i32 v[160:161], s[6:7], v159, s46, v[174:175]
	global_load_dword v210, v[160:161], off
	v_or_b32_e32 v161, 3, v170
	v_mad_i64_i32 v[162:163], s[6:7], v161, s46, v[174:175]
	global_load_dword v211, v[162:163], off
	v_or_b32_e32 v163, 4, v170
	v_mad_i64_i32 v[164:165], s[6:7], v163, s46, v[174:175]
	global_load_dword v212, v[164:165], off
	v_or_b32_e32 v165, 5, v170
	v_mad_i64_i32 v[166:167], s[6:7], v165, s46, v[174:175]
	global_load_dword v213, v[166:167], off
	v_or_b32_e32 v167, 6, v170
	v_mad_i64_i32 v[172:173], s[6:7], v167, s46, v[174:175]
	global_load_dword v214, v[172:173], off
	v_or_b32_e32 v173, 7, v170
	v_mad_i64_i32 v[174:175], s[6:7], v173, s46, v[174:175]
	global_load_dword v215, v[174:175], off
	v_lshl_add_u64 v[174:175], v[154:155], 2, s[14:15]
	s_waitcnt vmcnt(0)
	v_add_f32_e32 v141, 0, v208
	v_add_f32_e32 v141, v141, v209
	v_add_f32_e32 v141, v141, v210
	v_add_f32_e32 v141, v141, v211
	v_add_f32_e32 v141, v141, v212
	v_add_f32_e32 v141, v141, v213
	v_add_f32_e32 v141, v141, v214
	v_add_f32_e32 v141, v141, v215
	ds_bpermute_b32 v152, v157, v141
	s_waitcnt lgkmcnt(0)
	v_add_f32_e32 v141, v141, v152
	ds_bpermute_b32 v152, v153, v141
	s_waitcnt lgkmcnt(0)
	v_add_f32_e32 v141, v141, v152
	v_fmamk_f32 v141, v141, 0x3a000000, v220
	v_cmp_gt_f32_e32 vcc, s43, v141
	v_mul_f32_e32 v152, 0x4f800000, v141
	s_nop 0
	v_cndmask_b32_e32 v141, v141, v152, vcc
	v_sqrt_f32_e32 v152, v141
	s_nop 0
	v_add_u32_e32 v156, -1, v152
	v_fma_f32 v160, -v156, v152, v141
	v_cmp_ge_f32_e64 s[6:7], 0, v160
	v_add_u32_e32 v160, 1, v152
	s_nop 0
	v_cndmask_b32_e64 v156, v152, v156, s[6:7]
	v_fma_f32 v152, -v160, v152, v141
	v_cmp_lt_f32_e64 s[6:7], 0, v152
	s_nop 1
	v_cndmask_b32_e64 v152, v156, v160, s[6:7]
	v_mul_f32_e32 v156, 0x37800000, v152
	v_cndmask_b32_e32 v152, v152, v156, vcc
	v_cmp_class_f32_e32 vcc, v141, v221
	v_mad_i64_i32 v[176:177], s[6:7], v170, s46, v[174:175]
	s_nop 0
	v_cndmask_b32_e32 v141, v152, v141, vcc
	v_div_scale_f32 v152, s[6:7], v141, v141, 1.0
	v_rcp_f32_e32 v156, v152
	s_nop 0
	v_fma_f32 v160, -v152, v156, 1.0
	v_fmac_f32_e32 v156, v160, v156
	v_div_scale_f32 v160, vcc, 1.0, v141, 1.0
	v_mul_f32_e32 v162, v160, v156
	v_fma_f32 v164, -v152, v162, v160
	v_fmac_f32_e32 v162, v164, v156
	v_fma_f32 v152, -v152, v162, v160
	v_div_fmas_f32 v152, v152, v156, v162
	v_div_fixup_f32 v172, v152, v141, 1.0
	global_load_dword v208, v[176:177], off
	v_mad_i64_i32 v[176:177], s[6:7], v158, s46, v[174:175]
	global_load_dword v209, v[176:177], off
	v_mad_i64_i32 v[176:177], s[6:7], v159, s46, v[174:175]
	global_load_dword v210, v[176:177], off
	v_mad_i64_i32 v[176:177], s[6:7], v161, s46, v[174:175]
	global_load_dword v211, v[176:177], off
	v_mad_i64_i32 v[176:177], s[6:7], v163, s46, v[174:175]
	global_load_dword v212, v[176:177], off
	v_mad_i64_i32 v[176:177], s[6:7], v165, s46, v[174:175]
	global_load_dword v213, v[176:177], off
	v_mad_i64_i32 v[176:177], s[6:7], v167, s46, v[174:175]
	v_mad_i64_i32 v[174:175], s[6:7], v173, s46, v[174:175]
	global_load_dword v214, v[176:177], off
	global_load_dword v215, v[174:175], off
	v_lshl_add_u64 v[174:175], v[150:151], 2, s[14:15]
	s_waitcnt vmcnt(0)
	v_add_f32_e32 v141, 0, v208
	v_add_f32_e32 v141, v141, v209
	v_add_f32_e32 v141, v141, v210
	v_add_f32_e32 v141, v141, v211
	v_add_f32_e32 v141, v141, v212
	v_add_f32_e32 v141, v141, v213
	v_add_f32_e32 v141, v141, v214
	v_add_f32_e32 v141, v141, v215
	ds_bpermute_b32 v152, v157, v141
	s_waitcnt lgkmcnt(0)
	v_add_f32_e32 v141, v141, v152
	ds_bpermute_b32 v152, v153, v141
	s_waitcnt lgkmcnt(0)
; __device__ __forceinline__ void rows_rstd(const float* SS, const Unit& u, int wr, int fr, int fq, float (&rs)[2][4]) {
;     ...
;             for (int m = 0; m < 4; ++m) rs[ai][m] = RSTD[u.pm * BM + ai * HALF + wr * 64 + m * 16 + fr];
;     } else {
; #pragma unroll
;         for (int ai = 0; ai < 2; ++ai)
; #pragma unroll
;             for (int m = 0; m < 4; ++m) {
;                 const int row = u.pm * BM + ai * HALF + wr * 64 + m * 16 + fr; float s = 0.f;
; #pragma unroll
;                 for (int j = 0; j < 8; ++j) s += SS[(size_t)(fq * 8 + j) * MPAD + row];
;                 s += __shfl_xor(s, 16); s += __shfl_xor(s, 32);
;                 rs[ai][m] = 1.0f / sqrtf(s * (1.0f / 2048.0f) + RMS_EPS);
	v_add_f32_e32 v141, v141, v152
	v_fmamk_f32 v141, v141, 0x3a000000, v220
	v_cmp_gt_f32_e32 vcc, s43, v141
	v_mul_f32_e32 v152, 0x4f800000, v141
	s_nop 0
	v_cndmask_b32_e32 v141, v141, v152, vcc
	v_sqrt_f32_e32 v152, v141
	s_nop 0
	v_add_u32_e32 v156, -1, v152
	v_fma_f32 v160, -v156, v152, v141
	v_cmp_ge_f32_e64 s[6:7], 0, v160
	v_add_u32_e32 v160, 1, v152
	s_nop 0
	v_cndmask_b32_e64 v156, v152, v156, s[6:7]
	v_fma_f32 v152, -v160, v152, v141
	v_cmp_lt_f32_e64 s[6:7], 0, v152
	s_nop 1
	v_cndmask_b32_e64 v152, v156, v160, s[6:7]
	v_mul_f32_e32 v156, 0x37800000, v152
	v_cndmask_b32_e32 v152, v152, v156, vcc
	v_cmp_class_f32_e32 vcc, v141, v221
	v_mad_i64_i32 v[176:177], s[6:7], v170, s46, v[174:175]
	s_nop 0
	v_cndmask_b32_e32 v141, v152, v141, vcc
	v_div_scale_f32 v152, s[6:7], v141, v141, 1.0
	v_rcp_f32_e32 v156, v152
	s_nop 0
	v_fma_f32 v160, -v152, v156, 1.0
	v_fmac_f32_e32 v156, v160, v156
	v_div_scale_f32 v160, vcc, 1.0, v141, 1.0
	v_mul_f32_e32 v162, v160, v156
	v_fma_f32 v164, -v152, v162, v160
	v_fmac_f32_e32 v162, v164, v156
	v_fma_f32 v152, -v152, v162, v160
	v_div_fmas_f32 v152, v152, v156, v162
	v_div_fixup_f32 v166, v152, v141, 1.0
	global_load_dword v208, v[176:177], off
	v_mad_i64_i32 v[176:177], s[6:7], v158, s46, v[174:175]
	global_load_dword v209, v[176:177], off
	v_mad_i64_i32 v[176:177], s[6:7], v159, s46, v[174:175]
	global_load_dword v210, v[176:177], off
	v_mad_i64_i32 v[176:177], s[6:7], v161, s46, v[174:175]
	global_load_dword v211, v[176:177], off
	v_mad_i64_i32 v[176:177], s[6:7], v163, s46, v[174:175]
	global_load_dword v212, v[176:177], off
	v_mad_i64_i32 v[176:177], s[6:7], v165, s46, v[174:175]
	global_load_dword v213, v[176:177], off
	v_mad_i64_i32 v[176:177], s[6:7], v167, s46, v[174:175]
	v_mad_i64_i32 v[174:175], s[6:7], v173, s46, v[174:175]
	global_load_dword v214, v[176:177], off
	global_load_dword v215, v[174:175], off
	v_lshl_add_u64 v[174:175], v[148:149], 2, s[14:15]
	s_waitcnt vmcnt(0)
	v_add_f32_e32 v141, 0, v208
	v_add_f32_e32 v141, v141, v209
	v_add_f32_e32 v141, v141, v210
	v_add_f32_e32 v141, v141, v211
	v_add_f32_e32 v141, v141, v212
	v_add_f32_e32 v141, v141, v213
	v_add_f32_e32 v141, v141, v214
	v_add_f32_e32 v141, v141, v215
	ds_bpermute_b32 v152, v157, v141
	s_waitcnt lgkmcnt(0)
	v_add_f32_e32 v141, v141, v152
	ds_bpermute_b32 v152, v153, v141
	s_waitcnt lgkmcnt(0)
	v_add_f32_e32 v141, v141, v152
	v_fmamk_f32 v141, v141, 0x3a000000, v220
	v_cmp_gt_f32_e32 vcc, s43, v141
	v_mul_f32_e32 v152, 0x4f800000, v141
	s_nop 0
	v_cndmask_b32_e32 v141, v141, v152, vcc
	v_sqrt_f32_e32 v152, v141
	s_nop 0
	v_add_u32_e32 v156, -1, v152
	v_fma_f32 v160, -v156, v152, v141
	v_cmp_ge_f32_e64 s[6:7], 0, v160
	v_add_u32_e32 v160, 1, v152
	s_nop 0
	v_cndmask_b32_e64 v156, v152, v156, s[6:7]
	v_fma_f32 v152, -v160, v152, v141
	v_cmp_lt_f32_e64 s[6:7], 0, v152
	s_nop 1
	v_cndmask_b32_e64 v152, v156, v160, s[6:7]
	v_mul_f32_e32 v156, 0x37800000, v152
	v_cndmask_b32_e32 v152, v152, v156, vcc
	v_cmp_class_f32_e32 vcc, v141, v221
	v_mad_i64_i32 v[176:177], s[6:7], v170, s46, v[174:175]
	s_nop 0
	v_cndmask_b32_e32 v141, v152, v141, vcc
	v_div_scale_f32 v152, s[6:7], v141, v141, 1.0
	v_rcp_f32_e32 v156, v152
	s_nop 0
	v_fma_f32 v160, -v152, v156, 1.0
	v_fmac_f32_e32 v156, v160, v156
	v_div_scale_f32 v160, vcc, 1.0, v141, 1.0
	v_mul_f32_e32 v162, v160, v156
	v_fma_f32 v164, -v152, v162, v160
	v_fmac_f32_e32 v162, v164, v156
	v_fma_f32 v152, -v152, v162, v160
	v_div_fmas_f32 v152, v152, v156, v162
	v_div_fixup_f32 v164, v152, v141, 1.0
	global_load_dword v208, v[176:177], off
	v_mad_i64_i32 v[176:177], s[6:7], v158, s46, v[174:175]
	global_load_dword v209, v[176:177], off
	v_mad_i64_i32 v[176:177], s[6:7], v159, s46, v[174:175]
	global_load_dword v210, v[176:177], off
	v_mad_i64_i32 v[176:177], s[6:7], v161, s46, v[174:175]
	global_load_dword v211, v[176:177], off
	v_mad_i64_i32 v[176:177], s[6:7], v163, s46, v[174:175]
	global_load_dword v212, v[176:177], off
	v_mad_i64_i32 v[176:177], s[6:7], v165, s46, v[174:175]
	global_load_dword v213, v[176:177], off
	v_mad_i64_i32 v[176:177], s[6:7], v167, s46, v[174:175]
	v_mad_i64_i32 v[174:175], s[6:7], v173, s46, v[174:175]
	global_load_dword v214, v[176:177], off
	global_load_dword v215, v[174:175], off
	s_waitcnt vmcnt(0)
	v_add_f32_e32 v141, 0, v208
	v_add_f32_e32 v141, v141, v209
	v_add_f32_e32 v141, v141, v210
	v_add_f32_e32 v141, v141, v211
	v_add_f32_e32 v141, v141, v212
	v_add_f32_e32 v141, v141, v213
	v_add_f32_e32 v141, v141, v214
	v_add_f32_e32 v141, v141, v215
	ds_bpermute_b32 v152, v157, v141
	s_waitcnt lgkmcnt(0)
	v_add_f32_e32 v141, v141, v152
	ds_bpermute_b32 v152, v153, v141
	s_waitcnt lgkmcnt(0)
; __device__ __forceinline__ void rows_rstd(const float* SS, const Unit& u, int wr, int fr, int fq, float (&rs)[2][4]) {
;     ...
;             for (int m = 0; m < 4; ++m) rs[ai][m] = RSTD[u.pm * BM + ai * HALF + wr * 64 + m * 16 + fr];
;     } else {
; #pragma unroll
;         for (int ai = 0; ai < 2; ++ai)
; #pragma unroll
;             for (int m = 0; m < 4; ++m) {
;                 const int row = u.pm * BM + ai * HALF + wr * 64 + m * 16 + fr; float s = 0.f;
; #pragma unroll
;                 for (int j = 0; j < 8; ++j) s += SS[(size_t)(fq * 8 + j) * MPAD + row];
;                 s += __shfl_xor(s, 16); s += __shfl_xor(s, 32);
;                 rs[ai][m] = 1.0f / sqrtf(s * (1.0f / 2048.0f) + RMS_EPS);
	v_add_f32_e32 v141, v141, v152
	v_fmamk_f32 v141, v141, 0x3a000000, v220
	v_cmp_gt_f32_e32 vcc, s43, v141
	v_mul_f32_e32 v152, 0x4f800000, v141
	s_nop 0
	v_cndmask_b32_e32 v141, v141, v152, vcc
	v_sqrt_f32_e32 v152, v141
	s_nop 0
	v_add_u32_e32 v156, -1, v152
	v_fma_f32 v160, -v156, v152, v141
	v_cmp_ge_f32_e64 s[6:7], 0, v160
	v_add_u32_e32 v160, 1, v152
	s_nop 0
	v_cndmask_b32_e64 v156, v152, v156, s[6:7]
	v_fma_f32 v152, -v160, v152, v141
	v_cmp_lt_f32_e64 s[6:7], 0, v152
	s_nop 1
	v_cndmask_b32_e64 v152, v156, v160, s[6:7]
	v_mul_f32_e32 v156, 0x37800000, v152
	v_cndmask_b32_e32 v152, v152, v156, vcc
	v_cmp_class_f32_e32 vcc, v141, v221
	s_nop 1
	v_cndmask_b32_e32 v141, v152, v141, vcc
	v_div_scale_f32 v152, s[6:7], v141, v141, 1.0
	v_rcp_f32_e32 v156, v152
	s_nop 0
	v_fma_f32 v160, -v152, v156, 1.0
	v_fmac_f32_e32 v156, v160, v156
	v_div_scale_f32 v160, vcc, 1.0, v141, 1.0
	v_mul_f32_e32 v162, v160, v156
	v_fma_f32 v174, -v152, v162, v160
	v_fmac_f32_e32 v162, v174, v156
	v_fma_f32 v152, -v152, v162, v160
	v_lshl_add_u64 v[174:175], v[146:147], 2, s[14:15]
	v_div_fmas_f32 v152, v152, v156, v162
	v_mad_i64_i32 v[176:177], s[6:7], v170, s46, v[174:175]
	v_div_fixup_f32 v162, v152, v141, 1.0
	global_load_dword v208, v[176:177], off
	v_mad_i64_i32 v[176:177], s[6:7], v158, s46, v[174:175]
	global_load_dword v209, v[176:177], off
	v_mad_i64_i32 v[176:177], s[6:7], v159, s46, v[174:175]
	global_load_dword v210, v[176:177], off
	v_mad_i64_i32 v[176:177], s[6:7], v161, s46, v[174:175]
	global_load_dword v211, v[176:177], off
	v_mad_i64_i32 v[176:177], s[6:7], v163, s46, v[174:175]
	global_load_dword v212, v[176:177], off
	v_mad_i64_i32 v[176:177], s[6:7], v165, s46, v[174:175]
	global_load_dword v213, v[176:177], off
	v_mad_i64_i32 v[176:177], s[6:7], v167, s46, v[174:175]
	v_mad_i64_i32 v[174:175], s[6:7], v173, s46, v[174:175]
	global_load_dword v214, v[176:177], off
	global_load_dword v215, v[174:175], off
	s_waitcnt vmcnt(0)
	v_add_f32_e32 v141, 0, v208
	v_add_f32_e32 v141, v141, v209
	v_add_f32_e32 v141, v141, v210
	v_add_f32_e32 v141, v141, v211
	v_add_f32_e32 v141, v141, v212
	v_add_f32_e32 v141, v141, v213
	v_add_f32_e32 v141, v141, v214
	v_add_f32_e32 v141, v141, v215
	ds_bpermute_b32 v152, v157, v141
	s_waitcnt lgkmcnt(0)
	v_add_f32_e32 v141, v141, v152
	ds_bpermute_b32 v152, v153, v141
	s_waitcnt lgkmcnt(0)
	v_add_f32_e32 v141, v141, v152
	v_fmamk_f32 v141, v141, 0x3a000000, v220
	v_cmp_gt_f32_e32 vcc, s43, v141
	v_mul_f32_e32 v152, 0x4f800000, v141
	s_nop 0
	v_cndmask_b32_e32 v141, v141, v152, vcc
	v_sqrt_f32_e32 v152, v141
	s_nop 0
	v_add_u32_e32 v156, -1, v152
	v_fma_f32 v160, -v156, v152, v141
	v_cmp_ge_f32_e64 s[6:7], 0, v160
	v_add_u32_e32 v160, 1, v152
	s_nop 0
	v_cndmask_b32_e64 v156, v152, v156, s[6:7]
	v_fma_f32 v152, -v160, v152, v141
	v_cmp_lt_f32_e64 s[6:7], 0, v152
	s_nop 1
	v_cndmask_b32_e64 v152, v156, v160, s[6:7]
	v_mul_f32_e32 v156, 0x37800000, v152
	v_cndmask_b32_e32 v152, v152, v156, vcc
	v_cmp_class_f32_e32 vcc, v141, v221
	s_nop 1
	v_cndmask_b32_e32 v141, v152, v141, vcc
	v_div_scale_f32 v152, s[6:7], v141, v141, 1.0
	v_rcp_f32_e32 v156, v152
	s_nop 0
	v_fma_f32 v160, -v152, v156, 1.0
	v_fmac_f32_e32 v156, v160, v156
	v_div_scale_f32 v160, vcc, 1.0, v141, 1.0
	v_mul_f32_e32 v174, v160, v156
	v_fma_f32 v175, -v152, v174, v160
	v_fmac_f32_e32 v174, v175, v156
	v_fma_f32 v152, -v152, v174, v160
	v_div_fmas_f32 v152, v152, v156, v174
	v_lshl_add_u64 v[174:175], v[144:145], 2, s[14:15]
	v_mad_i64_i32 v[176:177], s[6:7], v170, s46, v[174:175]
	v_div_fixup_f32 v160, v152, v141, 1.0
	global_load_dword v208, v[176:177], off
	v_mad_i64_i32 v[176:177], s[6:7], v158, s46, v[174:175]
	global_load_dword v209, v[176:177], off
	v_mad_i64_i32 v[176:177], s[6:7], v159, s46, v[174:175]
	global_load_dword v210, v[176:177], off
	v_mad_i64_i32 v[176:177], s[6:7], v161, s46, v[174:175]
	global_load_dword v211, v[176:177], off
	v_mad_i64_i32 v[176:177], s[6:7], v163, s46, v[174:175]
	global_load_dword v212, v[176:177], off
	v_mad_i64_i32 v[176:177], s[6:7], v165, s46, v[174:175]
	global_load_dword v213, v[176:177], off
	v_mad_i64_i32 v[176:177], s[6:7], v167, s46, v[174:175]
	v_mad_i64_i32 v[174:175], s[6:7], v173, s46, v[174:175]
	global_load_dword v214, v[176:177], off
	global_load_dword v215, v[174:175], off
	s_waitcnt vmcnt(0)
	v_add_f32_e32 v141, 0, v208
	v_add_f32_e32 v141, v141, v209
	v_add_f32_e32 v141, v141, v210
	v_add_f32_e32 v141, v141, v211
	v_add_f32_e32 v141, v141, v212
	v_add_f32_e32 v141, v141, v213
	v_add_f32_e32 v141, v141, v214
	v_add_f32_e32 v141, v141, v215
	ds_bpermute_b32 v152, v157, v141
	s_waitcnt lgkmcnt(0)
	v_add_f32_e32 v141, v141, v152
	ds_bpermute_b32 v152, v153, v141
	s_waitcnt lgkmcnt(0)
; __device__ __forceinline__ void rows_rstd(const float* SS, const Unit& u, int wr, int fr, int fq, float (&rs)[2][4]) {
;     ...
;             for (int m = 0; m < 4; ++m) rs[ai][m] = RSTD[u.pm * BM + ai * HALF + wr * 64 + m * 16 + fr];
;     } else {
; #pragma unroll
;         for (int ai = 0; ai < 2; ++ai)
; #pragma unroll
;             for (int m = 0; m < 4; ++m) {
;                 const int row = u.pm * BM + ai * HALF + wr * 64 + m * 16 + fr; float s = 0.f;
; #pragma unroll
;                 for (int j = 0; j < 8; ++j) s += SS[(size_t)(fq * 8 + j) * MPAD + row];
;                 s += __shfl_xor(s, 16); s += __shfl_xor(s, 32);
;                 rs[ai][m] = 1.0f / sqrtf(s * (1.0f / 2048.0f) + RMS_EPS);
	v_add_f32_e32 v141, v141, v152
	v_fmamk_f32 v141, v141, 0x3a000000, v220
	v_cmp_gt_f32_e32 vcc, s43, v141
	v_mul_f32_e32 v152, 0x4f800000, v141
	s_nop 0
	v_cndmask_b32_e32 v141, v141, v152, vcc
	v_sqrt_f32_e32 v152, v141
	s_nop 0
	v_add_u32_e32 v156, -1, v152
	v_fma_f32 v174, -v156, v152, v141
	v_cmp_ge_f32_e64 s[6:7], 0, v174
	v_add_u32_e32 v174, 1, v152
	s_nop 0
	v_cndmask_b32_e64 v156, v152, v156, s[6:7]
	v_fma_f32 v152, -v174, v152, v141
	v_cmp_lt_f32_e64 s[6:7], 0, v152
	s_nop 1
	v_cndmask_b32_e64 v152, v156, v174, s[6:7]
	v_mul_f32_e32 v156, 0x37800000, v152
	v_cndmask_b32_e32 v152, v152, v156, vcc
	v_cmp_class_f32_e32 vcc, v141, v221
	s_nop 1
	v_cndmask_b32_e32 v141, v152, v141, vcc
	v_div_scale_f32 v152, s[6:7], v141, v141, 1.0
	v_rcp_f32_e32 v156, v152
	s_nop 0
	v_fma_f32 v174, -v152, v156, 1.0
	v_fmac_f32_e32 v156, v174, v156
	v_div_scale_f32 v174, vcc, 1.0, v141, 1.0
	v_mul_f32_e32 v175, v174, v156
	v_fma_f32 v176, -v152, v175, v174
	v_fmac_f32_e32 v175, v176, v156
	v_fma_f32 v152, -v152, v175, v174
	v_div_fmas_f32 v152, v152, v156, v175
	v_lshl_add_u64 v[174:175], v[142:143], 2, s[14:15]
	v_mad_i64_i32 v[176:177], s[6:7], v170, s46, v[174:175]
	v_div_fixup_f32 v156, v152, v141, 1.0
	global_load_dword v208, v[176:177], off
	v_mad_i64_i32 v[176:177], s[6:7], v158, s46, v[174:175]
	global_load_dword v209, v[176:177], off
	v_mad_i64_i32 v[176:177], s[6:7], v159, s46, v[174:175]
	global_load_dword v210, v[176:177], off
	v_mad_i64_i32 v[176:177], s[6:7], v161, s46, v[174:175]
	global_load_dword v211, v[176:177], off
	v_mad_i64_i32 v[176:177], s[6:7], v163, s46, v[174:175]
	global_load_dword v212, v[176:177], off
	v_mad_i64_i32 v[176:177], s[6:7], v165, s46, v[174:175]
	global_load_dword v213, v[176:177], off
	v_mad_i64_i32 v[176:177], s[6:7], v167, s46, v[174:175]
	v_mad_i64_i32 v[174:175], s[6:7], v173, s46, v[174:175]
	global_load_dword v214, v[176:177], off
	global_load_dword v215, v[174:175], off
	s_waitcnt vmcnt(0)
	v_add_f32_e32 v141, 0, v208
	v_add_f32_e32 v141, v141, v209
	v_add_f32_e32 v141, v141, v210
	v_add_f32_e32 v141, v141, v211
	v_add_f32_e32 v141, v141, v212
	v_add_f32_e32 v141, v141, v213
	v_add_f32_e32 v141, v141, v214
	v_add_f32_e32 v141, v141, v215
	ds_bpermute_b32 v152, v157, v141
	s_waitcnt lgkmcnt(0)
	v_add_f32_e32 v141, v141, v152
	ds_bpermute_b32 v152, v153, v141
	s_waitcnt lgkmcnt(0)
	v_add_f32_e32 v141, v141, v152
	v_fmamk_f32 v141, v141, 0x3a000000, v220
	v_cmp_gt_f32_e32 vcc, s43, v141
	v_mul_f32_e32 v152, 0x4f800000, v141
	s_nop 0
	v_cndmask_b32_e32 v141, v141, v152, vcc
	v_sqrt_f32_e32 v152, v141
	s_nop 0
	v_add_u32_e32 v174, -1, v152
	v_fma_f32 v175, -v174, v152, v141
	v_cmp_ge_f32_e64 s[6:7], 0, v175
	v_add_u32_e32 v175, 1, v152
	s_nop 0
	v_cndmask_b32_e64 v174, v152, v174, s[6:7]
	v_fma_f32 v152, -v175, v152, v141
	v_cmp_lt_f32_e64 s[6:7], 0, v152
	s_nop 1
	v_cndmask_b32_e64 v152, v174, v175, s[6:7]
	v_mul_f32_e32 v174, 0x37800000, v152
	v_cndmask_b32_e32 v152, v152, v174, vcc
	v_cmp_class_f32_e32 vcc, v141, v221
	s_nop 1
	v_cndmask_b32_e32 v141, v152, v141, vcc
	v_div_scale_f32 v152, s[6:7], v141, v141, 1.0
	v_rcp_f32_e32 v174, v152
	s_nop 0
	v_fma_f32 v175, -v152, v174, 1.0
	v_fmac_f32_e32 v174, v175, v174
	v_div_scale_f32 v175, vcc, 1.0, v141, 1.0
	v_mul_f32_e32 v176, v175, v174
	v_fma_f32 v177, -v152, v176, v175
	v_fmac_f32_e32 v176, v177, v174
	v_fma_f32 v152, -v152, v176, v175
	v_div_fmas_f32 v152, v152, v174, v176
	v_div_fixup_f32 v152, v152, v141, 1.0
	v_ashrrev_i32_e32 v141, 31, v140
	v_lshl_add_u64 v[174:175], v[140:141], 2, s[14:15]
	v_mad_i64_i32 v[176:177], s[6:7], v170, s46, v[174:175]
	global_load_dword v208, v[176:177], off
	v_mad_i64_i32 v[176:177], s[6:7], v158, s46, v[174:175]
	global_load_dword v209, v[176:177], off
	v_mad_i64_i32 v[158:159], s[6:7], v159, s46, v[174:175]
	global_load_dword v210, v[158:159], off
	v_mad_i64_i32 v[158:159], s[6:7], v161, s46, v[174:175]
	global_load_dword v211, v[158:159], off
	v_mad_i64_i32 v[158:159], s[6:7], v163, s46, v[174:175]
	global_load_dword v212, v[158:159], off
	v_mad_i64_i32 v[158:159], s[6:7], v165, s46, v[174:175]
	global_load_dword v213, v[158:159], off
	v_mad_i64_i32 v[158:159], s[6:7], v167, s46, v[174:175]
	global_load_dword v214, v[158:159], off
	v_mad_i64_i32 v[158:159], s[6:7], v173, s46, v[174:175]
	global_load_dword v215, v[158:159], off
	s_waitcnt vmcnt(0)
	v_add_f32_e32 v141, 0, v208
	v_add_f32_e32 v141, v141, v209
	v_add_f32_e32 v141, v141, v210
	v_add_f32_e32 v141, v141, v211
	v_add_f32_e32 v141, v141, v212
	v_add_f32_e32 v141, v141, v213
	v_add_f32_e32 v141, v141, v214
	v_add_f32_e32 v141, v141, v215
	ds_bpermute_b32 v157, v157, v141
	s_waitcnt lgkmcnt(0)
	v_add_f32_e32 v141, v141, v157
	ds_bpermute_b32 v153, v153, v141
	s_waitcnt lgkmcnt(0)
	v_add_f32_e32 v141, v141, v153
	v_fmamk_f32 v141, v141, 0x3a000000, v220
	v_cmp_gt_f32_e32 vcc, s43, v141
	v_mul_f32_e32 v153, 0x4f800000, v141
	s_nop 0
	v_cndmask_b32_e32 v141, v141, v153, vcc
	v_sqrt_f32_e32 v153, v141
	s_nop 0
	v_add_u32_e32 v157, -1, v153
	v_fma_f32 v158, -v157, v153, v141
	v_cmp_ge_f32_e64 s[6:7], 0, v158
	v_add_u32_e32 v158, 1, v153
	s_nop 0
	v_cndmask_b32_e64 v157, v153, v157, s[6:7]
	v_fma_f32 v153, -v158, v153, v141
	v_cmp_lt_f32_e64 s[6:7], 0, v153
	s_nop 1
	v_cndmask_b32_e64 v153, v157, v158, s[6:7]
	v_mul_f32_e32 v157, 0x37800000, v153
	v_cndmask_b32_e32 v153, v153, v157, vcc
	v_cmp_class_f32_e32 vcc, v141, v221
	s_nop 1
	v_cndmask_b32_e32 v141, v153, v141, vcc
	v_div_scale_f32 v153, s[6:7], v141, v141, 1.0
	v_rcp_f32_e32 v157, v153
	s_mov_b64 s[6:7], 0
	v_fma_f32 v158, -v153, v157, 1.0
	v_fmac_f32_e32 v157, v158, v157
	v_div_scale_f32 v158, vcc, 1.0, v141, 1.0
	v_mul_f32_e32 v159, v158, v157
	v_fma_f32 v161, -v153, v159, v158
	v_fmac_f32_e32 v159, v161, v157
	v_fma_f32 v153, -v153, v159, v158
	v_div_fmas_f32 v153, v153, v157, v159
	v_div_fixup_f32 v158, v153, v141, 1.0

; __device__ __forceinline__ void phase_conv(KArgs a, int tid) {
;     ...
;     for (int s = blockIdx.x; s < MSAMP; s += gridDim.x) {
;         const int row = MPROMPT + s;
;         const float* SS = (const float*)(a->ws + WS_SS); const float* PS = (const float*)(a->ws + WS_PS); float sq = 0.f;
;         for (int j = 0; j < 32; ++j) sq += SS[(size_t)j * MPAD + row];
;         const float rs = 1.0f / sqrtf(sq * (1.0f / 2048.0f) + RMS_EPS);
;         f32x4 gy = zero, x3 = zero;
; #pragma unroll
;         for (int sl = 0; sl < 8; ++sl) { const float* p = PS + ((size_t)sl * 128 + s) * 4096 + c; gy = gy + *(const f32x4*)p; x3 = x3 + *(const f32x4*)(p + 2048); }
.LBB0_1396:
	s_add_i32 s10, s8, 0x2000
	s_ashr_i32 s11, s10, 31
	s_lshl_b64 s[4:5], s[10:11], 2
	s_add_u32 s4, s2, s4
	s_addc_u32 s5, s12, s5
	global_load_dword v0, v1, s[4:5]
	v_mov_b32_e32 v97, 0x8000
	global_load_dword v97, v97, s[4:5] offset:1024
	v_mov_b32_e32 v98, 0x10000
	global_load_dword v98, v98, s[4:5] offset:2048
	v_mov_b32_e32 v99, 0x18000
	global_load_dword v99, v99, s[4:5] offset:3072
	v_mov_b32_e32 v100, 0x21000
	global_load_dword v100, v100, s[4:5]
	v_mov_b32_e32 v101, 0x29000
	global_load_dword v101, v101, s[4:5] offset:1024
	v_mov_b32_e32 v102, 0x31000
	global_load_dword v102, v102, s[4:5] offset:2048
	v_mov_b32_e32 v103, 0x39000
	global_load_dword v103, v103, s[4:5] offset:3072
	v_mov_b32_e32 v104, 0x42000
	global_load_dword v104, v104, s[4:5]
	v_mov_b32_e32 v105, 0x4a000
	global_load_dword v105, v105, s[4:5] offset:1024
	v_mov_b32_e32 v106, 0x52000
	global_load_dword v106, v106, s[4:5] offset:2048
	v_mov_b32_e32 v107, 0x5a000
	global_load_dword v107, v107, s[4:5] offset:3072
	v_mov_b32_e32 v108, 0x63000
	global_load_dword v108, v108, s[4:5]
	v_mov_b32_e32 v109, 0x6b000
	global_load_dword v109, v109, s[4:5] offset:1024
	v_mov_b32_e32 v110, 0x73000
	global_load_dword v110, v110, s[4:5] offset:2048
	v_mov_b32_e32 v111, 0x7b000
	global_load_dword v111, v111, s[4:5] offset:3072
	v_mov_b32_e32 v112, 0x84000
	global_load_dword v112, v112, s[4:5]
	v_mov_b32_e32 v113, 0x8c000
	global_load_dword v113, v113, s[4:5] offset:1024
	v_mov_b32_e32 v114, 0x94000
	global_load_dword v114, v114, s[4:5] offset:2048
	v_mov_b32_e32 v115, 0x9c000
	global_load_dword v115, v115, s[4:5] offset:3072
	v_mov_b32_e32 v116, 0xa5000
	global_load_dword v116, v116, s[4:5]
	v_mov_b32_e32 v117, 0xad000
	global_load_dword v117, v117, s[4:5] offset:1024
	v_mov_b32_e32 v118, 0xb5000
	global_load_dword v118, v118, s[4:5] offset:2048
	v_mov_b32_e32 v119, 0xbd000
	global_load_dword v119, v119, s[4:5] offset:3072
	v_mov_b32_e32 v120, 0xc6000
	global_load_dword v120, v120, s[4:5]
	v_mov_b32_e32 v121, 0xce000
	global_load_dword v121, v121, s[4:5] offset:1024
	v_mov_b32_e32 v122, 0xd6000
	global_load_dword v122, v122, s[4:5] offset:2048
	v_mov_b32_e32 v123, 0xde000
	global_load_dword v123, v123, s[4:5] offset:3072
	v_mov_b32_e32 v124, 0xe7000
	global_load_dword v124, v124, s[4:5]
	v_mov_b32_e32 v125, 0xef000
	global_load_dword v125, v125, s[4:5] offset:1024
	v_mov_b32_e32 v126, 0xf7000
	global_load_dword v126, v126, s[4:5] offset:2048
	v_mov_b32_e32 v127, 0xff000
	global_load_dword v127, v127, s[4:5] offset:3072
	s_ashr_i32 s9, s8, 31
	s_waitcnt vmcnt(0)
	v_add_f32_e32 v0, 0, v0
	v_add_f32_e32 v0, v0, v97
	v_add_f32_e32 v0, v0, v98
	v_add_f32_e32 v0, v0, v99
	v_add_f32_e32 v0, v0, v100
	v_add_f32_e32 v0, v0, v101
	v_add_f32_e32 v0, v0, v102
	v_add_f32_e32 v0, v0, v103
	v_add_f32_e32 v0, v0, v104
	v_add_f32_e32 v0, v0, v105
	v_add_f32_e32 v0, v0, v106
	v_add_f32_e32 v0, v0, v107
	v_add_f32_e32 v0, v0, v108
	v_add_f32_e32 v0, v0, v109
	v_add_f32_e32 v0, v0, v110
	v_add_f32_e32 v0, v0, v111
	v_add_f32_e32 v0, v0, v112
	v_add_f32_e32 v0, v0, v113
	v_add_f32_e32 v0, v0, v114
	v_add_f32_e32 v0, v0, v115
	v_add_f32_e32 v0, v0, v116
	v_add_f32_e32 v0, v0, v117
	v_add_f32_e32 v0, v0, v118
	v_add_f32_e32 v0, v0, v119
	v_add_f32_e32 v0, v0, v120
	v_add_f32_e32 v0, v0, v121
	v_add_f32_e32 v0, v0, v122
	v_add_f32_e32 v0, v0, v123
	v_add_f32_e32 v0, v0, v124
	v_add_f32_e32 v0, v0, v125
	v_add_f32_e32 v0, v0, v126
	v_add_f32_e32 v0, v0, v127
	v_fmamk_f32 v0, v0, 0x3a000000, v220
	v_cmp_gt_f32_e32 vcc, s43, v0
	v_mul_f32_e32 v24, 0x4f800000, v0
	s_nop 0
	v_cndmask_b32_e32 v0, v0, v24, vcc
	v_sqrt_f32_e32 v24, v0
	s_nop 0
	v_add_u32_e32 v25, -1, v24
	v_fma_f32 v26, -v25, v24, v0
	v_cmp_ge_f32_e64 s[4:5], 0, v26
	v_add_u32_e32 v26, 1, v24
	s_nop 0
	v_cndmask_b32_e64 v25, v24, v25, s[4:5]
	v_fma_f32 v24, -v26, v24, v0
	v_cmp_lt_f32_e64 s[4:5], 0, v24
	s_nop 1
	v_cndmask_b32_e64 v24, v25, v26, s[4:5]
	v_mul_f32_e32 v25, 0x37800000, v24
	s_lshl_b64 s[4:5], s[8:9], 14
	v_cndmask_b32_e32 v24, v24, v25, vcc
	v_cmp_class_f32_e32 vcc, v0, v221
	v_lshl_add_u64 v[66:67], v[38:39], 0, s[4:5]
	s_mov_b32 s4, 0x202000
	v_cndmask_b32_e32 v0, v24, v0, vcc
	global_load_dwordx4 v[24:27], v[66:67], off
	s_waitcnt vmcnt(0)
	v_pk_add_f32 v[34:35], v[24:25], 0 op_sel_hi:[1,0]
	v_add_co_u32_e32 v24, vcc, s38, v66
	v_pk_add_f32 v[32:33], v[26:27], 0 op_sel_hi:[1,0]
	s_nop 0
	v_addc_co_u32_e32 v25, vcc, 0, v67, vcc
	v_add_co_u32_e32 v28, vcc, s39, v66
	global_load_dwordx4 v[24:27], v[24:25], off
	s_nop 0
	v_addc_co_u32_e32 v29, vcc, 0, v67, vcc
	global_load_dwordx4 v[28:31], v[28:29], off
	s_waitcnt vmcnt(1)
	v_pk_add_f32 v[24:25], v[24:25], 0 op_sel_hi:[1,0]
	v_pk_add_f32 v[26:27], v[26:27], 0 op_sel_hi:[1,0]
	s_waitcnt vmcnt(0)
	v_pk_add_f32 v[48:49], v[34:35], v[28:29]
	v_add_co_u32_e32 v28, vcc, s4, v66
	v_pk_add_f32 v[46:47], v[32:33], v[30:31]
	s_nop 0
	v_addc_co_u32_e32 v29, vcc, 0, v67, vcc
	v_add_co_u32_e32 v32, vcc, s77, v66
	global_load_dwordx4 v[28:31], v[28:29], off
	s_nop 0
	v_addc_co_u32_e32 v33, vcc, 0, v67, vcc
	global_load_dwordx4 v[32:35], v[32:33], off
	s_mov_b32 s4, 0x402000
	s_waitcnt vmcnt(1)
	v_pk_add_f32 v[24:25], v[24:25], v[28:29]
	v_pk_add_f32 v[26:27], v[26:27], v[30:31]
	s_waitcnt vmcnt(0)
	v_pk_add_f32 v[52:53], v[48:49], v[32:33]
	v_add_co_u32_e32 v32, vcc, s4, v66
	v_pk_add_f32 v[50:51], v[46:47], v[34:35]
	s_nop 0
	v_addc_co_u32_e32 v33, vcc, 0, v67, vcc
	v_add_co_u32_e32 v46, vcc, s74, v66
	global_load_dwordx4 v[32:35], v[32:33], off
	s_nop 0
	v_addc_co_u32_e32 v47, vcc, 0, v67, vcc
	global_load_dwordx4 v[46:49], v[46:47], off
	s_mov_b32 s4, 0x602000
	s_waitcnt vmcnt(1)
; __device__ __forceinline__ float gelu_tanh_f(float x) { const float t = 1.5957691216f * (x + 0.044715f * x * x * x); return x * fast_rcp(1.0f + __expf(-t)); }
; __device__ __forceinline__ unsigned cvtpk(float lo, float hi) { unsigned r; asm volatile("v_cvt_pk_bf16_f32 %0, %1, %2" : "=v"(r) : "v"(lo), "v"(hi)); return r; }
; __device__ __forceinline__ void phase_conv(KArgs a, int tid) {
;     ...
;         for (int sl = 0; sl < 8; ++sl) { const float* p = PS + ((size_t)sl * 128 + s) * 4096 + c; gy = gy + *(const f32x4*)p; x3 = x3 + *(const f32x4*)(p + 2048); }
;         x3 = x3 * rs; gy = gy * rs;
; #pragma unroll
;         for (int e = 0; e < 4; ++e) gy[e] = pg8::gelu_tanh_f(gy[e]);
;         u32x2 go; go.x = cvtpk(gy[0], gy[1]); go.y = cvtpk(gy[2], gy[3]); *(u32x2*)((bf16*)(a->ws + WS_GATE) + (size_t)row * DM + c) = go;
;         const float* b = buf + (size_t)s * 3 * DM + c;
;         const f32x4 x0 = *(const f32x4*)b, x1 = *(const f32x4*)(b + DM), x2 = *(const f32x4*)(b + 2 * DM);
;         float* o = a->out + OUT_SC + (size_t)s * 3 * DM + c; *(f32x4*)o = x1; *(f32x4*)(o + DM) = x2; *(f32x4*)(o + 2 * DM) = x3;
;         const f32x4 xc = bias + x0 * w0 + x1 * w1 + x2 * w2 + x3 * w3;
;         u32x2 ow; ow.x = cvtpk(xc[0], xc[1]); ow.y = cvtpk(xc[2], xc[3]);
;         *(u32x2*)(XCB + ((size_t)(c >> 8) * MPAD + row) * 256 + (c & 255)) = ow;
;     }
	v_pk_add_f32 v[24:25], v[24:25], v[32:33]
	v_pk_add_f32 v[26:27], v[26:27], v[34:35]
	s_waitcnt vmcnt(0)
	v_pk_add_f32 v[56:57], v[52:53], v[46:47]
	v_add_co_u32_e32 v46, vcc, s4, v66
	v_pk_add_f32 v[54:55], v[50:51], v[48:49]
	s_nop 0
	v_addc_co_u32_e32 v47, vcc, 0, v67, vcc
	v_add_co_u32_e32 v50, vcc, s37, v66
	global_load_dwordx4 v[46:49], v[46:47], off
	s_nop 0
	v_addc_co_u32_e32 v51, vcc, 0, v67, vcc
	global_load_dwordx4 v[50:53], v[50:51], off
	s_mov_b32 s4, 0x802000
	s_waitcnt vmcnt(1)
	v_pk_add_f32 v[24:25], v[24:25], v[46:47]
	v_mad_i64_i32 v[46:47], s[14:15], s8, v231, v[2:3]
	s_waitcnt vmcnt(0)
	v_pk_add_f32 v[60:61], v[56:57], v[50:51]
	v_add_co_u32_e32 v50, vcc, s4, v66
	v_pk_add_f32 v[58:59], v[54:55], v[52:53]
	s_nop 0
	v_addc_co_u32_e32 v51, vcc, 0, v67, vcc
	v_add_co_u32_e32 v54, vcc, s97, v66
	global_load_dwordx4 v[50:53], v[50:51], off
	s_nop 0
	v_addc_co_u32_e32 v55, vcc, 0, v67, vcc
	global_load_dwordx4 v[54:57], v[54:55], off
	s_mov_b32 s4, 0xa02000
	v_pk_add_f32 v[26:27], v[26:27], v[48:49]
	s_waitcnt vmcnt(1)
	v_pk_add_f32 v[24:25], v[24:25], v[50:51]
	v_pk_add_f32 v[26:27], v[26:27], v[52:53]
	s_waitcnt vmcnt(0)
	v_pk_add_f32 v[64:65], v[60:61], v[54:55]
	v_add_co_u32_e32 v54, vcc, s4, v66
	v_pk_add_f32 v[62:63], v[58:59], v[56:57]
	s_nop 0
	v_addc_co_u32_e32 v55, vcc, 0, v67, vcc
	v_add_co_u32_e32 v58, vcc, s56, v66
	global_load_dwordx4 v[54:57], v[54:55], off
	s_nop 0
	v_addc_co_u32_e32 v59, vcc, 0, v67, vcc
	global_load_dwordx4 v[58:61], v[58:59], off
	s_mov_b32 s4, 0xc02000
	s_waitcnt vmcnt(1)
	v_pk_add_f32 v[26:27], v[26:27], v[56:57]
	v_pk_add_f32 v[24:25], v[24:25], v[54:55]
	s_waitcnt vmcnt(0)
	v_pk_add_f32 v[70:71], v[64:65], v[58:59]
	v_add_co_u32_e32 v58, vcc, s4, v66
	v_pk_add_f32 v[68:69], v[62:63], v[60:61]
	s_nop 0
	v_addc_co_u32_e32 v59, vcc, 0, v67, vcc
	v_add_co_u32_e32 v62, vcc, s57, v66
	global_load_dwordx4 v[58:61], v[58:59], off
	s_nop 0
	v_addc_co_u32_e32 v63, vcc, 0, v67, vcc
	global_load_dwordx4 v[62:65], v[62:63], off
	s_waitcnt vmcnt(1)
	v_pk_add_f32 v[26:27], v[26:27], v[60:61]
	v_pk_add_f32 v[24:25], v[24:25], v[58:59]
	s_waitcnt vmcnt(0)
	v_pk_add_f32 v[70:71], v[70:71], v[62:63]
	v_add_co_u32_e32 v62, vcc, 0xe02000, v66
	v_div_scale_f32 v66, s[4:5], v0, v0, 1.0
	s_nop 0
	v_addc_co_u32_e32 v63, vcc, 0, v67, vcc
	v_rcp_f32_e32 v67, v66
	v_pk_add_f32 v[68:69], v[68:69], v[64:65]
	s_lshl_b64 s[4:5], s[10:11], 12
	v_lshl_add_u64 v[30:31], v[40:41], 0, s[4:5]
	v_fma_f32 v72, -v66, v67, 1.0
	v_fmac_f32_e32 v67, v72, v67
	v_div_scale_f32 v72, vcc, 1.0, v0, 1.0
	v_mul_f32_e32 v73, v72, v67
	v_fma_f32 v74, -v66, v73, v72
	v_fmac_f32_e32 v73, v74, v67
	v_fma_f32 v66, -v66, v73, v72
	v_div_fmas_f32 v66, v66, v67, v73
	v_div_fixup_f32 v0, v66, v0, 1.0
	v_pk_mul_f32 v[66:67], v[0:1], v[68:69] op_sel_hi:[0,1]
	v_pk_mul_f32 v[68:69], v[0:1], v[70:71] op_sel_hi:[0,1]
	v_mul_f32_e32 v70, 0x3d372713, v68
	v_mul_f32_e32 v70, v68, v70
	v_fma_f32 v70, v68, v70, v68
	v_mul_f32_e32 v70, 0xbfcc422a, v70
	v_mul_f32_e32 v70, 0x3fb8aa3b, v70
	v_exp_f32_e32 v70, v70
	v_add_co_u32_e32 v32, vcc, s38, v46
	global_load_dwordx4 v[62:65], v[62:63], off
	v_add_f32_e32 v70, 1.0, v70
	v_rcp_f32_e32 v70, v70
	v_addc_co_u32_e32 v33, vcc, 0, v47, vcc
	s_mul_i32 s5, s8, 0x6000
	v_mul_f32_e32 v68, v68, v70
	v_mul_f32_e32 v70, 0x3d372713, v69
	v_mul_f32_e32 v70, v69, v70
	v_fma_f32 v70, v69, v70, v69
	v_mul_f32_e32 v70, 0xbfcc422a, v70
	v_mul_f32_e32 v70, 0x3fb8aa3b, v70
	v_exp_f32_e32 v70, v70
	s_mul_hi_i32 s4, s8, 0x6000
	v_add_f32_e32 v70, 1.0, v70
	v_rcp_f32_e32 v70, v70
	s_waitcnt vmcnt(0)
	v_pk_add_f32 v[26:27], v[26:27], v[64:65]
	v_mul_f32_e32 v69, v69, v70
	v_mul_f32_e32 v70, 0x3d372713, v66
	v_mul_f32_e32 v70, v66, v70
	v_fma_f32 v70, v66, v70, v66
	v_mul_f32_e32 v70, 0xbfcc422a, v70
	v_mul_f32_e32 v70, 0x3fb8aa3b, v70
	v_exp_f32_e32 v70, v70
	v_cvt_pk_bf16_f32 v28, v68, v69
	v_pk_add_f32 v[24:25], v[24:25], v[62:63]
	v_pk_mul_f32 v[26:27], v[0:1], v[26:27] op_sel_hi:[0,1]
	v_add_f32_e32 v70, 1.0, v70
	v_rcp_f32_e32 v70, v70
	v_pk_mul_f32 v[24:25], v[0:1], v[24:25] op_sel_hi:[0,1]
	v_mul_f32_e32 v66, v66, v70
	v_mul_f32_e32 v70, 0x3d372713, v67
	v_mul_f32_e32 v70, v67, v70
	v_fma_f32 v70, v67, v70, v67
	v_mul_f32_e32 v70, 0xbfcc422a, v70
	v_mul_f32_e32 v70, 0x3fb8aa3b, v70
	v_exp_f32_e32 v70, v70
	s_nop 0
	v_add_f32_e32 v70, 1.0, v70
	v_rcp_f32_e32 v70, v70
	s_nop 0
	v_mul_f32_e32 v67, v67, v70
	v_cvt_pk_bf16_f32 v29, v66, v67
	global_store_dwordx2 v[30:31], v[28:29], off
	global_load_dwordx4 v[28:31], v[46:47], off
	s_load_dwordx2 s[14:15], s[6:7], 0x110
	global_load_dwordx4 v[32:35], v[32:33], off
	v_add_co_u32_e32 v46, vcc, s41, v46
	s_waitcnt lgkmcnt(0)
	s_add_u32 s14, s14, s5
	v_addc_co_u32_e32 v47, vcc, 0, v47, vcc
	global_load_dwordx4 v[46:49], v[46:47], off
	s_addc_u32 s15, s15, s4
	v_lshl_add_u64 v[50:51], v[36:37], 2, s[14:15]
	s_mov_b32 s4, 0x4a20000
	v_add_co_u32_e32 v52, vcc, s4, v50
	s_mov_b32 s4, 0x4a22000
	s_nop 0
	v_addc_co_u32_e32 v53, vcc, 0, v51, vcc
	s_add_i32 s8, s8, s73
	s_cmpk_lt_i32 s8, 0x80
	s_waitcnt vmcnt(2)
	v_pk_fma_f32 v[30:31], v[6:7], v[30:31], v[22:23]
	v_pk_fma_f32 v[28:29], v[4:5], v[28:29], v[20:21]
	s_waitcnt vmcnt(1)
	global_store_dwordx4 v[52:53], v[32:35], off
	v_add_co_u32_e32 v52, vcc, s4, v50
	s_mov_b32 s4, 0x4a24000
	s_nop 0
	v_addc_co_u32_e32 v53, vcc, 0, v51, vcc
	v_add_co_u32_e32 v50, vcc, s4, v50
	v_pk_fma_f32 v[30:31], v[10:11], v[34:35], v[30:31]
	v_pk_fma_f32 v[28:29], v[8:9], v[32:33], v[28:29]
	v_addc_co_u32_e32 v51, vcc, 0, v51, vcc
	s_waitcnt vmcnt(1)
	v_pk_fma_f32 v[30:31], v[14:15], v[48:49], v[30:31]
	v_pk_fma_f32 v[28:29], v[12:13], v[46:47], v[28:29]
	global_store_dwordx4 v[50:51], v[24:27], off
	global_store_dwordx4 v[52:53], v[46:49], off
	s_nop 0
	v_pk_fma_f32 v[26:27], v[18:19], v[26:27], v[30:31]
	v_pk_fma_f32 v[24:25], v[16:17], v[24:25], v[28:29]
	s_nop 0
	v_cvt_pk_bf16_f32 v24, v24, v25
	v_cvt_pk_bf16_f32 v25, v26, v27
	v_lshl_add_u64 v[26:27], v[42:43], 0, s[10:11]
	v_lshlrev_b64 v[26:27], 9, v[26:27]
	v_lshl_add_u64 v[26:27], v[44:45], 0, v[26:27]
	global_store_dwordx2 v[26:27], v[24:25], off
	s_cbranch_scc1 .LBB0_1396

; __device__ __forceinline__ void phase_scan_sum(KArgs a, int gw, int NGW, int lane) {
;     ...
; #pragma unroll 8
;         for (int t = 0; t < 64; ++t) { const u32x2 lw = *(const u32x2*)(AA + (row0 + t) * DM + c); const f32x4 av = (f32x4){__expf(bflo(lw.x)), __expf(bfhi(lw.x)), __expf(bflo(lw.y)), __expf(bfhi(lw.y))}; const u32x2 bw = *(const u32x2*)(BB + (row0 + t) * DM + c); const f32x4 bv = (f32x4){bflo(bw.x), bfhi(bw.x), bflo(bw.y), bfhi(bw.y)}; Ap = Ap * av; Hh = av * Hh + bv; }
.LBB0_1526:
	v_lshl_add_u64 v[12:13], v[10:11], 0, s[8:9]
	s_mov_b64 s[100:101], 0x2ddd5000
	s_add_u32 s8, s8, 0x8000
	s_addc_u32 s9, s9, 0
	v_lshl_add_u64 v[96:97], v[12:13], 0, s[100:101]
	s_mov_b64 s[100:101], 0x31fd5000
	s_nop 0
	v_lshl_add_u64 v[98:99], v[12:13], 0, s[100:101]
	s_mov_b64 s[100:101], 0x2000
	s_nop 0
	v_lshl_add_u64 v[100:101], v[96:97], 0, s[100:101]
	v_lshl_add_u64 v[102:103], v[98:99], 0, s[100:101]
	global_load_dwordx2 v[112:113], v[96:97], off offset:-2816
	global_load_dwordx2 v[114:115], v[98:99], off offset:-2816
	global_load_dwordx2 v[116:117], v[96:97], off offset:1280
	global_load_dwordx2 v[118:119], v[98:99], off offset:1280
	v_lshl_add_u64 v[104:105], v[100:101], 0, s[100:101]
	v_lshl_add_u64 v[106:107], v[102:103], 0, s[100:101]
	global_load_dwordx2 v[120:121], v[100:101], off offset:-2816
	global_load_dwordx2 v[122:123], v[102:103], off offset:-2816
	global_load_dwordx2 v[124:125], v[100:101], off offset:1280
	global_load_dwordx2 v[126:127], v[102:103], off offset:1280
	v_lshl_add_u64 v[108:109], v[104:105], 0, s[100:101]
	v_lshl_add_u64 v[110:111], v[106:107], 0, s[100:101]
	global_load_dwordx2 v[128:129], v[104:105], off offset:-2816
	global_load_dwordx2 v[130:131], v[106:107], off offset:-2816
	global_load_dwordx2 v[132:133], v[104:105], off offset:1280
	global_load_dwordx2 v[134:135], v[106:107], off offset:1280
	global_load_dwordx2 v[136:137], v[108:109], off offset:-2816
	global_load_dwordx2 v[138:139], v[110:111], off offset:-2816
	global_load_dwordx2 v[140:141], v[108:109], off offset:1280
	global_load_dwordx2 v[142:143], v[110:111], off offset:1280
	s_cmp_eq_u32 s8, 0x40000
	s_waitcnt vmcnt(14)
	v_lshlrev_b32_e32 v0, 16, v112
	v_mul_f32_e32 v0, 0x3fb8aa3b, v0
	v_exp_f32_e32 v18, v0
	v_and_b32_e32 v0, 0xffff0000, v112
	v_mul_f32_e32 v0, 0x3fb8aa3b, v0
	v_exp_f32_e32 v19, v0
	v_lshlrev_b32_e32 v0, 16, v113
	v_mul_f32_e32 v0, 0x3fb8aa3b, v0
	v_exp_f32_e32 v16, v0
	v_and_b32_e32 v0, 0xffff0000, v113
	v_mul_f32_e32 v0, 0x3fb8aa3b, v0
	v_exp_f32_e32 v17, v0
	v_lshlrev_b32_e32 v22, 16, v114
	v_and_b32_e32 v23, 0xffff0000, v114
	v_lshlrev_b32_e32 v20, 16, v115
	v_and_b32_e32 v21, 0xffff0000, v115
	v_pk_mul_f32 v[8:9], v[8:9], v[16:17]
	v_pk_fma_f32 v[4:5], v[4:5], v[16:17], v[20:21]
	v_pk_mul_f32 v[6:7], v[6:7], v[18:19]
	v_pk_fma_f32 v[2:3], v[2:3], v[18:19], v[22:23]
	s_waitcnt vmcnt(12)
	v_lshlrev_b32_e32 v0, 16, v116
	v_mul_f32_e32 v0, 0x3fb8aa3b, v0
	v_exp_f32_e32 v18, v0
	v_and_b32_e32 v0, 0xffff0000, v116
	v_mul_f32_e32 v0, 0x3fb8aa3b, v0
	v_exp_f32_e32 v19, v0
	v_lshlrev_b32_e32 v0, 16, v117
	v_mul_f32_e32 v0, 0x3fb8aa3b, v0
	v_exp_f32_e32 v16, v0
	v_and_b32_e32 v0, 0xffff0000, v117
	v_mul_f32_e32 v0, 0x3fb8aa3b, v0
	v_exp_f32_e32 v17, v0
	v_lshlrev_b32_e32 v22, 16, v118
	v_and_b32_e32 v23, 0xffff0000, v118
	v_lshlrev_b32_e32 v20, 16, v119
	v_and_b32_e32 v21, 0xffff0000, v119
	v_pk_mul_f32 v[8:9], v[8:9], v[16:17]
	v_pk_fma_f32 v[4:5], v[4:5], v[16:17], v[20:21]
	v_pk_mul_f32 v[6:7], v[6:7], v[18:19]
	v_pk_fma_f32 v[2:3], v[2:3], v[18:19], v[22:23]
	s_waitcnt vmcnt(10)
	v_lshlrev_b32_e32 v0, 16, v120
	v_mul_f32_e32 v0, 0x3fb8aa3b, v0
	v_exp_f32_e32 v18, v0
	v_and_b32_e32 v0, 0xffff0000, v120
	v_mul_f32_e32 v0, 0x3fb8aa3b, v0
	v_exp_f32_e32 v19, v0
	v_lshlrev_b32_e32 v0, 16, v121
	v_mul_f32_e32 v0, 0x3fb8aa3b, v0
	v_exp_f32_e32 v16, v0
	v_and_b32_e32 v0, 0xffff0000, v121
	v_mul_f32_e32 v0, 0x3fb8aa3b, v0
	v_exp_f32_e32 v17, v0
	v_lshlrev_b32_e32 v22, 16, v122
	v_and_b32_e32 v23, 0xffff0000, v122
	v_lshlrev_b32_e32 v20, 16, v123
	v_and_b32_e32 v21, 0xffff0000, v123
	v_pk_mul_f32 v[8:9], v[8:9], v[16:17]
	v_pk_fma_f32 v[4:5], v[4:5], v[16:17], v[20:21]
	v_pk_mul_f32 v[6:7], v[6:7], v[18:19]
	v_pk_fma_f32 v[2:3], v[2:3], v[18:19], v[22:23]
	s_waitcnt vmcnt(8)
; __device__ __forceinline__ void phase_scan_sum(KArgs a, int gw, int NGW, int lane) {
;     ...
;     for (int it = gwb; it < NBATCH * NCHUNK * 8; it += NGW) {
;         const int cg8 = it & 7, bc = it >> 3; const int c = cg8 * 256 + lane * 4; const size_t row0 = (size_t)bc * 64;
;         f32x4 Ap = (f32x4){1.f, 1.f, 1.f, 1.f}, Hh = (f32x4){0.f, 0.f, 0.f, 0.f};
; #pragma unroll 8
;         for (int t = 0; t < 64; ++t) { const u32x2 lw = *(const u32x2*)(AA + (row0 + t) * DM + c); const f32x4 av = (f32x4){__expf(bflo(lw.x)), __expf(bfhi(lw.x)), __expf(bflo(lw.y)), __expf(bfhi(lw.y))}; const u32x2 bw = *(const u32x2*)(BB + (row0 + t) * DM + c); const f32x4 bv = (f32x4){bflo(bw.x), bfhi(bw.x), bflo(bw.y), bfhi(bw.y)}; Ap = Ap * av; Hh = av * Hh + bv; }
;         *(f32x4*)(SA + (size_t)bc * DM + c) = Ap; *(f32x4*)(SH + (size_t)bc * DM + c) = Hh;
;     }
	v_lshlrev_b32_e32 v0, 16, v124
	v_mul_f32_e32 v0, 0x3fb8aa3b, v0
	v_exp_f32_e32 v18, v0
	v_and_b32_e32 v0, 0xffff0000, v124
	v_mul_f32_e32 v0, 0x3fb8aa3b, v0
	v_exp_f32_e32 v19, v0
	v_lshlrev_b32_e32 v0, 16, v125
	v_mul_f32_e32 v0, 0x3fb8aa3b, v0
	v_exp_f32_e32 v16, v0
	v_and_b32_e32 v0, 0xffff0000, v125
	v_mul_f32_e32 v0, 0x3fb8aa3b, v0
	v_exp_f32_e32 v17, v0
	v_lshlrev_b32_e32 v22, 16, v126
	v_and_b32_e32 v23, 0xffff0000, v126
	v_lshlrev_b32_e32 v20, 16, v127
	v_and_b32_e32 v21, 0xffff0000, v127
	v_pk_mul_f32 v[8:9], v[8:9], v[16:17]
	v_pk_fma_f32 v[4:5], v[4:5], v[16:17], v[20:21]
	v_pk_mul_f32 v[6:7], v[6:7], v[18:19]
	v_pk_fma_f32 v[2:3], v[2:3], v[18:19], v[22:23]
	s_waitcnt vmcnt(6)
	v_lshlrev_b32_e32 v0, 16, v128
	v_mul_f32_e32 v0, 0x3fb8aa3b, v0
	v_exp_f32_e32 v18, v0
	v_and_b32_e32 v0, 0xffff0000, v128
	v_mul_f32_e32 v0, 0x3fb8aa3b, v0
	v_exp_f32_e32 v19, v0
	v_lshlrev_b32_e32 v0, 16, v129
	v_mul_f32_e32 v0, 0x3fb8aa3b, v0
	v_exp_f32_e32 v16, v0
	v_and_b32_e32 v0, 0xffff0000, v129
	v_mul_f32_e32 v0, 0x3fb8aa3b, v0
	v_exp_f32_e32 v17, v0
	v_lshlrev_b32_e32 v22, 16, v130
	v_and_b32_e32 v23, 0xffff0000, v130
	v_lshlrev_b32_e32 v20, 16, v131
	v_and_b32_e32 v21, 0xffff0000, v131
	v_pk_mul_f32 v[8:9], v[8:9], v[16:17]
	v_pk_fma_f32 v[4:5], v[4:5], v[16:17], v[20:21]
	v_pk_mul_f32 v[6:7], v[6:7], v[18:19]
	v_pk_fma_f32 v[2:3], v[2:3], v[18:19], v[22:23]
	s_waitcnt vmcnt(4)
	v_lshlrev_b32_e32 v0, 16, v132
	v_mul_f32_e32 v0, 0x3fb8aa3b, v0
	v_exp_f32_e32 v18, v0
	v_and_b32_e32 v0, 0xffff0000, v132
	v_mul_f32_e32 v0, 0x3fb8aa3b, v0
	v_exp_f32_e32 v19, v0
	v_lshlrev_b32_e32 v0, 16, v133
	v_mul_f32_e32 v0, 0x3fb8aa3b, v0
	v_exp_f32_e32 v16, v0
	v_and_b32_e32 v0, 0xffff0000, v133
	v_mul_f32_e32 v0, 0x3fb8aa3b, v0
	v_exp_f32_e32 v17, v0
	v_lshlrev_b32_e32 v22, 16, v134
	v_and_b32_e32 v23, 0xffff0000, v134
	v_lshlrev_b32_e32 v20, 16, v135
	v_and_b32_e32 v21, 0xffff0000, v135
	v_pk_mul_f32 v[8:9], v[8:9], v[16:17]
	v_pk_fma_f32 v[4:5], v[4:5], v[16:17], v[20:21]
	v_pk_mul_f32 v[6:7], v[6:7], v[18:19]
	v_pk_fma_f32 v[2:3], v[2:3], v[18:19], v[22:23]
	s_waitcnt vmcnt(2)
	v_lshlrev_b32_e32 v0, 16, v136
	v_mul_f32_e32 v0, 0x3fb8aa3b, v0
	v_exp_f32_e32 v18, v0
	v_and_b32_e32 v0, 0xffff0000, v136
	v_mul_f32_e32 v0, 0x3fb8aa3b, v0
	v_exp_f32_e32 v19, v0
	v_lshlrev_b32_e32 v0, 16, v137
	v_mul_f32_e32 v0, 0x3fb8aa3b, v0
	v_exp_f32_e32 v16, v0
	v_and_b32_e32 v0, 0xffff0000, v137
	v_mul_f32_e32 v0, 0x3fb8aa3b, v0
	v_exp_f32_e32 v17, v0
	v_lshlrev_b32_e32 v22, 16, v138
	v_and_b32_e32 v23, 0xffff0000, v138
	v_lshlrev_b32_e32 v20, 16, v139
	v_and_b32_e32 v21, 0xffff0000, v139
	v_pk_mul_f32 v[8:9], v[8:9], v[16:17]
	v_pk_fma_f32 v[4:5], v[4:5], v[16:17], v[20:21]
	v_pk_mul_f32 v[6:7], v[6:7], v[18:19]
	v_pk_fma_f32 v[2:3], v[2:3], v[18:19], v[22:23]
	s_waitcnt vmcnt(0)
	v_lshlrev_b32_e32 v0, 16, v140
	v_mul_f32_e32 v0, 0x3fb8aa3b, v0
	v_exp_f32_e32 v18, v0
	v_and_b32_e32 v0, 0xffff0000, v140
	v_mul_f32_e32 v0, 0x3fb8aa3b, v0
	v_exp_f32_e32 v19, v0
	v_lshlrev_b32_e32 v0, 16, v141
	v_mul_f32_e32 v0, 0x3fb8aa3b, v0
	v_exp_f32_e32 v16, v0
	v_and_b32_e32 v0, 0xffff0000, v141
	v_mul_f32_e32 v0, 0x3fb8aa3b, v0
	v_exp_f32_e32 v17, v0
	v_lshlrev_b32_e32 v22, 16, v142
	v_and_b32_e32 v23, 0xffff0000, v142
	v_lshlrev_b32_e32 v20, 16, v143
	v_and_b32_e32 v21, 0xffff0000, v143
	v_pk_mul_f32 v[8:9], v[8:9], v[16:17]
	v_pk_fma_f32 v[4:5], v[4:5], v[16:17], v[20:21]
	v_pk_mul_f32 v[6:7], v[6:7], v[18:19]
	v_pk_fma_f32 v[2:3], v[2:3], v[18:19], v[22:23]
	s_cbranch_scc0 .LBB0_1526
	s_lshl_b32 s8, s2, 8
	s_and_b32 s8, s8, 0x700
	s_lshl_b64 s[6:7], s[6:7], 13
	v_or_b32_e32 v0, s8, v14
	s_add_u32 s8, s10, s6
	s_addc_u32 s9, s11, s7
	s_add_u32 s6, s12, s6
	s_addc_u32 s7, s13, s7
	s_add_i32 s2, s2, s26
	s_add_i32 s14, s14, s35
	v_lshlrev_b32_e32 v0, 2, v0
	s_cmpk_gt_i32 s2, 0x3ff
	global_store_dwordx4 v0, v[6:9], s[8:9]
	global_store_dwordx4 v0, v[2:5], s[6:7]
	s_cbranch_scc0 .LBB0_1525

; __device__ __forceinline__ void phase_scan_fix(KArgs a, int gw, int NGW, int lane) {
;     ...
;             for (int p = 0; p < ch; ++p) { const f32x4 av = *(const f32x4*)(SA + (size_t)(b * 32 + p) * DM + c), hv = *(const f32x4*)(SH + (size_t)(b * 32 + p) * DM + c); h = av * h + hv; }
.LBB0_1588:
	s_mov_b64 s[18:19], 0x2000
	v_add_co_u32_e32 v80, vcc, 0xfff00000, v8
	v_mov_b32_e32 v64, v8
	v_mov_b32_e32 v65, v9
	v_addc_co_u32_e32 v81, vcc, -1, v9, vcc
	v_lshl_add_u64 v[66:67], v[64:65], 0, s[18:19]
	v_lshl_add_u64 v[82:83], v[80:81], 0, s[18:19]
	v_lshl_add_u64 v[68:69], v[66:67], 0, s[18:19]
	v_lshl_add_u64 v[84:85], v[82:83], 0, s[18:19]
	v_lshl_add_u64 v[70:71], v[68:69], 0, s[18:19]
	v_lshl_add_u64 v[86:87], v[84:85], 0, s[18:19]
	v_lshl_add_u64 v[72:73], v[70:71], 0, s[18:19]
	v_lshl_add_u64 v[88:89], v[86:87], 0, s[18:19]
	v_lshl_add_u64 v[74:75], v[72:73], 0, s[18:19]
	v_lshl_add_u64 v[90:91], v[88:89], 0, s[18:19]
	v_lshl_add_u64 v[76:77], v[74:75], 0, s[18:19]
	v_lshl_add_u64 v[92:93], v[90:91], 0, s[18:19]
	v_lshl_add_u64 v[78:79], v[76:77], 0, s[18:19]
	v_lshl_add_u64 v[94:95], v[92:93], 0, s[18:19]
	global_load_dwordx4 v[96:99], v[80:81], off
	global_load_dwordx4 v[100:103], v[64:65], off
	global_load_dwordx4 v[104:107], v[82:83], off
	global_load_dwordx4 v[108:111], v[66:67], off
	global_load_dwordx4 v[112:115], v[84:85], off
	global_load_dwordx4 v[116:119], v[68:69], off
	global_load_dwordx4 v[120:123], v[86:87], off
	global_load_dwordx4 v[124:127], v[70:71], off
	global_load_dwordx4 v[128:131], v[88:89], off
	global_load_dwordx4 v[132:135], v[72:73], off
	global_load_dwordx4 v[136:139], v[90:91], off
	global_load_dwordx4 v[140:143], v[74:75], off
	global_load_dwordx4 v[144:147], v[92:93], off
	global_load_dwordx4 v[148:151], v[76:77], off
	global_load_dwordx4 v[152:155], v[94:95], off
	global_load_dwordx4 v[156:159], v[78:79], off
	v_lshl_add_u64 v[8:9], v[78:79], 0, s[18:19]
	s_waitcnt vmcnt(14)
	v_pk_fma_f32 v[4:5], v[4:5], v[98:99], v[102:103]
	v_pk_fma_f32 v[2:3], v[2:3], v[96:97], v[100:101]
	s_add_i32 s17, s17, -1
	s_cmp_eq_u32 s17, 0
	s_cbranch_scc1 .Lsfp_done
	s_waitcnt vmcnt(12)
	v_pk_fma_f32 v[4:5], v[4:5], v[106:107], v[110:111]
	v_pk_fma_f32 v[2:3], v[2:3], v[104:105], v[108:109]
	s_add_i32 s17, s17, -1
	s_cmp_eq_u32 s17, 0
	s_cbranch_scc1 .Lsfp_done
	s_waitcnt vmcnt(10)
	v_pk_fma_f32 v[4:5], v[4:5], v[114:115], v[118:119]
	v_pk_fma_f32 v[2:3], v[2:3], v[112:113], v[116:117]
	s_add_i32 s17, s17, -1
	s_cmp_eq_u32 s17, 0
	s_cbranch_scc1 .Lsfp_done
	s_waitcnt vmcnt(8)
	v_pk_fma_f32 v[4:5], v[4:5], v[122:123], v[126:127]
	v_pk_fma_f32 v[2:3], v[2:3], v[120:121], v[124:125]
	s_add_i32 s17, s17, -1
	s_cmp_eq_u32 s17, 0
	s_cbranch_scc1 .Lsfp_done
	s_waitcnt vmcnt(6)
	v_pk_fma_f32 v[4:5], v[4:5], v[130:131], v[134:135]
	v_pk_fma_f32 v[2:3], v[2:3], v[128:129], v[132:133]
	s_add_i32 s17, s17, -1
	s_cmp_eq_u32 s17, 0
	s_cbranch_scc1 .Lsfp_done
	s_waitcnt vmcnt(4)
	v_pk_fma_f32 v[4:5], v[4:5], v[138:139], v[142:143]
	v_pk_fma_f32 v[2:3], v[2:3], v[136:137], v[140:141]
	s_add_i32 s17, s17, -1
	s_cmp_eq_u32 s17, 0
	s_cbranch_scc1 .Lsfp_done
	s_waitcnt vmcnt(2)
	v_pk_fma_f32 v[4:5], v[4:5], v[146:147], v[150:151]
	v_pk_fma_f32 v[2:3], v[2:3], v[144:145], v[148:149]
	s_add_i32 s17, s17, -1
	s_cmp_eq_u32 s17, 0
	s_cbranch_scc1 .Lsfp_done
	s_waitcnt vmcnt(0)
	v_pk_fma_f32 v[4:5], v[4:5], v[154:155], v[158:159]
	v_pk_fma_f32 v[2:3], v[2:3], v[152:153], v[156:157]
	s_add_i32 s17, s17, -1
	s_cmp_eq_u32 s17, 0
	s_cbranch_scc0 .LBB0_1588
.Lsfp_done:
	s_branch .LBB0_1591
.LBB0_1590:
	v_mov_b32_e32 v2, v1
	v_mov_b32_e32 v3, v1
	v_mov_b32_e32 v0, v1
	v_mov_b64_e32 v[4:5], v[2:3]
	v_mov_b64_e32 v[2:3], v[0:1]

; __device__ __forceinline__ void rows_rstd(const float* SS, const Unit& u, int wr, int fr, int fq, float (&rs)[2][4]) {
;     if (u.pm < 32) { const float* RSTD = (const float*)((const char*)SS + SS_TO_RSTD);
; #pragma unroll
;         for (int ai = 0; ai < 2; ++ai)
; #pragma unroll
;             for (int m = 0; m < 4; ++m) rs[ai][m] = RSTD[u.pm * BM + ai * HALF + wr * 64 + m * 16 + fr];
;     } else {
; #pragma unroll
;         for (int ai = 0; ai < 2; ++ai)
; #pragma unroll
;             for (int m = 0; m < 4; ++m) {
;                 const int row = u.pm * BM + ai * HALF + wr * 64 + m * 16 + fr; float s = 0.f;
; #pragma unroll
;                 for (int j = 0; j < 8; ++j) s += SS[(size_t)(fq * 8 + j) * MPAD + row];
;                 s += __shfl_xor(s, 16); s += __shfl_xor(s, 32);
;                 rs[ai][m] = 1.0f / sqrtf(s * (1.0f / 2048.0f) + RMS_EPS);
;             }
.LBB0_1852:
	s_lshl_b32 s6, s76, 8
	v_mov_b32_e32 v140, v159
	v_mov_b32_e32 v141, v161
	s_add_i32 s6, s6, s71
	s_cmp_lt_i32 s76, 32
	v_add_u32_e32 v156, s6, v141
	v_lshlrev_b32_e32 v154, 3, v140
	v_add_u32_e32 v152, 16, v156
	v_add_u32_e32 v150, 32, v156
	v_add_u32_e32 v148, 48, v156
	v_add_u32_e32 v146, 0x80, v156
	v_add_u32_e32 v144, 0x90, v156
	v_add_u32_e32 v142, 0xa0, v156
	s_mov_b64 s[6:7], -1
	v_ashrrev_i32_e32 v157, 31, v156
	v_ashrrev_i32_e32 v155, 31, v154
	v_ashrrev_i32_e32 v153, 31, v152
	v_ashrrev_i32_e32 v151, 31, v150
	v_ashrrev_i32_e32 v149, 31, v148
	v_ashrrev_i32_e32 v147, 31, v146
	v_ashrrev_i32_e32 v145, 31, v144
	v_ashrrev_i32_e32 v143, 31, v142
	v_add_u32_e32 v140, 0xb0, v156
	s_cbranch_scc1 .LBB0_1854
	v_and_b32_e32 v158, 64, v219
	v_xor_b32_e32 v141, 16, v219
	v_add_u32_e32 v158, 64, v158
	v_cmp_lt_i32_e32 vcc, v141, v158
	v_lshl_add_u64 v[194:195], v[156:157], 2, s[14:15]
	v_mad_i64_i32 v[170:171], s[6:7], v154, s46, v[194:195]
	v_cndmask_b32_e32 v141, v219, v141, vcc
	v_lshlrev_b32_e32 v169, 2, v141
	v_xor_b32_e32 v141, 32, v219
	v_cmp_lt_i32_e32 vcc, v141, v158
	s_nop 1
	v_cndmask_b32_e32 v141, v219, v141, vcc
	v_lshlrev_b32_e32 v167, 2, v141
	global_load_dword v208, v[170:171], off
	v_or_b32_e32 v171, 1, v154
	v_mad_i64_i32 v[172:173], s[6:7], v171, s46, v[194:195]
	global_load_dword v209, v[172:173], off
	v_or_b32_e32 v172, 2, v154
	v_mad_i64_i32 v[174:175], s[6:7], v172, s46, v[194:195]
	v_or_b32_e32 v173, 3, v154
	global_load_dword v210, v[174:175], off
	v_mad_i64_i32 v[174:175], s[6:7], v173, s46, v[194:195]
	global_load_dword v211, v[174:175], off
	v_or_b32_e32 v174, 4, v154
	v_mad_i64_i32 v[176:177], s[6:7], v174, s46, v[194:195]
	v_or_b32_e32 v175, 5, v154
	global_load_dword v212, v[176:177], off
	v_mad_i64_i32 v[176:177], s[6:7], v175, s46, v[194:195]
	global_load_dword v213, v[176:177], off
	v_or_b32_e32 v176, 6, v154
	v_mad_i64_i32 v[196:197], s[6:7], v176, s46, v[194:195]
	v_or_b32_e32 v177, 7, v154
	v_mad_i64_i32 v[194:195], s[6:7], v177, s46, v[194:195]
	global_load_dword v214, v[196:197], off
	global_load_dword v215, v[194:195], off
	v_lshl_add_u64 v[194:195], v[152:153], 2, s[14:15]
	s_waitcnt vmcnt(0)
	v_add_f32_e32 v141, 0, v208
	v_add_f32_e32 v141, v141, v209
	v_add_f32_e32 v141, v141, v210
	v_add_f32_e32 v141, v141, v211
	v_add_f32_e32 v141, v141, v212
	v_add_f32_e32 v141, v141, v213
	v_add_f32_e32 v141, v141, v214
	v_add_f32_e32 v141, v141, v215
	ds_bpermute_b32 v158, v169, v141
	s_waitcnt lgkmcnt(0)
	v_add_f32_e32 v141, v141, v158
	ds_bpermute_b32 v158, v167, v141
	s_waitcnt lgkmcnt(0)
	v_add_f32_e32 v141, v141, v158
	v_fmamk_f32 v141, v141, 0x3a000000, v220
	v_cmp_gt_f32_e32 vcc, s43, v141
	v_mul_f32_e32 v158, 0x4f800000, v141
	s_nop 0
	v_cndmask_b32_e32 v141, v141, v158, vcc
	v_sqrt_f32_e32 v158, v141
	s_nop 0
	v_add_u32_e32 v160, -1, v158
	v_fma_f32 v162, -v160, v158, v141
	v_cmp_ge_f32_e64 s[6:7], 0, v162
	v_add_u32_e32 v162, 1, v158
	s_nop 0
	v_cndmask_b32_e64 v160, v158, v160, s[6:7]
	v_fma_f32 v158, -v162, v158, v141
	v_cmp_lt_f32_e64 s[6:7], 0, v158
	s_nop 1
	v_cndmask_b32_e64 v158, v160, v162, s[6:7]
	v_mul_f32_e32 v160, 0x37800000, v158
	v_cndmask_b32_e32 v158, v158, v160, vcc
	v_cmp_class_f32_e32 vcc, v141, v221
	v_mad_i64_i32 v[196:197], s[6:7], v154, s46, v[194:195]
	s_nop 0
	v_cndmask_b32_e32 v141, v158, v141, vcc
	v_div_scale_f32 v158, s[6:7], v141, v141, 1.0
	v_rcp_f32_e32 v160, v158
	s_nop 0
	v_fma_f32 v162, -v158, v160, 1.0
	v_fmac_f32_e32 v160, v162, v160
	v_div_scale_f32 v162, vcc, 1.0, v141, 1.0
	v_mul_f32_e32 v164, v162, v160
	v_fma_f32 v166, -v158, v164, v162
	v_fmac_f32_e32 v164, v166, v160
	v_fma_f32 v158, -v158, v164, v162
	v_div_fmas_f32 v158, v158, v160, v164
	v_div_fixup_f32 v158, v158, v141, 1.0
	global_load_dword v208, v[196:197], off
	v_mad_i64_i32 v[196:197], s[6:7], v171, s46, v[194:195]
	global_load_dword v209, v[196:197], off
	v_mad_i64_i32 v[196:197], s[6:7], v172, s46, v[194:195]
	global_load_dword v210, v[196:197], off
	v_mad_i64_i32 v[196:197], s[6:7], v173, s46, v[194:195]
	global_load_dword v211, v[196:197], off
	v_mad_i64_i32 v[196:197], s[6:7], v174, s46, v[194:195]
	global_load_dword v212, v[196:197], off
	v_mad_i64_i32 v[196:197], s[6:7], v175, s46, v[194:195]
	global_load_dword v213, v[196:197], off
	v_mad_i64_i32 v[196:197], s[6:7], v176, s46, v[194:195]
	v_mad_i64_i32 v[194:195], s[6:7], v177, s46, v[194:195]
	global_load_dword v214, v[196:197], off
	global_load_dword v215, v[194:195], off
	v_lshl_add_u64 v[194:195], v[150:151], 2, s[14:15]
	s_waitcnt vmcnt(0)
	v_add_f32_e32 v141, 0, v208
	v_add_f32_e32 v141, v141, v209
	v_add_f32_e32 v141, v141, v210
	v_add_f32_e32 v141, v141, v211
	v_add_f32_e32 v141, v141, v212
	v_add_f32_e32 v141, v141, v213
	v_add_f32_e32 v141, v141, v214
	v_add_f32_e32 v141, v141, v215
	ds_bpermute_b32 v160, v169, v141
	s_waitcnt lgkmcnt(0)
	v_add_f32_e32 v141, v141, v160
	ds_bpermute_b32 v160, v167, v141
	s_waitcnt lgkmcnt(0)
; __device__ __forceinline__ void rows_rstd(const float* SS, const Unit& u, int wr, int fr, int fq, float (&rs)[2][4]) {
;     if (u.pm < 32) { const float* RSTD = (const float*)((const char*)SS + SS_TO_RSTD);
; #pragma unroll
;         for (int ai = 0; ai < 2; ++ai)
; #pragma unroll
;             for (int m = 0; m < 4; ++m) rs[ai][m] = RSTD[u.pm * BM + ai * HALF + wr * 64 + m * 16 + fr];
;     } else {
; #pragma unroll
;         for (int ai = 0; ai < 2; ++ai)
; #pragma unroll
;             for (int m = 0; m < 4; ++m) {
;                 const int row = u.pm * BM + ai * HALF + wr * 64 + m * 16 + fr; float s = 0.f;
; #pragma unroll
;                 for (int j = 0; j < 8; ++j) s += SS[(size_t)(fq * 8 + j) * MPAD + row];
;                 s += __shfl_xor(s, 16); s += __shfl_xor(s, 32);
;                 rs[ai][m] = 1.0f / sqrtf(s * (1.0f / 2048.0f) + RMS_EPS);
;             }
	v_add_f32_e32 v141, v141, v160
	v_fmamk_f32 v141, v141, 0x3a000000, v220
	v_cmp_gt_f32_e32 vcc, s43, v141
	v_mul_f32_e32 v160, 0x4f800000, v141
	s_nop 0
	v_cndmask_b32_e32 v141, v141, v160, vcc
	v_sqrt_f32_e32 v160, v141
	s_nop 0
	v_add_u32_e32 v162, -1, v160
	v_fma_f32 v164, -v162, v160, v141
	v_cmp_ge_f32_e64 s[6:7], 0, v164
	v_add_u32_e32 v164, 1, v160
	s_nop 0
	v_cndmask_b32_e64 v162, v160, v162, s[6:7]
	v_fma_f32 v160, -v164, v160, v141
	v_cmp_lt_f32_e64 s[6:7], 0, v160
	s_nop 1
	v_cndmask_b32_e64 v160, v162, v164, s[6:7]
	v_mul_f32_e32 v162, 0x37800000, v160
	v_cndmask_b32_e32 v160, v160, v162, vcc
	v_cmp_class_f32_e32 vcc, v141, v221
	v_mad_i64_i32 v[196:197], s[6:7], v154, s46, v[194:195]
	s_nop 0
	v_cndmask_b32_e32 v141, v160, v141, vcc
	v_div_scale_f32 v160, s[6:7], v141, v141, 1.0
	v_rcp_f32_e32 v162, v160
	s_nop 0
	v_fma_f32 v164, -v160, v162, 1.0
	v_fmac_f32_e32 v162, v164, v162
	v_div_scale_f32 v164, vcc, 1.0, v141, 1.0
	v_mul_f32_e32 v166, v164, v162
	v_fma_f32 v168, -v160, v166, v164
	v_fmac_f32_e32 v166, v168, v162
	v_fma_f32 v160, -v160, v166, v164
	v_div_fmas_f32 v160, v160, v162, v166
	v_div_fixup_f32 v160, v160, v141, 1.0
	global_load_dword v208, v[196:197], off
	v_mad_i64_i32 v[196:197], s[6:7], v171, s46, v[194:195]
	global_load_dword v209, v[196:197], off
	v_mad_i64_i32 v[196:197], s[6:7], v172, s46, v[194:195]
	global_load_dword v210, v[196:197], off
	v_mad_i64_i32 v[196:197], s[6:7], v173, s46, v[194:195]
	global_load_dword v211, v[196:197], off
	v_mad_i64_i32 v[196:197], s[6:7], v174, s46, v[194:195]
	global_load_dword v212, v[196:197], off
	v_mad_i64_i32 v[196:197], s[6:7], v175, s46, v[194:195]
	global_load_dword v213, v[196:197], off
	v_mad_i64_i32 v[196:197], s[6:7], v176, s46, v[194:195]
	v_mad_i64_i32 v[194:195], s[6:7], v177, s46, v[194:195]
	global_load_dword v214, v[196:197], off
	global_load_dword v215, v[194:195], off
	v_lshl_add_u64 v[194:195], v[148:149], 2, s[14:15]
	s_waitcnt vmcnt(0)
	v_add_f32_e32 v141, 0, v208
	v_add_f32_e32 v141, v141, v209
	v_add_f32_e32 v141, v141, v210
	v_add_f32_e32 v141, v141, v211
	v_add_f32_e32 v141, v141, v212
	v_add_f32_e32 v141, v141, v213
	v_add_f32_e32 v141, v141, v214
	v_add_f32_e32 v141, v141, v215
	ds_bpermute_b32 v162, v169, v141
	s_waitcnt lgkmcnt(0)
	v_add_f32_e32 v141, v141, v162
	ds_bpermute_b32 v162, v167, v141
	s_waitcnt lgkmcnt(0)
	v_add_f32_e32 v141, v141, v162
	v_fmamk_f32 v141, v141, 0x3a000000, v220
	v_cmp_gt_f32_e32 vcc, s43, v141
	v_mul_f32_e32 v162, 0x4f800000, v141
	s_nop 0
	v_cndmask_b32_e32 v141, v141, v162, vcc
	v_sqrt_f32_e32 v162, v141
	s_nop 0
	v_add_u32_e32 v164, -1, v162
	v_fma_f32 v166, -v164, v162, v141
	v_cmp_ge_f32_e64 s[6:7], 0, v166
	v_add_u32_e32 v166, 1, v162
	s_nop 0
	v_cndmask_b32_e64 v164, v162, v164, s[6:7]
	v_fma_f32 v162, -v166, v162, v141
	v_cmp_lt_f32_e64 s[6:7], 0, v162
	s_nop 1
	v_cndmask_b32_e64 v162, v164, v166, s[6:7]
	v_mul_f32_e32 v164, 0x37800000, v162
	v_cndmask_b32_e32 v162, v162, v164, vcc
	v_cmp_class_f32_e32 vcc, v141, v221
	v_mad_i64_i32 v[196:197], s[6:7], v154, s46, v[194:195]
	s_nop 0
	v_cndmask_b32_e32 v141, v162, v141, vcc
	v_div_scale_f32 v162, s[6:7], v141, v141, 1.0
	v_rcp_f32_e32 v164, v162
	s_nop 0
	v_fma_f32 v166, -v162, v164, 1.0
	v_fmac_f32_e32 v164, v166, v164
	v_div_scale_f32 v166, vcc, 1.0, v141, 1.0
	v_mul_f32_e32 v168, v166, v164
	v_fma_f32 v170, -v162, v168, v166
	v_fmac_f32_e32 v168, v170, v164
	v_fma_f32 v162, -v162, v168, v166
	v_div_fmas_f32 v162, v162, v164, v168
	v_div_fixup_f32 v162, v162, v141, 1.0
	global_load_dword v208, v[196:197], off
	v_mad_i64_i32 v[196:197], s[6:7], v171, s46, v[194:195]
	global_load_dword v209, v[196:197], off
	v_mad_i64_i32 v[196:197], s[6:7], v172, s46, v[194:195]
	global_load_dword v210, v[196:197], off
	v_mad_i64_i32 v[196:197], s[6:7], v173, s46, v[194:195]
	global_load_dword v211, v[196:197], off
	v_mad_i64_i32 v[196:197], s[6:7], v174, s46, v[194:195]
	global_load_dword v212, v[196:197], off
	v_mad_i64_i32 v[196:197], s[6:7], v175, s46, v[194:195]
	global_load_dword v213, v[196:197], off
	v_mad_i64_i32 v[196:197], s[6:7], v176, s46, v[194:195]
	v_mad_i64_i32 v[194:195], s[6:7], v177, s46, v[194:195]
	global_load_dword v214, v[196:197], off
	global_load_dword v215, v[194:195], off
	v_lshl_add_u64 v[194:195], v[146:147], 2, s[14:15]
	s_waitcnt vmcnt(0)
	v_add_f32_e32 v141, 0, v208
	v_add_f32_e32 v141, v141, v209
	v_add_f32_e32 v141, v141, v210
	v_add_f32_e32 v141, v141, v211
	v_add_f32_e32 v141, v141, v212
	v_add_f32_e32 v141, v141, v213
	v_add_f32_e32 v141, v141, v214
	v_add_f32_e32 v141, v141, v215
	ds_bpermute_b32 v164, v169, v141
	s_waitcnt lgkmcnt(0)
	v_add_f32_e32 v141, v141, v164
	ds_bpermute_b32 v164, v167, v141
	s_waitcnt lgkmcnt(0)
; __device__ __forceinline__ void rows_rstd(const float* SS, const Unit& u, int wr, int fr, int fq, float (&rs)[2][4]) {
;     if (u.pm < 32) { const float* RSTD = (const float*)((const char*)SS + SS_TO_RSTD);
; #pragma unroll
;         for (int ai = 0; ai < 2; ++ai)
; #pragma unroll
;             for (int m = 0; m < 4; ++m) rs[ai][m] = RSTD[u.pm * BM + ai * HALF + wr * 64 + m * 16 + fr];
;     } else {
; #pragma unroll
;         for (int ai = 0; ai < 2; ++ai)
; #pragma unroll
;             for (int m = 0; m < 4; ++m) {
;                 const int row = u.pm * BM + ai * HALF + wr * 64 + m * 16 + fr; float s = 0.f;
; #pragma unroll
;                 for (int j = 0; j < 8; ++j) s += SS[(size_t)(fq * 8 + j) * MPAD + row];
;                 s += __shfl_xor(s, 16); s += __shfl_xor(s, 32);
;                 rs[ai][m] = 1.0f / sqrtf(s * (1.0f / 2048.0f) + RMS_EPS);
;             }
	v_add_f32_e32 v141, v141, v164
	v_fmamk_f32 v141, v141, 0x3a000000, v220
	v_cmp_gt_f32_e32 vcc, s43, v141
	v_mul_f32_e32 v164, 0x4f800000, v141
	s_nop 0
	v_cndmask_b32_e32 v141, v141, v164, vcc
	v_sqrt_f32_e32 v164, v141
	s_nop 0
	v_add_u32_e32 v166, -1, v164
	v_fma_f32 v168, -v166, v164, v141
	v_cmp_ge_f32_e64 s[6:7], 0, v168
	v_add_u32_e32 v168, 1, v164
	s_nop 0
	v_cndmask_b32_e64 v166, v164, v166, s[6:7]
	v_fma_f32 v164, -v168, v164, v141
	v_cmp_lt_f32_e64 s[6:7], 0, v164
	s_nop 1
	v_cndmask_b32_e64 v164, v166, v168, s[6:7]
	v_mul_f32_e32 v166, 0x37800000, v164
	v_cndmask_b32_e32 v164, v164, v166, vcc
	v_cmp_class_f32_e32 vcc, v141, v221
	v_mad_i64_i32 v[196:197], s[6:7], v154, s46, v[194:195]
	s_nop 0
	v_cndmask_b32_e32 v141, v164, v141, vcc
	v_div_scale_f32 v164, s[6:7], v141, v141, 1.0
	v_rcp_f32_e32 v166, v164
	s_nop 0
	v_fma_f32 v168, -v164, v166, 1.0
	v_fmac_f32_e32 v166, v168, v166
	v_div_scale_f32 v168, vcc, 1.0, v141, 1.0
	v_mul_f32_e32 v170, v168, v166
	v_fma_f32 v189, -v164, v170, v168
	v_fmac_f32_e32 v170, v189, v166
	v_fma_f32 v164, -v164, v170, v168
	v_div_fmas_f32 v164, v164, v166, v170
	v_div_fixup_f32 v164, v164, v141, 1.0
	global_load_dword v208, v[196:197], off
	v_mad_i64_i32 v[196:197], s[6:7], v171, s46, v[194:195]
	global_load_dword v209, v[196:197], off
	v_mad_i64_i32 v[196:197], s[6:7], v172, s46, v[194:195]
	global_load_dword v210, v[196:197], off
	v_mad_i64_i32 v[196:197], s[6:7], v173, s46, v[194:195]
	global_load_dword v211, v[196:197], off
	v_mad_i64_i32 v[196:197], s[6:7], v174, s46, v[194:195]
	global_load_dword v212, v[196:197], off
	v_mad_i64_i32 v[196:197], s[6:7], v175, s46, v[194:195]
	global_load_dword v213, v[196:197], off
	v_mad_i64_i32 v[196:197], s[6:7], v176, s46, v[194:195]
	v_mad_i64_i32 v[194:195], s[6:7], v177, s46, v[194:195]
	global_load_dword v214, v[196:197], off
	global_load_dword v215, v[194:195], off
	s_waitcnt vmcnt(0)
	v_add_f32_e32 v141, 0, v208
	v_add_f32_e32 v141, v141, v209
	v_add_f32_e32 v141, v141, v210
	v_add_f32_e32 v141, v141, v211
	v_add_f32_e32 v141, v141, v212
	v_add_f32_e32 v141, v141, v213
	v_add_f32_e32 v141, v141, v214
	v_add_f32_e32 v141, v141, v215
	ds_bpermute_b32 v166, v169, v141
	s_waitcnt lgkmcnt(0)
	v_add_f32_e32 v141, v141, v166
	ds_bpermute_b32 v166, v167, v141
	s_waitcnt lgkmcnt(0)
	v_add_f32_e32 v141, v141, v166
	v_fmamk_f32 v141, v141, 0x3a000000, v220
	v_cmp_gt_f32_e32 vcc, s43, v141
	v_mul_f32_e32 v166, 0x4f800000, v141
	s_nop 0
	v_cndmask_b32_e32 v141, v141, v166, vcc
	v_sqrt_f32_e32 v166, v141
	s_nop 0
	v_add_u32_e32 v168, -1, v166
	v_fma_f32 v170, -v168, v166, v141
	v_cmp_ge_f32_e64 s[6:7], 0, v170
	v_add_u32_e32 v170, 1, v166
	s_nop 0
	v_cndmask_b32_e64 v168, v166, v168, s[6:7]
	v_fma_f32 v166, -v170, v166, v141
	v_cmp_lt_f32_e64 s[6:7], 0, v166
	s_nop 1
	v_cndmask_b32_e64 v166, v168, v170, s[6:7]
	v_mul_f32_e32 v168, 0x37800000, v166
	v_cndmask_b32_e32 v166, v166, v168, vcc
	v_cmp_class_f32_e32 vcc, v141, v221
	s_nop 1
	v_cndmask_b32_e32 v141, v166, v141, vcc
	v_div_scale_f32 v166, s[6:7], v141, v141, 1.0
	v_rcp_f32_e32 v168, v166
	s_nop 0
	v_fma_f32 v170, -v166, v168, 1.0
	v_fmac_f32_e32 v168, v170, v168
	v_div_scale_f32 v170, vcc, 1.0, v141, 1.0
	v_mul_f32_e32 v189, v170, v168
	v_fma_f32 v194, -v166, v189, v170
	v_fmac_f32_e32 v189, v194, v168
	v_fma_f32 v166, -v166, v189, v170
	v_lshl_add_u64 v[194:195], v[144:145], 2, s[14:15]
	v_div_fmas_f32 v166, v166, v168, v189
	v_mad_i64_i32 v[196:197], s[6:7], v154, s46, v[194:195]
	v_div_fixup_f32 v166, v166, v141, 1.0
	global_load_dword v208, v[196:197], off
	v_mad_i64_i32 v[196:197], s[6:7], v171, s46, v[194:195]
	global_load_dword v209, v[196:197], off
	v_mad_i64_i32 v[196:197], s[6:7], v172, s46, v[194:195]
	global_load_dword v210, v[196:197], off
	v_mad_i64_i32 v[196:197], s[6:7], v173, s46, v[194:195]
	global_load_dword v211, v[196:197], off
	v_mad_i64_i32 v[196:197], s[6:7], v174, s46, v[194:195]
	global_load_dword v212, v[196:197], off
	v_mad_i64_i32 v[196:197], s[6:7], v175, s46, v[194:195]
	global_load_dword v213, v[196:197], off
	v_mad_i64_i32 v[196:197], s[6:7], v176, s46, v[194:195]
	v_mad_i64_i32 v[194:195], s[6:7], v177, s46, v[194:195]
	global_load_dword v214, v[196:197], off
	global_load_dword v215, v[194:195], off
	s_waitcnt vmcnt(0)
	v_add_f32_e32 v141, 0, v208
	v_add_f32_e32 v141, v141, v209
	v_add_f32_e32 v141, v141, v210
	v_add_f32_e32 v141, v141, v211
	v_add_f32_e32 v141, v141, v212
	v_add_f32_e32 v141, v141, v213
	v_add_f32_e32 v141, v141, v214
	v_add_f32_e32 v141, v141, v215
	ds_bpermute_b32 v168, v169, v141
	s_waitcnt lgkmcnt(0)
	v_add_f32_e32 v141, v141, v168
	ds_bpermute_b32 v168, v167, v141
	s_waitcnt lgkmcnt(0)
; __device__ __forceinline__ void rows_rstd(const float* SS, const Unit& u, int wr, int fr, int fq, float (&rs)[2][4]) {
;     if (u.pm < 32) { const float* RSTD = (const float*)((const char*)SS + SS_TO_RSTD);
; #pragma unroll
;         for (int ai = 0; ai < 2; ++ai)
; #pragma unroll
;             for (int m = 0; m < 4; ++m) rs[ai][m] = RSTD[u.pm * BM + ai * HALF + wr * 64 + m * 16 + fr];
;     } else {
; #pragma unroll
;         for (int ai = 0; ai < 2; ++ai)
; #pragma unroll
;             for (int m = 0; m < 4; ++m) {
;                 const int row = u.pm * BM + ai * HALF + wr * 64 + m * 16 + fr; float s = 0.f;
; #pragma unroll
;                 for (int j = 0; j < 8; ++j) s += SS[(size_t)(fq * 8 + j) * MPAD + row];
;                 s += __shfl_xor(s, 16); s += __shfl_xor(s, 32);
;                 rs[ai][m] = 1.0f / sqrtf(s * (1.0f / 2048.0f) + RMS_EPS);
;             }
	v_add_f32_e32 v141, v141, v168
	v_fmamk_f32 v141, v141, 0x3a000000, v220
	v_cmp_gt_f32_e32 vcc, s43, v141
	v_mul_f32_e32 v168, 0x4f800000, v141
	s_nop 0
	v_cndmask_b32_e32 v141, v141, v168, vcc
	v_sqrt_f32_e32 v168, v141
	s_nop 0
	v_add_u32_e32 v170, -1, v168
	v_fma_f32 v189, -v170, v168, v141
	v_cmp_ge_f32_e64 s[6:7], 0, v189
	v_add_u32_e32 v189, 1, v168
	s_nop 0
	v_cndmask_b32_e64 v170, v168, v170, s[6:7]
	v_fma_f32 v168, -v189, v168, v141
	v_cmp_lt_f32_e64 s[6:7], 0, v168
	s_nop 1
	v_cndmask_b32_e64 v168, v170, v189, s[6:7]
	v_mul_f32_e32 v170, 0x37800000, v168
	v_cndmask_b32_e32 v168, v168, v170, vcc
	v_cmp_class_f32_e32 vcc, v141, v221
	s_nop 1
	v_cndmask_b32_e32 v141, v168, v141, vcc
	v_div_scale_f32 v168, s[6:7], v141, v141, 1.0
	v_rcp_f32_e32 v170, v168
	s_nop 0
	v_fma_f32 v189, -v168, v170, 1.0
	v_fmac_f32_e32 v170, v189, v170
	v_div_scale_f32 v189, vcc, 1.0, v141, 1.0
	v_mul_f32_e32 v194, v189, v170
	v_fma_f32 v195, -v168, v194, v189
	v_fmac_f32_e32 v194, v195, v170
	v_fma_f32 v168, -v168, v194, v189
	v_div_fmas_f32 v168, v168, v170, v194
	v_lshl_add_u64 v[194:195], v[142:143], 2, s[14:15]
	v_mad_i64_i32 v[196:197], s[6:7], v154, s46, v[194:195]
	v_div_fixup_f32 v168, v168, v141, 1.0
	global_load_dword v208, v[196:197], off
	v_mad_i64_i32 v[196:197], s[6:7], v171, s46, v[194:195]
	global_load_dword v209, v[196:197], off
	v_mad_i64_i32 v[196:197], s[6:7], v172, s46, v[194:195]
	global_load_dword v210, v[196:197], off
	v_mad_i64_i32 v[196:197], s[6:7], v173, s46, v[194:195]
	global_load_dword v211, v[196:197], off
	v_mad_i64_i32 v[196:197], s[6:7], v174, s46, v[194:195]
	global_load_dword v212, v[196:197], off
	v_mad_i64_i32 v[196:197], s[6:7], v175, s46, v[194:195]
	global_load_dword v213, v[196:197], off
	v_mad_i64_i32 v[196:197], s[6:7], v176, s46, v[194:195]
	v_mad_i64_i32 v[194:195], s[6:7], v177, s46, v[194:195]
	global_load_dword v214, v[196:197], off
	global_load_dword v215, v[194:195], off
	s_waitcnt vmcnt(0)
	v_add_f32_e32 v141, 0, v208
	v_add_f32_e32 v141, v141, v209
	v_add_f32_e32 v141, v141, v210
	v_add_f32_e32 v141, v141, v211
	v_add_f32_e32 v141, v141, v212
	v_add_f32_e32 v141, v141, v213
	v_add_f32_e32 v141, v141, v214
	v_add_f32_e32 v141, v141, v215
	ds_bpermute_b32 v170, v169, v141
	s_waitcnt lgkmcnt(0)
	v_add_f32_e32 v141, v141, v170
	ds_bpermute_b32 v170, v167, v141
	s_waitcnt lgkmcnt(0)
	v_add_f32_e32 v141, v141, v170
	v_fmamk_f32 v141, v141, 0x3a000000, v220
	v_cmp_gt_f32_e32 vcc, s43, v141
	v_mul_f32_e32 v170, 0x4f800000, v141
	s_nop 0
	v_cndmask_b32_e32 v141, v141, v170, vcc
	v_sqrt_f32_e32 v170, v141
	s_nop 0
	v_add_u32_e32 v189, -1, v170
	v_fma_f32 v194, -v189, v170, v141
	v_cmp_ge_f32_e64 s[6:7], 0, v194
	v_add_u32_e32 v194, 1, v170
	s_nop 0
	v_cndmask_b32_e64 v189, v170, v189, s[6:7]
	v_fma_f32 v170, -v194, v170, v141
	v_cmp_lt_f32_e64 s[6:7], 0, v170
	s_nop 1
	v_cndmask_b32_e64 v170, v189, v194, s[6:7]
	v_mul_f32_e32 v189, 0x37800000, v170
	v_cndmask_b32_e32 v170, v170, v189, vcc
	v_cmp_class_f32_e32 vcc, v141, v221
	s_nop 1
	v_cndmask_b32_e32 v141, v170, v141, vcc
	v_div_scale_f32 v170, s[6:7], v141, v141, 1.0
	v_rcp_f32_e32 v189, v170
	s_nop 0
	v_fma_f32 v194, -v170, v189, 1.0
	v_fmac_f32_e32 v189, v194, v189
	v_div_scale_f32 v194, vcc, 1.0, v141, 1.0
	v_mul_f32_e32 v195, v194, v189
	v_fma_f32 v196, -v170, v195, v194
	v_fmac_f32_e32 v195, v196, v189
	v_fma_f32 v170, -v170, v195, v194
	v_div_fmas_f32 v170, v170, v189, v195
	v_div_fixup_f32 v170, v170, v141, 1.0
	v_ashrrev_i32_e32 v141, 31, v140
	v_lshl_add_u64 v[194:195], v[140:141], 2, s[14:15]
	v_mad_i64_i32 v[196:197], s[6:7], v154, s46, v[194:195]
	global_load_dword v208, v[196:197], off
	v_mad_i64_i32 v[196:197], s[6:7], v171, s46, v[194:195]
	global_load_dword v209, v[196:197], off
	v_mad_i64_i32 v[196:197], s[6:7], v172, s46, v[194:195]
	global_load_dword v210, v[196:197], off
	v_mad_i64_i32 v[172:173], s[6:7], v173, s46, v[194:195]
	global_load_dword v211, v[172:173], off
	v_mad_i64_i32 v[172:173], s[6:7], v174, s46, v[194:195]
	global_load_dword v212, v[172:173], off
	v_mad_i64_i32 v[172:173], s[6:7], v175, s46, v[194:195]
	global_load_dword v213, v[172:173], off
	v_mad_i64_i32 v[172:173], s[6:7], v176, s46, v[194:195]
	global_load_dword v214, v[172:173], off
	v_mad_i64_i32 v[172:173], s[6:7], v177, s46, v[194:195]
	global_load_dword v215, v[172:173], off
	s_waitcnt vmcnt(0)
	v_add_f32_e32 v189, 0, v208
	v_add_f32_e32 v171, v189, v209
	v_add_f32_e32 v171, v171, v210
	v_add_f32_e32 v171, v171, v211
	v_add_f32_e32 v171, v171, v212
	v_add_f32_e32 v171, v171, v213
	v_add_f32_e32 v171, v171, v214
	v_add_f32_e32 v171, v171, v215
	ds_bpermute_b32 v169, v169, v171
	s_waitcnt lgkmcnt(0)
	v_add_f32_e32 v169, v171, v169
	ds_bpermute_b32 v167, v167, v169
	s_waitcnt lgkmcnt(0)
	v_add_f32_e32 v167, v169, v167
	v_fmamk_f32 v167, v167, 0x3a000000, v220
	v_cmp_gt_f32_e32 vcc, s43, v167
	v_mul_f32_e32 v169, 0x4f800000, v167
	s_nop 0
	v_cndmask_b32_e32 v167, v167, v169, vcc
	v_sqrt_f32_e32 v169, v167
	s_nop 0
	v_add_u32_e32 v171, -1, v169
	v_fma_f32 v172, -v171, v169, v167
	v_cmp_ge_f32_e64 s[6:7], 0, v172
	v_add_u32_e32 v172, 1, v169
	s_nop 0
	v_cndmask_b32_e64 v171, v169, v171, s[6:7]
	v_fma_f32 v169, -v172, v169, v167
	v_cmp_lt_f32_e64 s[6:7], 0, v169
	s_nop 1
	v_cndmask_b32_e64 v169, v171, v172, s[6:7]
	v_mul_f32_e32 v171, 0x37800000, v169
	v_cndmask_b32_e32 v169, v169, v171, vcc
	v_cmp_class_f32_e32 vcc, v167, v221
	s_nop 1
	v_cndmask_b32_e32 v167, v169, v167, vcc
	v_div_scale_f32 v169, s[6:7], v167, v167, 1.0
	v_rcp_f32_e32 v171, v169
	s_mov_b64 s[6:7], 0
	v_fma_f32 v172, -v169, v171, 1.0
	v_fmac_f32_e32 v171, v172, v171
	v_div_scale_f32 v172, vcc, 1.0, v167, 1.0
	v_mul_f32_e32 v173, v172, v171
	v_fma_f32 v174, -v169, v173, v172
	v_fmac_f32_e32 v173, v174, v171
	v_fma_f32 v169, -v169, v173, v172
	v_div_fmas_f32 v169, v169, v171, v173
	v_div_fixup_f32 v172, v169, v167, 1.0

; __device__ __forceinline__ void phase_final(KArgs a, int gw, int NGW, int lane) {
;     ...
;     for (int r = gw; r < MREAL; r += NGW) {
;         float s = lane < 32 ? SS[(size_t)lane * MPAD + r] : 0.f; s = wave_sum(s);
;         const float rs = 1.0f / sqrtf(s * (1.0f / 2048.0f) + RMS_EPS);
;         const float* X = (const float*)(a->ws + WS_X) + (size_t)r * DM; float* o = a->out + OUT_Y + (size_t)r * DM;
; #pragma unroll
;         for (int j = 0; j < 8; ++j) { const int c = j * 256 + lane * 4; const f32x4 v = *(const f32x4*)(X + c), gg = *(const f32x4*)(g + c); *(f32x4*)(o + c) = v * rs * gg; }
;     }
.LBB0_2111:
	s_or_b64 exec, exec, s[2:3]
	v_lshl_add_u64 v[32:33], s[12:13], 0, v[0:1]
	v_add_co_u32_e32 v34, vcc, s16, v32
	s_nop 1
	v_addc_co_u32_e32 v35, vcc, 0, v33, vcc
	v_add_co_u32_e32 v32, vcc, s15, v32
	s_nop 1
	v_addc_co_u32_e32 v33, vcc, 0, v33, vcc
	global_load_dwordx4 v[96:99], v[34:35], off offset:-4096
	global_load_dwordx4 v[100:103], v[2:3], off
	global_load_dwordx4 v[104:107], v[32:33], off offset:1024
	global_load_dwordx4 v[108:111], v[2:3], off offset:1024
	global_load_dwordx4 v[112:115], v[32:33], off offset:2048
	global_load_dwordx4 v[116:119], v[2:3], off offset:2048
	global_load_dwordx4 v[120:123], v[32:33], off offset:3072
	global_load_dwordx4 v[124:127], v[2:3], off offset:3072
	global_load_dwordx4 v[128:131], v[34:35], off
	global_load_dwordx4 v[132:135], v[4:5], off
	global_load_dwordx4 v[136:139], v[34:35], off offset:1024
	global_load_dwordx4 v[140:143], v[6:7], off
	global_load_dwordx4 v[144:147], v[34:35], off offset:2048
	global_load_dwordx4 v[148:151], v[8:9], off
	global_load_dwordx4 v[152:155], v[34:35], off offset:3072
	global_load_dwordx4 v[156:159], v[10:11], off
	s_waitcnt vmcnt(16)
	ds_bpermute_b32 v23, v14, v22
	v_lshl_add_u64 v[36:37], s[6:7], 0, v[0:1]
	s_waitcnt lgkmcnt(0)
	v_add_f32_e32 v22, v22, v23
	ds_bpermute_b32 v23, v15, v22
	s_add_i32 s8, s8, s26
	s_add_u32 s6, s6, s10
	s_addc_u32 s7, s7, s11
	s_add_u32 s12, s12, s10
	s_waitcnt lgkmcnt(0)
	v_add_f32_e32 v22, v22, v23
	ds_bpermute_b32 v23, v16, v22
	s_addc_u32 s13, s13, s11
	s_cmpk_lt_i32 s8, 0x2080
	v_lshl_add_u64 v[12:13], v[12:13], 0, s[4:5]
	s_waitcnt lgkmcnt(0)
	v_add_f32_e32 v22, v22, v23
	ds_bpermute_b32 v23, v17, v22
	s_waitcnt lgkmcnt(0)
	v_add_f32_e32 v22, v22, v23
	ds_bpermute_b32 v23, v18, v22
	s_waitcnt lgkmcnt(0)
	v_add_f32_e32 v22, v22, v23
	ds_bpermute_b32 v23, v19, v22
	s_waitcnt lgkmcnt(0)
	v_add_f32_e32 v22, v22, v23
	v_fmamk_f32 v22, v22, 0x3a000000, v20
	v_mul_f32_e32 v23, 0x4f800000, v22
	v_cmp_gt_f32_e32 vcc, s9, v22
	s_nop 1
	v_cndmask_b32_e32 v22, v22, v23, vcc
	v_sqrt_f32_e32 v23, v22
	s_nop 0
	v_add_u32_e32 v38, -1, v23
	v_add_u32_e32 v39, 1, v23
	v_fma_f32 v40, -v38, v23, v22
	v_fma_f32 v41, -v39, v23, v22
	v_cmp_ge_f32_e64 s[2:3], 0, v40
	s_nop 1
	v_cndmask_b32_e64 v23, v23, v38, s[2:3]
	v_cmp_lt_f32_e64 s[2:3], 0, v41
	s_nop 1
	v_cndmask_b32_e64 v23, v23, v39, s[2:3]
	v_mul_f32_e32 v38, 0x37800000, v23
	v_cndmask_b32_e32 v23, v23, v38, vcc
	v_cmp_class_f32_e32 vcc, v22, v21
	s_nop 1
	v_cndmask_b32_e32 v22, v23, v22, vcc
	v_div_scale_f32 v23, s[2:3], v22, v22, 1.0
	v_rcp_f32_e32 v38, v23
	s_nop 0
	v_fma_f32 v40, -v23, v38, 1.0
	v_div_scale_f32 v39, vcc, 1.0, v22, 1.0
	v_fmac_f32_e32 v38, v40, v38
	v_mul_f32_e32 v40, v39, v38
	v_fma_f32 v41, -v23, v40, v39
	v_fmac_f32_e32 v40, v41, v38
	v_fma_f32 v23, -v23, v40, v39
	v_div_fmas_f32 v23, v23, v38, v40
	v_div_fixup_f32 v38, v23, v22, 1.0
	v_add_co_u32_e32 v30, vcc, s14, v36
	s_nop 1
	v_addc_co_u32_e32 v31, vcc, 0, v37, vcc
	s_waitcnt vmcnt(14)
	v_pk_mul_f32 v[22:23], v[96:97], v[38:39] op_sel_hi:[1,0]
	v_pk_mul_f32 v[24:25], v[98:99], v[38:39] op_sel_hi:[1,0]
	v_pk_mul_f32 v[22:23], v[100:101], v[22:23]
	v_pk_mul_f32 v[24:25], v[102:103], v[24:25]
	global_store_dwordx4 v[36:37], v[22:25], off
	s_waitcnt vmcnt(13)
	v_pk_mul_f32 v[26:27], v[104:105], v[38:39] op_sel_hi:[1,0]
	v_pk_mul_f32 v[28:29], v[106:107], v[38:39] op_sel_hi:[1,0]
	v_pk_mul_f32 v[26:27], v[108:109], v[26:27]
	v_pk_mul_f32 v[28:29], v[110:111], v[28:29]
	global_store_dwordx4 v[36:37], v[26:29], off offset:1024
	s_waitcnt vmcnt(12)
	v_pk_mul_f32 v[22:23], v[112:113], v[38:39] op_sel_hi:[1,0]
	v_pk_mul_f32 v[24:25], v[114:115], v[38:39] op_sel_hi:[1,0]
	v_pk_mul_f32 v[22:23], v[116:117], v[22:23]
	v_pk_mul_f32 v[24:25], v[118:119], v[24:25]
	global_store_dwordx4 v[36:37], v[22:25], off offset:2048
	s_waitcnt vmcnt(11)
	v_pk_mul_f32 v[26:27], v[120:121], v[38:39] op_sel_hi:[1,0]
	v_pk_mul_f32 v[28:29], v[122:123], v[38:39] op_sel_hi:[1,0]
	v_pk_mul_f32 v[26:27], v[124:125], v[26:27]
	v_pk_mul_f32 v[28:29], v[126:127], v[28:29]
	global_store_dwordx4 v[36:37], v[26:29], off offset:3072
	s_waitcnt vmcnt(10)
	v_pk_mul_f32 v[22:23], v[128:129], v[38:39] op_sel_hi:[1,0]
	v_pk_mul_f32 v[24:25], v[130:131], v[38:39] op_sel_hi:[1,0]
	v_pk_mul_f32 v[22:23], v[132:133], v[22:23]
	v_pk_mul_f32 v[24:25], v[134:135], v[24:25]
	global_store_dwordx4 v[30:31], v[22:25], off
	s_waitcnt vmcnt(9)
	v_pk_mul_f32 v[26:27], v[136:137], v[38:39] op_sel_hi:[1,0]
	v_pk_mul_f32 v[28:29], v[138:139], v[38:39] op_sel_hi:[1,0]
	v_pk_mul_f32 v[26:27], v[140:141], v[26:27]
	v_pk_mul_f32 v[28:29], v[142:143], v[28:29]
	global_store_dwordx4 v[30:31], v[26:29], off offset:1024
	s_waitcnt vmcnt(8)
	v_pk_mul_f32 v[22:23], v[144:145], v[38:39] op_sel_hi:[1,0]
	v_pk_mul_f32 v[24:25], v[146:147], v[38:39] op_sel_hi:[1,0]
	v_pk_mul_f32 v[22:23], v[148:149], v[22:23]
	v_pk_mul_f32 v[24:25], v[150:151], v[24:25]
	global_store_dwordx4 v[30:31], v[22:25], off offset:2048
	s_waitcnt vmcnt(7)
	v_pk_mul_f32 v[26:27], v[152:153], v[38:39] op_sel_hi:[1,0]
	v_pk_mul_f32 v[28:29], v[154:155], v[38:39] op_sel_hi:[1,0]
	v_pk_mul_f32 v[26:27], v[156:157], v[26:27]
	v_pk_mul_f32 v[28:29], v[158:159], v[28:29]
	global_store_dwordx4 v[30:31], v[26:29], off offset:3072
	s_cbranch_scc0 .LBB0_2114

; __global__ void __launch_bounds__(NTHR, 2) fwd_megakernel(Args a_unused) {
	.amdhsa_kernel _Z14fwd_megakernel4Args
		.amdhsa_group_segment_fixed_size 0
		.amdhsa_private_segment_fixed_size 0
		.amdhsa_kernarg_size 544
		.amdhsa_user_sgpr_count 2
		.amdhsa_user_sgpr_dispatch_ptr 0
		.amdhsa_user_sgpr_queue_ptr 0
		.amdhsa_user_sgpr_kernarg_segment_ptr 1
		.amdhsa_user_sgpr_dispatch_id 0
		.amdhsa_user_sgpr_kernarg_preload_length 0
		.amdhsa_user_sgpr_kernarg_preload_offset 0
		.amdhsa_user_sgpr_private_segment_size 0
		.amdhsa_uses_dynamic_stack 0
		.amdhsa_enable_private_segment 0
		.amdhsa_system_sgpr_workgroup_id_x 1
		.amdhsa_system_sgpr_workgroup_id_y 0
		.amdhsa_system_sgpr_workgroup_id_z 0
		.amdhsa_system_sgpr_workgroup_info 0
		.amdhsa_system_vgpr_workitem_id 2
		.amdhsa_next_free_vgpr 256
		.amdhsa_next_free_sgpr 102
		.amdhsa_accum_offset 256
		.amdhsa_reserve_vcc 1
		.amdhsa_float_round_mode_32 0
		.amdhsa_float_round_mode_16_64 0
		.amdhsa_float_denorm_mode_32 3
		.amdhsa_float_denorm_mode_16_64 3
		.amdhsa_dx10_clamp 1
		.amdhsa_ieee_mode 1
		.amdhsa_fp16_overflow 0
		.amdhsa_tg_split 0
		.amdhsa_exception_fp_ieee_invalid_op 0
		.amdhsa_exception_fp_denorm_src 0
		.amdhsa_exception_fp_ieee_div_zero 0
		.amdhsa_exception_fp_ieee_overflow 0
		.amdhsa_exception_fp_ieee_underflow 0
		.amdhsa_exception_fp_ieee_inexact 0
		.amdhsa_exception_int_div_zero 0
	.end_amdhsa_kernel

; __device__ __forceinline__ KArgs kargs() { KArgs p = (KArgs)__builtin_amdgcn_kernarg_segment_ptr(); asm volatile("" : "+s"(p)); return p; }
amdhsa.kernels:
  - .agpr_count:     0
    .args:
      - .offset:         0
        .size:           288
        .value_kind:     by_value
      - .offset:         288
        .size:           4
        .value_kind:     hidden_block_count_x
      - .offset:         292
        .size:           4
        .value_kind:     hidden_block_count_y
      - .offset:         296
        .size:           4
        .value_kind:     hidden_block_count_z
      - .offset:         300
        .size:           2
        .value_kind:     hidden_group_size_x
      - .offset:         302
        .size:           2
        .value_kind:     hidden_group_size_y
      - .offset:         304
        .size:           2
        .value_kind:     hidden_group_size_z
      - .offset:         306
        .size:           2
        .value_kind:     hidden_remainder_x
      - .offset:         308
        .size:           2
        .value_kind:     hidden_remainder_y
      - .offset:         310
        .size:           2
        .value_kind:     hidden_remainder_z
      - .offset:         328
        .size:           8
        .value_kind:     hidden_global_offset_x
      - .offset:         336
        .size:           8
        .value_kind:     hidden_global_offset_y
      - .offset:         344
        .size:           8
        .value_kind:     hidden_global_offset_z
      - .offset:         352
        .size:           2
        .value_kind:     hidden_grid_dims
      - .offset:         376
        .size:           8
        .value_kind:     hidden_multigrid_sync_arg
      - .offset:         408
        .size:           4
        .value_kind:     hidden_dynamic_lds_size
    .group_segment_fixed_size: 0
    .kernarg_segment_align: 8
    .kernarg_segment_size: 544
    .language:       OpenCL C
    .language_version:
      - 2
      - 0
    .max_flat_workgroup_size: 512
    .name:           _Z14fwd_megakernel4Args
    .private_segment_fixed_size: 0
    .sgpr_count:     108
    .sgpr_spill_count: 37
    .symbol:         _Z14fwd_megakernel4Args.kd
    .uniform_work_group_size: 1
    .uses_dynamic_stack: false
    .vgpr_count:     256
    .vgpr_spill_count: 0
    .wavefront_size: 64
